# P3 loaders: two-chunk-ahead loads with two raw register sets, bpermute latency overlapped; direct role dispatch; nt stores in phase 2
# speedup vs baseline: 1.0708x; 1.0104x over previous
; __device__ __forceinline__ void unpack8(const u32x4 w, float (&f)[8]) { f[0] = bflo(w.x); f[1] = bfhi(w.x); f[2] = bflo(w.y); f[3] = bfhi(w.y); f[4] = bflo(w.z); f[5] = bfhi(w.z); f[6] = bflo(w.w); f[7] = bfhi(w.w); }
; __device__ __forceinline__ u32x4 pack8(const float (&f)[8]) { u32x4 o; o.x = pk2(f[0], f[1]); o.y = pk2(f[2], f[3]); o.z = pk2(f[4], f[5]); o.w = pk2(f[6], f[7]); return o; }
; __device__ __forceinline__ float sigmoidf_(float x) { return __builtin_amdgcn_rcpf(1.0f + __expf(-x)); }
; __device__ __forceinline__ float tanhf_(float x) { return 1.0f - 2.0f * __builtin_amdgcn_rcpf(__expf(2.0f * x) + 1.0f); }
; template <int CH> __device__ __forceinline__ void p2_rwkv_chunk(const Params& p, int t0, int lane) {
;     ...
; #pragma unroll 2
;     for (int i = 0; i < 16; ++i) {
;         const int t = t0 + i; const bool hasn = (t & (T_SEQ - 1)) != T_SEQ - 1;
;         if (hasn) unpack8(raw, N); else {
; #pragma unroll
;             for (int q = 0; q < 8; ++q) N[q] = 0.f; }
;         if (i < 15 && ((t + 1) & (T_SEQ - 1)) != T_SEQ - 1) raw = __builtin_nontemporal_load((const u32x4*)(zc + (size_t)(i + 2) * ZLD));
;         float zs[8];
; #pragma unroll
;         for (int q = 0; q < 8; ++q) zs[q] = C[q] + mu[q] * (0.5f * (P[q] + N[q]) - C[q]);
;         if (CH < 3) {
;             *(u32x4*)(RKV + (size_t)t * 1536 + c) = pack8(zs);
;             if (CH == 1) { float s2 = 0.f;
; #pragma unroll
;                 for (int q = 0; q < 8; ++q) { const float v = zs[q] * kq[q]; s2 += v * v; }
;                 s2 = red8s(s2);
;                 if ((lane & 7) == 0) RINV[t * 8 + (lane >> 3)] = rsqrtf(fmaxf(s2, 1e-24f)); }
;         } else {
;             const int cc = c - 1536; float o[8];
; #pragma unroll
;             for (int q = 0; q < 8; ++q) o[q] = cc < 128 ? tanhf_(zs[q]) : (cc < 192 ? zs[q] : sigmoidf_(zs[q]));
;             *(u32x4*)(AP + (size_t)t * KLORA + cc) = pack8(o);
;         }
; #pragma unroll
;         for (int q = 0; q < 8; ++q) { P[q] = C[q]; C[q] = N[q]; }
;     }
.LBB0_240:
	v_add_f32_e32 v0, v0, v16
	v_fma_f32 v0, v0, 0.5, -v8
	v_mov_b32_e32 v36, v8
	v_fmac_f32_e32 v36, v28, v0
	v_add_f32_e32 v0, v1, v17
	v_fma_f32 v0, v0, 0.5, -v9
	v_mov_b32_e32 v1, v9
	v_fmac_f32_e32 v1, v29, v0
	v_add_f32_e32 v0, v2, v18
	v_fma_f32 v0, v0, 0.5, -v10
	v_mov_b32_e32 v2, v10
	v_fmac_f32_e32 v2, v30, v0
	v_add_f32_e32 v0, v3, v19
	v_fma_f32 v0, v0, 0.5, -v11
	v_mov_b32_e32 v3, v11
	v_fmac_f32_e32 v3, v31, v0
	v_add_f32_e32 v0, v4, v20
	v_fma_f32 v0, v0, 0.5, -v12
	v_mov_b32_e32 v4, v12
	v_fmac_f32_e32 v4, v24, v0
	v_add_f32_e32 v0, v5, v21
	v_fma_f32 v0, v0, 0.5, -v13
	v_mov_b32_e32 v5, v13
	v_fmac_f32_e32 v5, v25, v0
	v_add_f32_e32 v0, v6, v22
	v_fma_f32 v0, v0, 0.5, -v14
	v_mov_b32_e32 v6, v14
	v_fmac_f32_e32 v6, v26, v0
	v_add_f32_e32 v0, v7, v23
	v_fma_f32 v0, v0, 0.5, -v15
	v_mov_b32_e32 v7, v15
	v_fmac_f32_e32 v7, v27, v0
	v_cvt_pk_bf16_f32 v0, v36, v1
	v_cvt_pk_bf16_f32 v1, v2, v3
	v_cvt_pk_bf16_f32 v2, v4, v5
	v_cvt_pk_bf16_f32 v3, v6, v7
	v_mad_i64_i32 v[4:5], s[76:77], s60, v219, v[142:143]
	global_store_dwordx4 v[4:5], v[0:3], off nt
	s_add_u32 s14, s14, 0x3800
	s_addc_u32 s15, s15, 0
	v_mov_b64_e32 v[0:1], v[16:17]
	s_add_i32 s60, s60, 2
	s_add_i32 s25, s25, -2
	s_waitcnt vmcnt(1)
	v_mov_b64_e32 v[38:39], v[34:35]
	v_mov_b64_e32 v[2:3], v[18:19]
	v_mov_b64_e32 v[4:5], v[20:21]
	v_mov_b64_e32 v[6:7], v[22:23]
	v_mov_b64_e32 v[22:23], v[14:15]
	v_lshl_add_u64 v[40:41], v[40:41], 0, s[40:41]
	s_cmp_lg_u32 s14, 0x1c000
	v_mov_b64_e32 v[36:37], v[32:33]
	v_mov_b64_e32 v[20:21], v[12:13]
	v_mov_b64_e32 v[18:19], v[10:11]
	v_mov_b64_e32 v[16:17], v[8:9]
	s_cbranch_scc0 .LBB0_247

; __device__ __forceinline__ void unpack8(const u32x4 w, float (&f)[8]) { f[0] = bflo(w.x); f[1] = bfhi(w.x); f[2] = bflo(w.y); f[3] = bfhi(w.y); f[4] = bflo(w.z); f[5] = bfhi(w.z); f[6] = bflo(w.w); f[7] = bfhi(w.w); }
; __device__ __forceinline__ u32x4 pack8(const float (&f)[8]) { u32x4 o; o.x = pk2(f[0], f[1]); o.y = pk2(f[2], f[3]); o.z = pk2(f[4], f[5]); o.w = pk2(f[6], f[7]); return o; }
; __device__ __forceinline__ float sigmoidf_(float x) { return __builtin_amdgcn_rcpf(1.0f + __expf(-x)); }
; __device__ __forceinline__ float tanhf_(float x) { return 1.0f - 2.0f * __builtin_amdgcn_rcpf(__expf(2.0f * x) + 1.0f); }
; template <int CH> __device__ __forceinline__ void p2_rwkv_chunk(const Params& p, int t0, int lane) {
;     ...
; #pragma unroll 2
;     for (int i = 0; i < 16; ++i) {
;         const int t = t0 + i; const bool hasn = (t & (T_SEQ - 1)) != T_SEQ - 1;
;         if (hasn) unpack8(raw, N); else {
; #pragma unroll
;             for (int q = 0; q < 8; ++q) N[q] = 0.f; }
;         if (i < 15 && ((t + 1) & (T_SEQ - 1)) != T_SEQ - 1) raw = __builtin_nontemporal_load((const u32x4*)(zc + (size_t)(i + 2) * ZLD));
;         float zs[8];
; #pragma unroll
;         for (int q = 0; q < 8; ++q) zs[q] = C[q] + mu[q] * (0.5f * (P[q] + N[q]) - C[q]);
;         if (CH < 3) {
;             *(u32x4*)(RKV + (size_t)t * 1536 + c) = pack8(zs);
;             if (CH == 1) { float s2 = 0.f;
; #pragma unroll
;                 for (int q = 0; q < 8; ++q) { const float v = zs[q] * kq[q]; s2 += v * v; }
;                 s2 = red8s(s2);
;                 if ((lane & 7) == 0) RINV[t * 8 + (lane >> 3)] = rsqrtf(fmaxf(s2, 1e-24f)); }
;         } else {
;             const int cc = c - 1536; float o[8];
; #pragma unroll
;             for (int q = 0; q < 8; ++q) o[q] = cc < 128 ? tanhf_(zs[q]) : (cc < 192 ? zs[q] : sigmoidf_(zs[q]));
;             *(u32x4*)(AP + (size_t)t * KLORA + cc) = pack8(o);
;         }
; #pragma unroll
;         for (int q = 0; q < 8; ++q) { P[q] = C[q]; C[q] = N[q]; }
;     }
.LBB0_243:
	v_lshlrev_b32_e32 v8, 16, v36
	v_and_b32_e32 v9, 0xffff0000, v36
	v_lshlrev_b32_e32 v10, 16, v37
	v_and_b32_e32 v11, 0xffff0000, v37
	v_lshlrev_b32_e32 v12, 16, v38
	v_and_b32_e32 v13, 0xffff0000, v38
	v_lshlrev_b32_e32 v14, 16, v39
	v_and_b32_e32 v15, 0xffff0000, v39
	v_add_f32_e32 v16, v16, v8
	v_add_f32_e32 v17, v17, v9
	v_add_f32_e32 v18, v18, v10
	v_add_f32_e32 v19, v19, v11
	v_fma_f32 v16, v16, 0.5, -v0
	v_fma_f32 v17, v17, 0.5, -v1
	v_fma_f32 v18, v18, 0.5, -v2
	v_fma_f32 v19, v19, 0.5, -v3
	v_add_f32_e32 v20, v20, v12
	v_add_f32_e32 v21, v21, v13
	v_add_f32_e32 v22, v22, v14
	v_add_f32_e32 v23, v23, v15
	s_and_b32 s61, s60, 0xfff
	v_fma_f32 v16, v28, v16, v0
	v_fma_f32 v17, v29, v17, v1
	v_fma_f32 v18, v30, v18, v2
	v_fma_f32 v19, v31, v19, v3
	v_fma_f32 v20, v20, 0.5, -v4
	v_fma_f32 v21, v21, 0.5, -v5
	v_fma_f32 v22, v22, 0.5, -v6
	v_fma_f32 v23, v23, 0.5, -v7
	s_cmpk_eq_i32 s61, 0xfff
	v_fma_f32 v20, v24, v20, v4
	v_fma_f32 v21, v25, v21, v5
	v_fma_f32 v22, v26, v22, v6
	v_fma_f32 v23, v27, v23, v7
	v_cvt_pk_bf16_f32 v16, v16, v17
	v_cvt_pk_bf16_f32 v17, v18, v19
	v_cvt_pk_bf16_f32 v18, v20, v21
	v_cvt_pk_bf16_f32 v19, v22, v23
	global_store_dwordx4 v[40:41], v[16:19], off nt
	s_cbranch_scc1 .LBB0_245
	s_waitcnt vmcnt(1)
	v_lshlrev_b32_e32 v16, 16, v32
	v_and_b32_e32 v17, 0xffff0000, v32
	v_lshlrev_b32_e32 v18, 16, v33
	v_and_b32_e32 v19, 0xffff0000, v33
	v_lshlrev_b32_e32 v20, 16, v34
	v_and_b32_e32 v21, 0xffff0000, v34
	v_lshlrev_b32_e32 v22, 16, v35
	v_and_b32_e32 v23, 0xffff0000, v35
	s_cmp_eq_u32 s14, 0x18800
	s_cbranch_scc1 .LBB0_240
	s_branch .LBB0_246

; __device__ __forceinline__ u32x4 pack8(const float (&f)[8]) { u32x4 o; o.x = pk2(f[0], f[1]); o.y = pk2(f[2], f[3]); o.z = pk2(f[4], f[5]); o.w = pk2(f[6], f[7]); return o; }
; template <int CH> __device__ __forceinline__ void p2_rwkv_chunk(const Params& p, int t0, int lane) {
;     ...
; #pragma unroll
;         for (int q = 0; q < 8; ++q) zs[q] = C[q] + mu[q] * (0.5f * (P[q] + N[q]) - C[q]);
;         if (CH < 3) {
;             *(u32x4*)(RKV + (size_t)t * 1536 + c) = pack8(zs);
;             if (CH == 1) { float s2 = 0.f;
; #pragma unroll
;                 for (int q = 0; q < 8; ++q) { const float v = zs[q] * kq[q]; s2 += v * v; }
;                 s2 = red8s(s2);
;                 if ((lane & 7) == 0) RINV[t * 8 + (lane >> 3)] = rsqrtf(fmaxf(s2, 1e-24f)); }
.LBB0_254:
	v_lshlrev_b32_e32 v0, 16, v44
	v_add_f32_e32 v16, v16, v0
	v_and_b32_e32 v1, 0xffff0000, v44
	v_fma_f32 v16, v16, 0.5, -v8
	v_fma_f32 v44, v28, v16, v8
	v_add_f32_e32 v16, v17, v1
	v_lshlrev_b32_e32 v2, 16, v45
	v_fma_f32 v16, v16, 0.5, -v9
	v_and_b32_e32 v3, 0xffff0000, v45
	v_fma_f32 v45, v29, v16, v9
	v_add_f32_e32 v16, v18, v2
	v_fma_f32 v16, v16, 0.5, -v10
	v_lshlrev_b32_e32 v4, 16, v46
	v_and_b32_e32 v5, 0xffff0000, v46
	v_fma_f32 v46, v30, v16, v10
	v_add_f32_e32 v16, v19, v3
	v_fma_f32 v16, v16, 0.5, -v11
	v_lshlrev_b32_e32 v6, 16, v47
	v_and_b32_e32 v7, 0xffff0000, v47
	v_fma_f32 v47, v31, v16, v11
	v_add_f32_e32 v16, v20, v4
	v_fma_f32 v16, v16, 0.5, -v12
	v_fma_f32 v20, v24, v16, v12
	v_add_f32_e32 v16, v21, v5
	v_fma_f32 v16, v16, 0.5, -v13
	v_fma_f32 v21, v25, v16, v13
	v_add_f32_e32 v16, v22, v6
	v_fma_f32 v16, v16, 0.5, -v14
	v_fma_f32 v22, v26, v16, v14
	v_add_f32_e32 v16, v23, v7
	v_fma_f32 v16, v16, 0.5, -v15
	v_cvt_pk_bf16_f32 v17, v46, v47
	v_fma_f32 v23, v27, v16, v15
	v_cvt_pk_bf16_f32 v16, v44, v45
	v_cvt_pk_bf16_f32 v18, v20, v21
	v_cvt_pk_bf16_f32 v19, v22, v23
	global_store_dwordx4 v[54:55], v[16:19], off nt
	s_nop 1
	v_mul_f32_e32 v17, v37, v45
	v_mul_f32_e32 v16, v36, v44
	v_mul_f32_e32 v17, v17, v17
	v_fmac_f32_e32 v17, v16, v16
	v_mul_f32_e32 v16, v38, v46
	v_fmac_f32_e32 v17, v16, v16
	v_mul_f32_e32 v16, v39, v47
	v_fmac_f32_e32 v17, v16, v16
	v_mul_f32_e32 v16, v32, v20
	v_fmac_f32_e32 v17, v16, v16
	v_mul_f32_e32 v16, v33, v21
	v_fmac_f32_e32 v17, v16, v16
	v_mul_f32_e32 v16, v34, v22
	v_fmac_f32_e32 v17, v16, v16
	v_mul_f32_e32 v16, v35, v23
	v_fmac_f32_e32 v17, v16, v16
	s_nop 1
	v_add_f32_dpp v16, v17, v17 quad_perm:[1,0,3,2] row_mask:0xf bank_mask:0xf bound_ctrl:1
	s_nop 1
	v_add_f32_dpp v16, v16, v16 quad_perm:[2,3,0,1] row_mask:0xf bank_mask:0xf bound_ctrl:1
	s_nop 1
	v_mov_b32_dpp v17, v16 row_half_mirror row_mask:0xf bank_mask:0xf bound_ctrl:1
	s_and_saveexec_b64 s[52:53], s[4:5]
	s_cbranch_execz .LBB0_256
	v_add_f32_e32 v16, v16, v17
	v_max_f32_e32 v16, 0x179abe15, v16
	v_rsq_f32_e32 v18, v16
	v_add_u32_e32 v16, s25, v137
	v_ashrrev_i32_e32 v17, 31, v16
	v_lshl_add_u64 v[16:17], v[16:17], 2, s[20:21]
	global_store_dword v[16:17], v18, off nt

; __device__ __forceinline__ u32x4 pack8(const float (&f)[8]) { u32x4 o; o.x = pk2(f[0], f[1]); o.y = pk2(f[2], f[3]); o.z = pk2(f[4], f[5]); o.w = pk2(f[6], f[7]); return o; }
; template <int CH> __device__ __forceinline__ void p2_rwkv_chunk(const Params& p, int t0, int lane) {
;     ...
; #pragma unroll
;         for (int q = 0; q < 8; ++q) zs[q] = C[q] + mu[q] * (0.5f * (P[q] + N[q]) - C[q]);
;         if (CH < 3) {
;             *(u32x4*)(RKV + (size_t)t * 1536 + c) = pack8(zs);
;             if (CH == 1) { float s2 = 0.f;
; #pragma unroll
;                 for (int q = 0; q < 8; ++q) { const float v = zs[q] * kq[q]; s2 += v * v; }
;                 s2 = red8s(s2);
;                 if ((lane & 7) == 0) RINV[t * 8 + (lane >> 3)] = rsqrtf(fmaxf(s2, 1e-24f)); }
.LBB0_260:
	v_add_f32_e32 v8, v8, v16
	v_fma_f32 v8, v8, 0.5, -v0
	v_fma_f32 v44, v28, v8, v0
	v_add_f32_e32 v8, v9, v17
	v_fma_f32 v8, v8, 0.5, -v1
	v_fma_f32 v45, v29, v8, v1
	v_add_f32_e32 v8, v10, v18
	v_fma_f32 v8, v8, 0.5, -v2
	v_fma_f32 v46, v30, v8, v2
	v_add_f32_e32 v8, v11, v19
	v_fma_f32 v8, v8, 0.5, -v3
	v_fma_f32 v47, v31, v8, v3
	v_add_f32_e32 v8, v12, v20
	v_fma_f32 v8, v8, 0.5, -v4
	v_fma_f32 v56, v24, v8, v4
	v_add_f32_e32 v8, v13, v21
	v_fma_f32 v8, v8, 0.5, -v5
	v_fma_f32 v57, v25, v8, v5
	v_add_f32_e32 v8, v14, v22
	v_fma_f32 v8, v8, 0.5, -v6
	v_fma_f32 v14, v26, v8, v6
	v_add_f32_e32 v8, v15, v23
	v_fma_f32 v8, v8, 0.5, -v7
	v_cvt_pk_bf16_f32 v9, v46, v47
	v_mad_i64_i32 v[12:13], s[52:53], s61, v219, v[170:171]
	v_fma_f32 v15, v27, v8, v7
	v_cvt_pk_bf16_f32 v8, v44, v45
	v_cvt_pk_bf16_f32 v10, v56, v57
	v_cvt_pk_bf16_f32 v11, v14, v15
	global_store_dwordx4 v[12:13], v[8:11], off nt
	s_nop 1
	v_mul_f32_e32 v9, v37, v45
	v_mul_f32_e32 v8, v36, v44
	v_mul_f32_e32 v9, v9, v9
	v_fmac_f32_e32 v9, v8, v8
	v_mul_f32_e32 v8, v38, v46
	v_fmac_f32_e32 v9, v8, v8
	v_mul_f32_e32 v8, v39, v47
	v_fmac_f32_e32 v9, v8, v8
	v_mul_f32_e32 v8, v32, v56
	v_fmac_f32_e32 v9, v8, v8
	v_mul_f32_e32 v8, v33, v57
	v_fmac_f32_e32 v9, v8, v8
	v_mul_f32_e32 v8, v34, v14
	v_fmac_f32_e32 v9, v8, v8
	v_mul_f32_e32 v8, v35, v15
	v_fmac_f32_e32 v9, v8, v8
	s_nop 1
	v_add_f32_dpp v8, v9, v9 quad_perm:[1,0,3,2] row_mask:0xf bank_mask:0xf bound_ctrl:1
	s_nop 1
	v_add_f32_dpp v8, v8, v8 quad_perm:[2,3,0,1] row_mask:0xf bank_mask:0xf bound_ctrl:1
	s_nop 1
	v_mov_b32_dpp v9, v8 row_half_mirror row_mask:0xf bank_mask:0xf bound_ctrl:1
	s_and_saveexec_b64 s[52:53], s[4:5]
	s_cbranch_execz .LBB0_251
	v_add_f32_e32 v8, v8, v9
	v_max_f32_e32 v8, 0x179abe15, v8
	v_rsq_f32_e32 v10, v8
	v_add3_u32 v8, v137, s25, 8
	v_ashrrev_i32_e32 v9, 31, v8
	v_lshl_add_u64 v[8:9], v[8:9], 2, s[20:21]
	global_store_dword v[8:9], v10, off nt
	s_branch .LBB0_251

; __device__ __forceinline__ void unpack8(const u32x4 w, float (&f)[8]) { f[0] = bflo(w.x); f[1] = bfhi(w.x); f[2] = bflo(w.y); f[3] = bfhi(w.y); f[4] = bflo(w.z); f[5] = bfhi(w.z); f[6] = bflo(w.w); f[7] = bfhi(w.w); }
; __device__ __forceinline__ u32x4 pack8(const float (&f)[8]) { u32x4 o; o.x = pk2(f[0], f[1]); o.y = pk2(f[2], f[3]); o.z = pk2(f[4], f[5]); o.w = pk2(f[6], f[7]); return o; }
; __device__ __forceinline__ float sigmoidf_(float x) { return __builtin_amdgcn_rcpf(1.0f + __expf(-x)); }
; __device__ __forceinline__ float tanhf_(float x) { return 1.0f - 2.0f * __builtin_amdgcn_rcpf(__expf(2.0f * x) + 1.0f); }
; template <int CH> __device__ __forceinline__ void p2_rwkv_chunk(const Params& p, int t0, int lane) {
;     ...
; #pragma unroll 2
;     for (int i = 0; i < 16; ++i) {
;         const int t = t0 + i; const bool hasn = (t & (T_SEQ - 1)) != T_SEQ - 1;
;         if (hasn) unpack8(raw, N); else {
; #pragma unroll
;             for (int q = 0; q < 8; ++q) N[q] = 0.f; }
;         if (i < 15 && ((t + 1) & (T_SEQ - 1)) != T_SEQ - 1) raw = __builtin_nontemporal_load((const u32x4*)(zc + (size_t)(i + 2) * ZLD));
;         float zs[8];
; #pragma unroll
;         for (int q = 0; q < 8; ++q) zs[q] = C[q] + mu[q] * (0.5f * (P[q] + N[q]) - C[q]);
;         if (CH < 3) {
;             *(u32x4*)(RKV + (size_t)t * 1536 + c) = pack8(zs);
;             if (CH == 1) { float s2 = 0.f;
; #pragma unroll
;                 for (int q = 0; q < 8; ++q) { const float v = zs[q] * kq[q]; s2 += v * v; }
;                 s2 = red8s(s2);
;                 if ((lane & 7) == 0) RINV[t * 8 + (lane >> 3)] = rsqrtf(fmaxf(s2, 1e-24f)); }
;         } else {
;             const int cc = c - 1536; float o[8];
; #pragma unroll
;             for (int q = 0; q < 8; ++q) o[q] = cc < 128 ? tanhf_(zs[q]) : (cc < 192 ? zs[q] : sigmoidf_(zs[q]));
;             *(u32x4*)(AP + (size_t)t * KLORA + cc) = pack8(o);
;         }
; #pragma unroll
;         for (int q = 0; q < 8; ++q) { P[q] = C[q]; C[q] = N[q]; }
;     }
.LBB0_266:
	v_add_f32_e32 v0, v0, v8
	v_fma_f32 v0, v0, 0.5, -v16
	v_mov_b32_e32 v36, v16
	v_fmac_f32_e32 v36, v28, v0
	v_add_f32_e32 v0, v1, v9
	v_fma_f32 v0, v0, 0.5, -v17
	v_mov_b32_e32 v1, v17
	v_fmac_f32_e32 v1, v29, v0
	v_add_f32_e32 v0, v2, v10
	v_fma_f32 v0, v0, 0.5, -v18
	v_mov_b32_e32 v2, v18
	v_fmac_f32_e32 v2, v30, v0
	v_add_f32_e32 v0, v3, v11
	v_fma_f32 v0, v0, 0.5, -v19
	v_mov_b32_e32 v3, v19
	v_fmac_f32_e32 v3, v31, v0
	v_add_f32_e32 v0, v4, v12
	v_fma_f32 v0, v0, 0.5, -v20
	v_mov_b32_e32 v4, v20
	v_fmac_f32_e32 v4, v24, v0
	v_add_f32_e32 v0, v5, v13
	v_fma_f32 v0, v0, 0.5, -v21
	v_mov_b32_e32 v5, v21
	v_fmac_f32_e32 v5, v25, v0
	v_add_f32_e32 v0, v6, v14
	v_fma_f32 v0, v0, 0.5, -v22
	v_mov_b32_e32 v6, v22
	v_fmac_f32_e32 v6, v26, v0
	v_add_f32_e32 v0, v7, v15
	v_fma_f32 v0, v0, 0.5, -v23
	v_mov_b32_e32 v7, v23
	v_fmac_f32_e32 v7, v27, v0
	v_cvt_pk_bf16_f32 v0, v36, v1
	v_cvt_pk_bf16_f32 v1, v2, v3
	v_cvt_pk_bf16_f32 v2, v4, v5
	v_cvt_pk_bf16_f32 v3, v6, v7
	v_mad_i64_i32 v[4:5], s[60:61], s52, v219, v[172:173]
	global_store_dwordx4 v[4:5], v[0:3], off nt
	s_add_u32 s42, s42, 0x3800
	s_addc_u32 s43, s43, 0
	v_mov_b64_e32 v[0:1], v[8:9]
	s_add_i32 s52, s52, 2
	s_add_i32 s25, s25, -2
	s_waitcnt vmcnt(1)
	v_mov_b64_e32 v[38:39], v[34:35]
	v_mov_b64_e32 v[2:3], v[10:11]
	v_mov_b64_e32 v[4:5], v[12:13]
	v_mov_b64_e32 v[6:7], v[14:15]
	v_mov_b64_e32 v[8:9], v[16:17]
	v_lshl_add_u64 v[40:41], v[40:41], 0, s[40:41]
	s_cmp_lg_u32 s42, 0x1c000
	v_mov_b64_e32 v[36:37], v[32:33]
	v_mov_b64_e32 v[10:11], v[18:19]
	v_mov_b64_e32 v[12:13], v[20:21]
	v_mov_b64_e32 v[14:15], v[22:23]
	s_cbranch_scc0 .LBB0_273

; __device__ __forceinline__ void unpack8(const u32x4 w, float (&f)[8]) { f[0] = bflo(w.x); f[1] = bfhi(w.x); f[2] = bflo(w.y); f[3] = bfhi(w.y); f[4] = bflo(w.z); f[5] = bfhi(w.z); f[6] = bflo(w.w); f[7] = bfhi(w.w); }
; __device__ __forceinline__ u32x4 pack8(const float (&f)[8]) { u32x4 o; o.x = pk2(f[0], f[1]); o.y = pk2(f[2], f[3]); o.z = pk2(f[4], f[5]); o.w = pk2(f[6], f[7]); return o; }
; __device__ __forceinline__ float sigmoidf_(float x) { return __builtin_amdgcn_rcpf(1.0f + __expf(-x)); }
; __device__ __forceinline__ float tanhf_(float x) { return 1.0f - 2.0f * __builtin_amdgcn_rcpf(__expf(2.0f * x) + 1.0f); }
; template <int CH> __device__ __forceinline__ void p2_rwkv_chunk(const Params& p, int t0, int lane) {
;     ...
; #pragma unroll 2
;     for (int i = 0; i < 16; ++i) {
;         const int t = t0 + i; const bool hasn = (t & (T_SEQ - 1)) != T_SEQ - 1;
;         if (hasn) unpack8(raw, N); else {
; #pragma unroll
;             for (int q = 0; q < 8; ++q) N[q] = 0.f; }
;         if (i < 15 && ((t + 1) & (T_SEQ - 1)) != T_SEQ - 1) raw = __builtin_nontemporal_load((const u32x4*)(zc + (size_t)(i + 2) * ZLD));
;         float zs[8];
; #pragma unroll
;         for (int q = 0; q < 8; ++q) zs[q] = C[q] + mu[q] * (0.5f * (P[q] + N[q]) - C[q]);
;         if (CH < 3) {
;             *(u32x4*)(RKV + (size_t)t * 1536 + c) = pack8(zs);
;             if (CH == 1) { float s2 = 0.f;
; #pragma unroll
;                 for (int q = 0; q < 8; ++q) { const float v = zs[q] * kq[q]; s2 += v * v; }
;                 s2 = red8s(s2);
;                 if ((lane & 7) == 0) RINV[t * 8 + (lane >> 3)] = rsqrtf(fmaxf(s2, 1e-24f)); }
;         } else {
;             const int cc = c - 1536; float o[8];
; #pragma unroll
;             for (int q = 0; q < 8; ++q) o[q] = cc < 128 ? tanhf_(zs[q]) : (cc < 192 ? zs[q] : sigmoidf_(zs[q]));
;             *(u32x4*)(AP + (size_t)t * KLORA + cc) = pack8(o);
;         }
; #pragma unroll
;         for (int q = 0; q < 8; ++q) { P[q] = C[q]; C[q] = N[q]; }
;     }
.LBB0_269:
	v_lshlrev_b32_e32 v16, 16, v36
	v_and_b32_e32 v17, 0xffff0000, v36
	v_lshlrev_b32_e32 v18, 16, v37
	v_and_b32_e32 v19, 0xffff0000, v37
	v_lshlrev_b32_e32 v20, 16, v38
	v_and_b32_e32 v21, 0xffff0000, v38
	v_lshlrev_b32_e32 v22, 16, v39
	v_and_b32_e32 v23, 0xffff0000, v39
	v_add_f32_e32 v8, v8, v16
	v_add_f32_e32 v9, v9, v17
	v_add_f32_e32 v10, v10, v18
	v_add_f32_e32 v11, v11, v19
	v_fma_f32 v8, v8, 0.5, -v0
	v_fma_f32 v9, v9, 0.5, -v1
	v_fma_f32 v10, v10, 0.5, -v2
	v_fma_f32 v11, v11, 0.5, -v3
	v_add_f32_e32 v12, v12, v20
	v_add_f32_e32 v13, v13, v21
	v_add_f32_e32 v14, v14, v22
	v_add_f32_e32 v15, v15, v23
	s_and_b32 s53, s52, 0xfff
	v_fma_f32 v8, v28, v8, v0
	v_fma_f32 v9, v29, v9, v1
	v_fma_f32 v10, v30, v10, v2
	v_fma_f32 v11, v31, v11, v3
	v_fma_f32 v12, v12, 0.5, -v4
	v_fma_f32 v13, v13, 0.5, -v5
	v_fma_f32 v14, v14, 0.5, -v6
	v_fma_f32 v15, v15, 0.5, -v7
	s_cmpk_eq_i32 s53, 0xfff
	v_fma_f32 v12, v24, v12, v4
	v_fma_f32 v13, v25, v13, v5
	v_fma_f32 v14, v26, v14, v6
	v_fma_f32 v15, v27, v15, v7
	v_cvt_pk_bf16_f32 v8, v8, v9
	v_cvt_pk_bf16_f32 v9, v10, v11
	v_cvt_pk_bf16_f32 v10, v12, v13
	v_cvt_pk_bf16_f32 v11, v14, v15
	global_store_dwordx4 v[40:41], v[8:11], off nt
	s_cbranch_scc1 .LBB0_271
	s_waitcnt vmcnt(1)
	v_lshlrev_b32_e32 v8, 16, v32
	v_and_b32_e32 v9, 0xffff0000, v32
	v_lshlrev_b32_e32 v10, 16, v33
	v_and_b32_e32 v11, 0xffff0000, v33
	v_lshlrev_b32_e32 v12, 16, v34
	v_and_b32_e32 v13, 0xffff0000, v34
	v_lshlrev_b32_e32 v14, 16, v35
	v_and_b32_e32 v15, 0xffff0000, v35
	s_cmp_eq_u32 s42, 0x18800
	s_cbranch_scc1 .LBB0_266
	s_branch .LBB0_272

; __device__ __forceinline__ u32x4 pack8(const float (&f)[8]) { u32x4 o; o.x = pk2(f[0], f[1]); o.y = pk2(f[2], f[3]); o.z = pk2(f[4], f[5]); o.w = pk2(f[6], f[7]); return o; }
; __device__ __forceinline__ float sigmoidf_(float x) { return __builtin_amdgcn_rcpf(1.0f + __expf(-x)); }
; __device__ __forceinline__ float tanhf_(float x) { return 1.0f - 2.0f * __builtin_amdgcn_rcpf(__expf(2.0f * x) + 1.0f); }
; template <int CH> __device__ __forceinline__ void p2_rwkv_chunk(const Params& p, int t0, int lane) {
;     ...
;         } else {
;             const int cc = c - 1536; float o[8];
; #pragma unroll
;             for (int q = 0; q < 8; ++q) o[q] = cc < 128 ? tanhf_(zs[q]) : (cc < 192 ? zs[q] : sigmoidf_(zs[q]));
;             *(u32x4*)(AP + (size_t)t * KLORA + cc) = pack8(o);
;         }
; #pragma unroll
;         for (int q = 0; q < 8; ++q) { P[q] = C[q]; C[q] = N[q]; }
;     }
.LBB0_278:
	s_or_b64 exec, exec, s[52:53]
	v_cvt_pk_bf16_f32 v0, v0, v1
	v_cvt_pk_bf16_f32 v1, v2, v3
	v_cvt_pk_bf16_f32 v2, v4, v5
	v_cvt_pk_bf16_f32 v3, v6, v7
	v_mad_i64_i32 v[4:5], s[52:53], s60, v220, v[150:151]
	s_add_u32 s26, s26, 0x3800
	global_store_dwordx4 v[4:5], v[0:3], off nt
	s_addc_u32 s27, s27, 0
	s_add_i32 s60, s60, 2
	s_mov_b64 s[52:53], 0x600
	s_add_i32 s25, s25, -2
	v_mov_b32_e32 v40, v31
	v_mov_b32_e32 v42, v30
	v_mov_b32_e32 v44, v29
	v_mov_b32_e32 v46, v28
	s_waitcnt vmcnt(1)
	v_mov_b64_e32 v[30:31], v[26:27]
	v_mov_b64_e32 v[0:1], v[8:9]
	v_lshl_add_u64 v[32:33], v[32:33], 0, s[52:53]
	s_cmp_lg_u32 s26, 0x1c000
	v_mov_b32_e32 v41, v39
	v_mov_b32_e32 v43, v38
	v_mov_b32_e32 v45, v37
	v_mov_b32_e32 v37, v36
	v_mov_b64_e32 v[28:29], v[24:25]
	v_mov_b64_e32 v[2:3], v[10:11]
	v_mov_b64_e32 v[4:5], v[12:13]
	v_mov_b64_e32 v[6:7], v[14:15]
	s_cbranch_scc0 .LBB0_349

; __device__ __forceinline__ u32x4 pack8(const float (&f)[8]) { u32x4 o; o.x = pk2(f[0], f[1]); o.y = pk2(f[2], f[3]); o.z = pk2(f[4], f[5]); o.w = pk2(f[6], f[7]); return o; }
; __device__ __forceinline__ float sigmoidf_(float x) { return __builtin_amdgcn_rcpf(1.0f + __expf(-x)); }
; __device__ __forceinline__ float tanhf_(float x) { return 1.0f - 2.0f * __builtin_amdgcn_rcpf(__expf(2.0f * x) + 1.0f); }
; template <int CH> __device__ __forceinline__ void p2_rwkv_chunk(const Params& p, int t0, int lane) {
;     ...
;         } else {
;             const int cc = c - 1536; float o[8];
; #pragma unroll
;             for (int q = 0; q < 8; ++q) o[q] = cc < 128 ? tanhf_(zs[q]) : (cc < 192 ? zs[q] : sigmoidf_(zs[q]));
;             *(u32x4*)(AP + (size_t)t * KLORA + cc) = pack8(o);
;         }
; #pragma unroll
;         for (int q = 0; q < 8; ++q) { P[q] = C[q]; C[q] = N[q]; }
;     }
.LBB0_313:
	s_or_b64 exec, exec, s[52:53]
	s_and_b32 s52, s60, 0xfff
	s_cmpk_eq_i32 s52, 0xfff
	v_cvt_pk_bf16_f32 v8, v8, v9
	v_cvt_pk_bf16_f32 v9, v10, v11
	v_cvt_pk_bf16_f32 v10, v12, v13
	v_cvt_pk_bf16_f32 v11, v14, v15
	global_store_dwordx4 v[32:33], v[8:11], off nt
	s_cbranch_scc1 .LBB0_315
	s_waitcnt vmcnt(1)
	v_lshlrev_b32_e32 v8, 16, v24
	v_and_b32_e32 v9, 0xffff0000, v24
	v_lshlrev_b32_e32 v10, 16, v25
	v_and_b32_e32 v11, 0xffff0000, v25
	v_lshlrev_b32_e32 v12, 16, v26
	v_and_b32_e32 v13, 0xffff0000, v26
	v_lshlrev_b32_e32 v14, 16, v27
	v_and_b32_e32 v15, 0xffff0000, v27
	s_cmp_eq_u32 s26, 0x18800
	s_cbranch_scc0 .LBB0_316
	s_branch .LBB0_317

; template <int CH> __device__ __forceinline__ void p2_rwkv_chunk(const Params& p, int t0, int lane) {
;     ...
;     if (CH == 3 && chunk >= 232) {
;         if (chunk < 240) { const u32x4 zero = {0u, 0u, 0u, 0u};
; #pragma unroll 4
;             for (int i = 0; i < 16; ++i) *(u32x4*)(AP + (size_t)(t0 + i) * KLORA + 320 + (chunk - 232) * 8) = zero; }
;         return; }
.LBB0_352:
	s_mov_b32 s25, s24
	s_mov_b32 s26, s24
	s_mov_b32 s27, s24
	v_mov_b64_e32 v[8:9], s[24:25]
	v_lshl_add_u64 v[6:7], v[32:33], 0, s[60:61]
	v_mov_b64_e32 v[10:11], s[26:27]
	global_store_dwordx4 v[6:7], v[8:11], off nt
	v_lshl_add_u64 v[6:7], v[4:5], 0, s[60:61]
	global_store_dwordx4 v[6:7], v[8:11], off nt
	v_lshl_add_u64 v[6:7], v[2:3], 0, s[60:61]
	global_store_dwordx4 v[6:7], v[8:11], off nt
	v_lshl_add_u64 v[6:7], v[0:1], 0, s[60:61]
	s_add_u32 s60, s60, 0xc00
	s_addc_u32 s61, s61, 0
	s_cmpk_eq_i32 s60, 0x3000
	global_store_dwordx4 v[6:7], v[8:11], off nt
	s_cbranch_scc0 .LBB0_352

; __device__ __forceinline__ void unpack8(const u32x4 w, float (&f)[8]) { f[0] = bflo(w.x); f[1] = bfhi(w.x); f[2] = bflo(w.y); f[3] = bfhi(w.y); f[4] = bflo(w.z); f[5] = bfhi(w.z); f[6] = bflo(w.w); f[7] = bfhi(w.w); }
; __device__ __forceinline__ u32x4 pack8(const float (&f)[8]) { u32x4 o; o.x = pk2(f[0], f[1]); o.y = pk2(f[2], f[3]); o.z = pk2(f[4], f[5]); o.w = pk2(f[6], f[7]); return o; }
; __device__ __forceinline__ float siluf_(float x) { return x * __builtin_amdgcn_rcpf(1.0f + __expf(-x)); }
; template <int CH> __device__ __forceinline__ void p2_gla_chunk(const Params& p, int t0, int lane) {
;     ...
; #pragma unroll 2
;     for (int i = 0; i < 16; ++i) {
;         const int t = t0 + i; const bool hasn = (t & (T_SEQ - 1)) != T_SEQ - 1;
;         if (hasn) unpack8(raw, N); else {
; #pragma unroll
;             for (int q = 0; q < 8; ++q) N[q] = 0.f; }
;         if (i < 15 && ((t + 1) & (T_SEQ - 1)) != T_SEQ - 1) raw = __builtin_nontemporal_load((const u32x4*)(zc + (size_t)(i + 2) * ZLD));
;         float o[8];
; #pragma unroll
;         for (int q = 0; q < 8; ++q) { const float y = w0[q] * P[q] + w1[q] * C[q] + w2[q] * N[q]; o[q] = siluf_(y) * sc; }
;         *(u32x4*)(GQKV + (size_t)t * 1024 + c) = pack8(o);
; #pragma unroll
;         for (int q = 0; q < 8; ++q) { P[q] = C[q]; C[q] = N[q]; }
;     }
.LBB0_358:
	v_mov_b32_e32 v46, v67
	v_mov_b32_e32 v47, v16
	v_pk_mul_f32 v[46:47], v[56:57], v[46:47]
	s_ashr_i32 s61, s60, 31
	v_fma_f32 v0, v28, v0, v46
	v_add_f32_e32 v0, v0, v47
	v_mov_b32_e32 v46, v9
	v_mov_b32_e32 v47, v17
	v_pk_mul_f32 v[46:47], v[36:37], v[46:47]
	v_mul_f32_e32 v12, 0xbfb8aa3b, v0
	v_fma_f32 v1, v29, v1, v46
	v_add_f32_e32 v1, v1, v47
	v_exp_f32_e32 v14, v12
	v_mul_f32_e32 v12, 0xbfb8aa3b, v1
	v_exp_f32_e32 v44, v12
	s_lshl_b64 s[74:75], s[60:61], 11
	v_add_f32_e32 v14, 1.0, v14
	v_rcp_f32_e32 v46, v14
	v_add_f32_e32 v14, 1.0, v44
	v_rcp_f32_e32 v44, v14
	v_mov_b32_e32 v14, v45
	v_mul_f32_e32 v0, v0, v46
	v_mul_f32_e32 v46, v216, v0
	v_mul_f32_e32 v44, v1, v44
	v_mov_b32_e32 v0, v63
	v_mov_b32_e32 v1, v18
	v_pk_mul_f32 v[0:1], v[54:55], v[0:1]
	v_mul_f32_e32 v44, v216, v44
	v_fma_f32 v0, v30, v2, v0
	v_add_f32_e32 v2, v0, v1
	v_mul_f32_e32 v0, 0xbfb8aa3b, v2
	v_exp_f32_e32 v47, v0
	v_mov_b32_e32 v0, v11
	v_mov_b32_e32 v1, v19
	v_pk_mul_f32 v[0:1], v[38:39], v[0:1]
	s_add_u32 s52, s52, 0x3800
	v_fma_f32 v0, v31, v3, v0
	v_add_f32_e32 v3, v0, v1
	v_mul_f32_e32 v0, 0xbfb8aa3b, v3
	v_exp_f32_e32 v0, v0
	v_add_f32_e32 v1, 1.0, v47
	v_rcp_f32_e32 v47, v1
	v_mov_b32_e32 v1, v20
	v_add_f32_e32 v0, 1.0, v0
	v_rcp_f32_e32 v60, v0
	v_mov_b32_e32 v0, v61
	v_pk_mul_f32 v[0:1], v[52:53], v[0:1]
	v_mov_b32_e32 v8, v67
	v_fma_f32 v0, v24, v4, v0
	v_add_f32_e32 v4, v0, v1
	v_mul_f32_e32 v0, 0xbfb8aa3b, v4
	v_exp_f32_e32 v0, v0
	v_mul_f32_e32 v1, v2, v47
	v_mul_f32_e32 v2, v216, v1
	v_mov_b32_e32 v1, v21
	v_add_f32_e32 v0, 1.0, v0
	v_rcp_f32_e32 v47, v0
	v_mov_b32_e32 v0, v13
	v_pk_mul_f32 v[0:1], v[32:33], v[0:1]
	v_mul_f32_e32 v3, v3, v60
	v_fma_f32 v0, v25, v5, v0
	v_add_f32_e32 v5, v0, v1
	v_mul_f32_e32 v0, 0xbfb8aa3b, v5
	v_exp_f32_e32 v0, v0
	v_mul_f32_e32 v1, v4, v47
	v_mul_f32_e32 v4, v216, v1
	v_mov_b32_e32 v1, v22
	v_add_f32_e32 v0, 1.0, v0
	v_rcp_f32_e32 v47, v0
	v_mov_b32_e32 v0, v45
	v_pk_mul_f32 v[0:1], v[50:51], v[0:1]
	v_mul_f32_e32 v3, v216, v3
	v_fma_f32 v0, v26, v6, v0
	v_add_f32_e32 v6, v0, v1
	v_mul_f32_e32 v0, 0xbfb8aa3b, v6
	v_exp_f32_e32 v45, v0
	v_mov_b32_e32 v0, v15
	v_mov_b32_e32 v1, v23
	v_pk_mul_f32 v[0:1], v[34:35], v[0:1]
	v_mul_f32_e32 v5, v5, v47
	v_fma_f32 v0, v27, v7, v0
	v_add_f32_e32 v0, v0, v1
	v_mul_f32_e32 v1, 0xbfb8aa3b, v0
	v_exp_f32_e32 v1, v1
	v_add_f32_e32 v7, 1.0, v45
	v_rcp_f32_e32 v7, v7
	v_mul_f32_e32 v5, v216, v5
	v_add_f32_e32 v1, 1.0, v1
	v_rcp_f32_e32 v1, v1
	v_mul_f32_e32 v6, v6, v7
	v_mul_f32_e32 v6, v216, v6
	v_mov_b32_e32 v10, v63
	v_mul_f32_e32 v0, v0, v1
	v_mul_f32_e32 v7, v216, v0
	v_cvt_pk_bf16_f32 v0, v46, v44
	v_cvt_pk_bf16_f32 v1, v2, v3
	v_cvt_pk_bf16_f32 v2, v4, v5
	v_cvt_pk_bf16_f32 v3, v6, v7
	v_lshl_add_u64 v[4:5], v[158:159], 0, s[74:75]
	global_store_dwordx4 v[4:5], v[0:3], off nt
	v_mov_b32_e32 v12, v61
	s_addc_u32 s53, s53, 0
	v_mov_b64_e32 v[0:1], v[16:17]
	s_add_i32 s60, s60, 2
	s_add_i32 s25, s25, -2
	s_waitcnt vmcnt(1)
	v_mov_b64_e32 v[46:47], v[42:43]
	v_mov_b64_e32 v[2:3], v[18:19]
	v_mov_b64_e32 v[4:5], v[20:21]
	v_mov_b64_e32 v[6:7], v[22:23]
	v_mov_b64_e32 v[22:23], v[14:15]
	v_lshl_add_u64 v[58:59], v[58:59], 0, s[16:17]
	s_cmp_lg_u32 s52, 0x1c000
	v_mov_b64_e32 v[44:45], v[40:41]
	v_mov_b64_e32 v[20:21], v[12:13]
	v_mov_b64_e32 v[18:19], v[10:11]
	v_mov_b64_e32 v[16:17], v[8:9]
	s_cbranch_scc0 .LBB0_365

; __device__ __forceinline__ void unpack8(const u32x4 w, float (&f)[8]) { f[0] = bflo(w.x); f[1] = bfhi(w.x); f[2] = bflo(w.y); f[3] = bfhi(w.y); f[4] = bflo(w.z); f[5] = bfhi(w.z); f[6] = bflo(w.w); f[7] = bfhi(w.w); }
; __device__ __forceinline__ u32x4 pack8(const float (&f)[8]) { u32x4 o; o.x = pk2(f[0], f[1]); o.y = pk2(f[2], f[3]); o.z = pk2(f[4], f[5]); o.w = pk2(f[6], f[7]); return o; }
; __device__ __forceinline__ float siluf_(float x) { return x * __builtin_amdgcn_rcpf(1.0f + __expf(-x)); }
; template <int CH> __device__ __forceinline__ void p2_gla_chunk(const Params& p, int t0, int lane) {
;     ...
; #pragma unroll 2
;     for (int i = 0; i < 16; ++i) {
;         const int t = t0 + i; const bool hasn = (t & (T_SEQ - 1)) != T_SEQ - 1;
;         if (hasn) unpack8(raw, N); else {
; #pragma unroll
;             for (int q = 0; q < 8; ++q) N[q] = 0.f; }
;         if (i < 15 && ((t + 1) & (T_SEQ - 1)) != T_SEQ - 1) raw = __builtin_nontemporal_load((const u32x4*)(zc + (size_t)(i + 2) * ZLD));
;         float o[8];
; #pragma unroll
;         for (int q = 0; q < 8; ++q) { const float y = w0[q] * P[q] + w1[q] * C[q] + w2[q] * N[q]; o[q] = siluf_(y) * sc; }
;         *(u32x4*)(GQKV + (size_t)t * 1024 + c) = pack8(o);
; #pragma unroll
;         for (int q = 0; q < 8; ++q) { P[q] = C[q]; C[q] = N[q]; }
;     }
.LBB0_361:
	v_lshlrev_b32_e32 v67, 16, v44
	v_mov_b32_e32 v66, v0
	v_lshlrev_b32_e32 v63, 16, v45
	v_and_b32_e32 v11, 0xffff0000, v45
	v_lshlrev_b32_e32 v61, 16, v46
	v_and_b32_e32 v13, 0xffff0000, v46
	v_lshlrev_b32_e32 v45, 16, v47
	v_and_b32_e32 v15, 0xffff0000, v47
	v_pk_mul_f32 v[46:47], v[56:57], v[66:67]
	v_and_b32_e32 v9, 0xffff0000, v44
	v_fma_f32 v8, v28, v16, v46
	v_add_f32_e32 v8, v8, v47
	v_mul_f32_e32 v10, 0xbfb8aa3b, v8
	v_exp_f32_e32 v10, v10
	v_mov_b32_e32 v62, v2
	v_mov_b32_e32 v60, v4
	v_mov_b32_e32 v44, v6
	v_add_f32_e32 v10, 1.0, v10
	v_rcp_f32_e32 v10, v10
	s_and_b32 s61, s60, 0xfff
	s_cmpk_eq_i32 s61, 0xfff
	v_mul_f32_e32 v8, v8, v10
	v_mul_f32_e32 v66, v216, v8
	v_mov_b32_e32 v8, v1
	v_pk_mul_f32 v[46:47], v[36:37], v[8:9]
	s_nop 0
	v_fma_f32 v8, v29, v17, v46
	v_add_f32_e32 v8, v8, v47
	v_mul_f32_e32 v10, 0xbfb8aa3b, v8
	v_exp_f32_e32 v10, v10
	v_pk_mul_f32 v[16:17], v[54:55], v[62:63]
	v_add_f32_e32 v10, 1.0, v10
	v_rcp_f32_e32 v10, v10
	s_nop 0
	v_mul_f32_e32 v8, v8, v10
	v_fma_f32 v10, v30, v18, v16
	v_add_f32_e32 v10, v10, v17
	v_mul_f32_e32 v12, 0xbfb8aa3b, v10
	v_exp_f32_e32 v12, v12
	v_mul_f32_e32 v8, v216, v8
	v_add_f32_e32 v12, 1.0, v12
	v_rcp_f32_e32 v12, v12
	s_nop 0
	v_mul_f32_e32 v10, v10, v12
	v_mul_f32_e32 v18, v216, v10
	v_mov_b32_e32 v10, v3
	v_pk_mul_f32 v[16:17], v[38:39], v[10:11]
	s_nop 0
	v_fma_f32 v10, v31, v19, v16
	v_add_f32_e32 v10, v10, v17
	v_mul_f32_e32 v12, 0xbfb8aa3b, v10
	v_exp_f32_e32 v12, v12
	v_pk_mul_f32 v[16:17], v[52:53], v[60:61]
	v_add_f32_e32 v12, 1.0, v12
	v_rcp_f32_e32 v12, v12
	s_nop 0
	v_mul_f32_e32 v10, v10, v12
	v_fma_f32 v12, v24, v20, v16
	v_add_f32_e32 v12, v12, v17
	v_mul_f32_e32 v14, 0xbfb8aa3b, v12
	v_exp_f32_e32 v14, v14
	v_mul_f32_e32 v10, v216, v10
	v_add_f32_e32 v14, 1.0, v14
	v_rcp_f32_e32 v14, v14
	s_nop 0
	v_mul_f32_e32 v12, v12, v14
	v_mul_f32_e32 v19, v216, v12
	v_mov_b32_e32 v12, v5
	v_pk_mul_f32 v[16:17], v[32:33], v[12:13]
	s_nop 0
	v_fma_f32 v12, v25, v21, v16
	v_add_f32_e32 v12, v12, v17
	v_mul_f32_e32 v14, 0xbfb8aa3b, v12
	v_exp_f32_e32 v14, v14
	v_pk_mul_f32 v[16:17], v[50:51], v[44:45]
	v_add_f32_e32 v14, 1.0, v14
	v_rcp_f32_e32 v14, v14
	s_nop 0
	v_mul_f32_e32 v12, v12, v14
	v_fma_f32 v14, v26, v22, v16
	v_add_f32_e32 v14, v14, v17
	v_mul_f32_e32 v16, 0xbfb8aa3b, v14
	v_exp_f32_e32 v16, v16
	v_mul_f32_e32 v12, v216, v12
	v_add_f32_e32 v16, 1.0, v16
	v_rcp_f32_e32 v16, v16
	s_nop 0
	v_mul_f32_e32 v14, v14, v16
	v_mul_f32_e32 v20, v216, v14
	v_mov_b32_e32 v14, v7
	v_pk_mul_f32 v[16:17], v[34:35], v[14:15]
	s_nop 0
	v_fma_f32 v14, v27, v23, v16
	v_add_f32_e32 v14, v14, v17
	v_mul_f32_e32 v16, 0xbfb8aa3b, v14
	v_exp_f32_e32 v16, v16
	v_cvt_pk_bf16_f32 v17, v18, v10
	v_cvt_pk_bf16_f32 v18, v19, v12
	s_nop 0
	v_add_f32_e32 v16, 1.0, v16
	v_rcp_f32_e32 v16, v16
	s_nop 0
	v_mul_f32_e32 v14, v14, v16
	v_mul_f32_e32 v14, v216, v14
	v_cvt_pk_bf16_f32 v16, v66, v8
	v_cvt_pk_bf16_f32 v19, v20, v14
	global_store_dwordx4 v[58:59], v[16:19], off nt
	s_cbranch_scc1 .LBB0_363
	s_waitcnt vmcnt(1)
	v_lshlrev_b32_e32 v16, 16, v40
	v_and_b32_e32 v17, 0xffff0000, v40
	v_lshlrev_b32_e32 v18, 16, v41
	v_and_b32_e32 v19, 0xffff0000, v41
	v_lshlrev_b32_e32 v20, 16, v42
	v_and_b32_e32 v21, 0xffff0000, v42
	v_lshlrev_b32_e32 v22, 16, v43
	v_and_b32_e32 v23, 0xffff0000, v43
	s_cmp_eq_u32 s52, 0x18800
	s_cbranch_scc1 .LBB0_358
	s_branch .LBB0_364

; __device__ __forceinline__ void unpack8(const u32x4 w, float (&f)[8]) { f[0] = bflo(w.x); f[1] = bfhi(w.x); f[2] = bflo(w.y); f[3] = bfhi(w.y); f[4] = bflo(w.z); f[5] = bfhi(w.z); f[6] = bflo(w.w); f[7] = bfhi(w.w); }
; __device__ __forceinline__ u32x4 pack8(const float (&f)[8]) { u32x4 o; o.x = pk2(f[0], f[1]); o.y = pk2(f[2], f[3]); o.z = pk2(f[4], f[5]); o.w = pk2(f[6], f[7]); return o; }
; __device__ __forceinline__ float siluf_(float x) { return x * __builtin_amdgcn_rcpf(1.0f + __expf(-x)); }
; template <int CH> __device__ __forceinline__ void p2_gla_chunk(const Params& p, int t0, int lane) {
;     ...
; #pragma unroll 2
;     for (int i = 0; i < 16; ++i) {
;         const int t = t0 + i; const bool hasn = (t & (T_SEQ - 1)) != T_SEQ - 1;
;         if (hasn) unpack8(raw, N); else {
; #pragma unroll
;             for (int q = 0; q < 8; ++q) N[q] = 0.f; }
;         if (i < 15 && ((t + 1) & (T_SEQ - 1)) != T_SEQ - 1) raw = __builtin_nontemporal_load((const u32x4*)(zc + (size_t)(i + 2) * ZLD));
;         float o[8];
; #pragma unroll
;         for (int q = 0; q < 8; ++q) { const float y = w0[q] * P[q] + w1[q] * C[q] + w2[q] * N[q]; o[q] = siluf_(y) * sc; }
;         *(u32x4*)(GQKV + (size_t)t * 1024 + c) = pack8(o);
; #pragma unroll
;         for (int q = 0; q < 8; ++q) { P[q] = C[q]; C[q] = N[q]; }
;     }
.LBB0_369:
	v_mov_b32_e32 v46, v67
	v_mov_b32_e32 v47, v16
	v_pk_mul_f32 v[46:47], v[58:59], v[46:47]
	v_mov_b32_e32 v14, v45
	v_fma_f32 v0, v28, v0, v46
	v_add_f32_e32 v44, v0, v47
	v_mul_f32_e32 v0, 0xbfb8aa3b, v44
	v_exp_f32_e32 v0, v0
	v_mov_b32_e32 v46, v9
	v_mov_b32_e32 v47, v17
	v_pk_mul_f32 v[46:47], v[36:37], v[46:47]
	v_add_f32_e32 v60, 1.0, v0
	v_fma_f32 v0, v29, v1, v46
	v_add_f32_e32 v46, v0, v47
	v_mul_f32_e32 v0, 0xbfb8aa3b, v46
	v_exp_f32_e32 v47, v0
	v_mov_b32_e32 v0, v63
	v_mov_b32_e32 v1, v18
	v_pk_mul_f32 v[0:1], v[56:57], v[0:1]
	v_rcp_f32_e32 v60, v60
	v_fma_f32 v0, v30, v2, v0
	v_add_f32_e32 v2, v0, v1
	v_mul_f32_e32 v0, 0xbfb8aa3b, v2
	v_exp_f32_e32 v0, v0
	v_add_f32_e32 v1, 1.0, v47
	v_rcp_f32_e32 v47, v1
	v_mov_b32_e32 v1, v19
	v_add_f32_e32 v0, 1.0, v0
	v_rcp_f32_e32 v62, v0
	v_mov_b32_e32 v0, v11
	v_pk_mul_f32 v[0:1], v[38:39], v[0:1]
	v_mul_f32_e32 v46, v46, v47
	v_fma_f32 v0, v31, v3, v0
	v_add_f32_e32 v3, v0, v1
	v_mul_f32_e32 v0, 0xbfb8aa3b, v3
	v_exp_f32_e32 v0, v0
	v_mov_b32_e32 v1, v20
	v_mul_f32_e32 v44, v44, v60
	s_ashr_i32 s27, s26, 31
	v_add_f32_e32 v0, 1.0, v0
	v_rcp_f32_e32 v47, v0
	v_mov_b32_e32 v0, v61
	v_pk_mul_f32 v[0:1], v[54:55], v[0:1]
	v_mul_f32_e32 v2, v2, v62
	v_fma_f32 v0, v24, v4, v0
	v_add_f32_e32 v4, v0, v1
	v_mul_f32_e32 v0, 0xbfb8aa3b, v4
	v_exp_f32_e32 v60, v0
	v_mov_b32_e32 v0, v13
	v_mov_b32_e32 v1, v21
	v_pk_mul_f32 v[0:1], v[32:33], v[0:1]
	v_mul_f32_e32 v3, v3, v47
	v_fma_f32 v0, v25, v5, v0
	v_add_f32_e32 v5, v0, v1
	v_mul_f32_e32 v0, 0xbfb8aa3b, v5
	v_exp_f32_e32 v0, v0
	v_add_f32_e32 v1, 1.0, v60
	v_rcp_f32_e32 v47, v1
	v_mov_b32_e32 v1, v22
	v_add_f32_e32 v60, 1.0, v0
	v_mov_b32_e32 v0, v45
	v_pk_mul_f32 v[0:1], v[52:53], v[0:1]
	v_mul_f32_e32 v4, v4, v47
	v_fma_f32 v0, v26, v6, v0
	v_add_f32_e32 v6, v0, v1
	v_mul_f32_e32 v0, 0xbfb8aa3b, v6
	v_exp_f32_e32 v45, v0
	v_mov_b32_e32 v0, v15
	v_mov_b32_e32 v1, v23
	v_pk_mul_f32 v[0:1], v[34:35], v[0:1]
	v_add_f32_e32 v45, 1.0, v45
	v_fma_f32 v0, v27, v7, v0
	v_add_f32_e32 v0, v0, v1
	v_mul_f32_e32 v1, 0xbfb8aa3b, v0
	v_exp_f32_e32 v1, v1
	v_rcp_f32_e32 v7, v60
	v_rcp_f32_e32 v45, v45
	s_lshl_b64 s[42:43], s[26:27], 11
	v_add_f32_e32 v1, 1.0, v1
	v_rcp_f32_e32 v1, v1
	v_mul_f32_e32 v5, v5, v7
	v_mul_f32_e32 v6, v6, v45
	s_add_u32 s14, s14, 0x3800
	v_mul_f32_e32 v7, v0, v1
	v_cvt_pk_bf16_f32 v0, v44, v46
	v_cvt_pk_bf16_f32 v1, v2, v3
	v_cvt_pk_bf16_f32 v2, v4, v5
	v_cvt_pk_bf16_f32 v3, v6, v7
	v_lshl_add_u64 v[4:5], v[174:175], 0, s[42:43]
	global_store_dwordx4 v[4:5], v[0:3], off nt
	v_mov_b32_e32 v8, v67
	v_mov_b32_e32 v10, v63
	v_mov_b64_e32 v[0:1], v[16:17]
	v_mov_b32_e32 v12, v61
	s_addc_u32 s15, s15, 0
	s_add_i32 s26, s26, 2
	s_add_i32 s25, s25, -2
	s_waitcnt vmcnt(1)
	v_mov_b64_e32 v[46:47], v[42:43]
	v_mov_b64_e32 v[2:3], v[18:19]
	v_mov_b64_e32 v[4:5], v[20:21]
	v_mov_b64_e32 v[6:7], v[22:23]
	v_mov_b64_e32 v[22:23], v[14:15]
	v_lshl_add_u64 v[50:51], v[50:51], 0, s[16:17]
	s_cmp_lg_u32 s14, 0x1c000
	v_mov_b64_e32 v[44:45], v[40:41]
	v_mov_b64_e32 v[20:21], v[12:13]
	v_mov_b64_e32 v[18:19], v[10:11]
	v_mov_b64_e32 v[16:17], v[8:9]
	s_cbranch_scc0 .LBB0_376

; __device__ __forceinline__ void unpack8(const u32x4 w, float (&f)[8]) { f[0] = bflo(w.x); f[1] = bfhi(w.x); f[2] = bflo(w.y); f[3] = bfhi(w.y); f[4] = bflo(w.z); f[5] = bfhi(w.z); f[6] = bflo(w.w); f[7] = bfhi(w.w); }
; __device__ __forceinline__ u32x4 pack8(const float (&f)[8]) { u32x4 o; o.x = pk2(f[0], f[1]); o.y = pk2(f[2], f[3]); o.z = pk2(f[4], f[5]); o.w = pk2(f[6], f[7]); return o; }
; __device__ __forceinline__ float siluf_(float x) { return x * __builtin_amdgcn_rcpf(1.0f + __expf(-x)); }
; template <int CH> __device__ __forceinline__ void p2_gla_chunk(const Params& p, int t0, int lane) {
;     ...
; #pragma unroll 2
;     for (int i = 0; i < 16; ++i) {
;         const int t = t0 + i; const bool hasn = (t & (T_SEQ - 1)) != T_SEQ - 1;
;         if (hasn) unpack8(raw, N); else {
; #pragma unroll
;             for (int q = 0; q < 8; ++q) N[q] = 0.f; }
;         if (i < 15 && ((t + 1) & (T_SEQ - 1)) != T_SEQ - 1) raw = __builtin_nontemporal_load((const u32x4*)(zc + (size_t)(i + 2) * ZLD));
;         float o[8];
; #pragma unroll
;         for (int q = 0; q < 8; ++q) { const float y = w0[q] * P[q] + w1[q] * C[q] + w2[q] * N[q]; o[q] = siluf_(y) * sc; }
;         *(u32x4*)(GQKV + (size_t)t * 1024 + c) = pack8(o);
; #pragma unroll
;         for (int q = 0; q < 8; ++q) { P[q] = C[q]; C[q] = N[q]; }
;     }
.LBB0_372:
	v_lshlrev_b32_e32 v67, 16, v44
	v_mov_b32_e32 v66, v0
	v_pk_mul_f32 v[12:13], v[58:59], v[66:67]
	v_and_b32_e32 v9, 0xffff0000, v44
	v_fma_f32 v8, v28, v16, v12
	v_add_f32_e32 v12, v8, v13
	v_mul_f32_e32 v8, 0xbfb8aa3b, v12
	v_exp_f32_e32 v8, v8
	v_lshlrev_b32_e32 v63, 16, v45
	v_and_b32_e32 v11, 0xffff0000, v45
	v_lshlrev_b32_e32 v61, 16, v46
	v_add_f32_e32 v10, 1.0, v8
	v_mov_b32_e32 v8, v1
	v_and_b32_e32 v13, 0xffff0000, v46
	v_lshlrev_b32_e32 v45, 16, v47
	v_and_b32_e32 v15, 0xffff0000, v47
	v_pk_mul_f32 v[46:47], v[36:37], v[8:9]
	v_mov_b32_e32 v62, v2
	v_fma_f32 v8, v29, v17, v46
	v_pk_mul_f32 v[16:17], v[56:57], v[62:63]
	v_add_f32_e32 v8, v8, v47
	v_fma_f32 v16, v30, v18, v16
	v_mul_f32_e32 v14, 0xbfb8aa3b, v8
	v_add_f32_e32 v18, v16, v17
	v_exp_f32_e32 v14, v14
	v_mul_f32_e32 v16, 0xbfb8aa3b, v18
	v_exp_f32_e32 v16, v16
	v_rcp_f32_e32 v44, v10
	v_add_f32_e32 v10, 1.0, v14
	v_rcp_f32_e32 v14, v10
	v_add_f32_e32 v10, 1.0, v16
	v_rcp_f32_e32 v46, v10
	v_mov_b32_e32 v10, v3
	v_pk_mul_f32 v[16:17], v[38:39], v[10:11]
	v_mov_b32_e32 v60, v4
	v_fma_f32 v10, v31, v19, v16
	v_add_f32_e32 v10, v10, v17
	v_mul_f32_e32 v16, 0xbfb8aa3b, v10
	v_exp_f32_e32 v16, v16
	v_mul_f32_e32 v19, v12, v44
	v_mul_f32_e32 v8, v8, v14
	v_mul_f32_e32 v18, v18, v46
	v_add_f32_e32 v12, 1.0, v16
	v_pk_mul_f32 v[16:17], v[54:55], v[60:61]
	v_rcp_f32_e32 v14, v12
	v_fma_f32 v12, v24, v20, v16
	v_add_f32_e32 v20, v12, v17
	v_mul_f32_e32 v12, 0xbfb8aa3b, v20
	v_exp_f32_e32 v44, v12
	v_mov_b32_e32 v12, v5
	v_pk_mul_f32 v[16:17], v[32:33], v[12:13]
	v_mul_f32_e32 v10, v10, v14
	v_fma_f32 v12, v25, v21, v16
	v_add_f32_e32 v12, v12, v17
	v_mul_f32_e32 v16, 0xbfb8aa3b, v12
	v_exp_f32_e32 v16, v16
	v_add_f32_e32 v14, 1.0, v44
	v_mov_b32_e32 v44, v6
	v_rcp_f32_e32 v21, v14
	v_add_f32_e32 v46, 1.0, v16
	v_pk_mul_f32 v[16:17], v[52:53], v[44:45]
	s_and_b32 s27, s26, 0xfff
	v_fma_f32 v14, v26, v22, v16
	v_add_f32_e32 v22, v14, v17
	v_mul_f32_e32 v14, 0xbfb8aa3b, v22
	v_exp_f32_e32 v44, v14
	v_mov_b32_e32 v14, v7
	v_pk_mul_f32 v[16:17], v[34:35], v[14:15]
	s_cmpk_eq_i32 s27, 0xfff
	v_fma_f32 v14, v27, v23, v16
	v_add_f32_e32 v14, v14, v17
	v_mul_f32_e32 v16, 0xbfb8aa3b, v14
	v_exp_f32_e32 v16, v16
	v_add_f32_e32 v23, 1.0, v44
	v_rcp_f32_e32 v17, v46
	v_rcp_f32_e32 v23, v23
	v_add_f32_e32 v16, 1.0, v16
	v_rcp_f32_e32 v16, v16
	v_mul_f32_e32 v20, v20, v21
	v_mul_f32_e32 v12, v12, v17
	v_mul_f32_e32 v21, v22, v23
	v_mul_f32_e32 v14, v14, v16
	v_cvt_pk_bf16_f32 v16, v19, v8
	v_cvt_pk_bf16_f32 v17, v18, v10
	v_cvt_pk_bf16_f32 v18, v20, v12
	v_cvt_pk_bf16_f32 v19, v21, v14
	global_store_dwordx4 v[50:51], v[16:19], off nt
	s_cbranch_scc1 .LBB0_374
	s_waitcnt vmcnt(1)
	v_lshlrev_b32_e32 v16, 16, v40
	v_and_b32_e32 v17, 0xffff0000, v40
	v_lshlrev_b32_e32 v18, 16, v41
	v_and_b32_e32 v19, 0xffff0000, v41
	v_lshlrev_b32_e32 v20, 16, v42
	v_and_b32_e32 v21, 0xffff0000, v42
	v_lshlrev_b32_e32 v22, 16, v43
	v_and_b32_e32 v23, 0xffff0000, v43
	s_cmp_eq_u32 s14, 0x18800
	s_cbranch_scc1 .LBB0_369
	s_branch .LBB0_375

; __device__ __forceinline__ void p2_gate(const Params& p, const LAS float* aup, int t0, int lane) {
;     ...
; #pragma unroll 2
;     for (int i = 0; i < 16; ++i) {
;         const int t = t0 + i; const bf16_t* zg = (const bf16_t*)(ws + WS_Z) + (size_t)t * ZLD + NRW;
;         *(u32x4*)(GG + (size_t)t * 512 + lane * 8) = __builtin_nontemporal_load((const u32x4*)(zg + 1024 + lane * 8));
;         const unsigned short araw = zg[1536 + (lane & 31)]; const int alo = (int)((unsigned)araw << 16);
;         f32x4 acc0 = ab0, acc1 = ab1;
; #pragma unroll
;         for (int r = 0; r < 16; ++r) { const float a0 = __int_as_float(__builtin_amdgcn_readlane(alo, r)), a1 = __int_as_float(__builtin_amdgcn_readlane(alo, 16 + r));
;             acc0 += a0 * *(const LAS f32x4*)(aup + r * 256 + 4 * lane); acc1 += a1 * *(const LAS f32x4*)(aup + (16 + r) * 256 + 4 * lane); }
.LBB0_377:
	v_lshl_add_u64 v[212:213], s[58:59], 0, v[208:209]
	global_load_dwordx4 v[222:225], v[212:213], off nt
	v_lshl_add_u64 v[212:213], s[58:59], 0, v[206:207]
	v_lshl_add_u64 v[206:207], v[206:207], 0, s[48:49]
	v_lshl_add_u64 v[208:209], v[208:209], 0, s[38:39]
	s_waitcnt vmcnt(0)
	global_store_dwordx4 v[212:213], v[222:225], off nt
	v_lshl_add_u64 v[212:213], s[58:59], 0, v[210:211]
	global_load_ushort v199, v[212:213], off
	v_lshl_add_u64 v[210:211], v[210:211], 0, s[38:39]
	s_waitcnt vmcnt(0)
	v_lshlrev_b32_e32 v199, 16, v199
	s_nop 0
	v_readlane_b32 s0, v199, 0
	v_readlane_b32 s14, v199, 16
	s_waitcnt lgkmcnt(14)
	v_pk_fma_f32 v[212:213], v[10:11], s[0:1], v[2:3] op_sel_hi:[1,0,1]
	v_pk_fma_f32 v[214:215], v[8:9], s[0:1], v[0:1] op_sel_hi:[1,0,1]
	v_readlane_b32 s0, v199, 1
	v_pk_fma_f32 v[222:223], v[18:19], s[14:15], v[6:7] op_sel_hi:[1,0,1]
	v_pk_fma_f32 v[224:225], v[16:17], s[14:15], v[4:5] op_sel_hi:[1,0,1]
	v_pk_fma_f32 v[212:213], v[14:15], s[0:1], v[212:213] op_sel_hi:[1,0,1]
	v_pk_fma_f32 v[214:215], v[12:13], s[0:1], v[214:215] op_sel_hi:[1,0,1]
	v_readlane_b32 s0, v199, 2
	v_readlane_b32 s14, v199, 17
	s_nop 0
	v_pk_fma_f32 v[212:213], v[26:27], s[0:1], v[212:213] op_sel_hi:[1,0,1]
	v_pk_fma_f32 v[214:215], v[24:25], s[0:1], v[214:215] op_sel_hi:[1,0,1]
	v_readlane_b32 s0, v199, 3
	v_pk_fma_f32 v[222:223], v[22:23], s[14:15], v[222:223] op_sel_hi:[1,0,1]
	v_pk_fma_f32 v[224:225], v[20:21], s[14:15], v[224:225] op_sel_hi:[1,0,1]
	v_pk_fma_f32 v[212:213], v[30:31], s[0:1], v[212:213] op_sel_hi:[1,0,1]
	v_pk_fma_f32 v[214:215], v[28:29], s[0:1], v[214:215] op_sel_hi:[1,0,1]
	v_readlane_b32 s0, v199, 4
	v_readlane_b32 s14, v199, 18
	s_nop 0
	v_pk_fma_f32 v[212:213], v[42:43], s[0:1], v[212:213] op_sel_hi:[1,0,1]
	v_pk_fma_f32 v[214:215], v[40:41], s[0:1], v[214:215] op_sel_hi:[1,0,1]
	v_readlane_b32 s0, v199, 5
	v_pk_fma_f32 v[222:223], v[34:35], s[14:15], v[222:223] op_sel_hi:[1,0,1]
	v_pk_fma_f32 v[224:225], v[32:33], s[14:15], v[224:225] op_sel_hi:[1,0,1]
	v_pk_fma_f32 v[212:213], v[46:47], s[0:1], v[212:213] op_sel_hi:[1,0,1]
	v_pk_fma_f32 v[214:215], v[44:45], s[0:1], v[214:215] op_sel_hi:[1,0,1]
	v_readlane_b32 s0, v199, 6
	v_readlane_b32 s14, v199, 19
	s_nop 0
	v_pk_fma_f32 v[212:213], v[58:59], s[0:1], v[212:213] op_sel_hi:[1,0,1]
	v_pk_fma_f32 v[214:215], v[56:57], s[0:1], v[214:215] op_sel_hi:[1,0,1]
	v_readlane_b32 s0, v199, 7
	v_pk_fma_f32 v[222:223], v[38:39], s[14:15], v[222:223] op_sel_hi:[1,0,1]
	v_pk_fma_f32 v[224:225], v[36:37], s[14:15], v[224:225] op_sel_hi:[1,0,1]
	v_pk_fma_f32 v[212:213], v[62:63], s[0:1], v[212:213] op_sel_hi:[1,0,1]
	v_pk_fma_f32 v[214:215], v[60:61], s[0:1], v[214:215] op_sel_hi:[1,0,1]
	v_readlane_b32 s0, v199, 8
	v_readlane_b32 s14, v199, 20
	s_nop 0
	v_pk_fma_f32 v[212:213], v[74:75], s[0:1], v[212:213] op_sel_hi:[1,0,1]
	v_pk_fma_f32 v[214:215], v[72:73], s[0:1], v[214:215] op_sel_hi:[1,0,1]
	v_readlane_b32 s0, v199, 9
	v_pk_fma_f32 v[222:223], v[50:51], s[14:15], v[222:223] op_sel_hi:[1,0,1]
	v_pk_fma_f32 v[224:225], v[48:49], s[14:15], v[224:225] op_sel_hi:[1,0,1]
	v_pk_fma_f32 v[212:213], v[78:79], s[0:1], v[212:213] op_sel_hi:[1,0,1]
	v_pk_fma_f32 v[214:215], v[76:77], s[0:1], v[214:215] op_sel_hi:[1,0,1]
	v_readlane_b32 s0, v199, 10
	v_readlane_b32 s14, v199, 21
	s_waitcnt lgkmcnt(11)
	v_pk_fma_f32 v[212:213], v[90:91], s[0:1], v[212:213] op_sel_hi:[1,0,1]
	v_pk_fma_f32 v[214:215], v[88:89], s[0:1], v[214:215] op_sel_hi:[1,0,1]
	v_readlane_b32 s0, v199, 11
	v_pk_fma_f32 v[222:223], v[54:55], s[14:15], v[222:223] op_sel_hi:[1,0,1]
	v_pk_fma_f32 v[224:225], v[52:53], s[14:15], v[224:225] op_sel_hi:[1,0,1]
	s_waitcnt lgkmcnt(10)
	v_pk_fma_f32 v[212:213], v[94:95], s[0:1], v[212:213] op_sel_hi:[1,0,1]
	v_pk_fma_f32 v[214:215], v[92:93], s[0:1], v[214:215] op_sel_hi:[1,0,1]
	v_readlane_b32 s0, v199, 12
	v_readlane_b32 s14, v199, 22
	s_waitcnt lgkmcnt(7)
	v_pk_fma_f32 v[212:213], v[106:107], s[0:1], v[212:213] op_sel_hi:[1,0,1]
	v_pk_fma_f32 v[214:215], v[104:105], s[0:1], v[214:215] op_sel_hi:[1,0,1]
	v_readlane_b32 s0, v199, 13
	v_pk_fma_f32 v[222:223], v[66:67], s[14:15], v[222:223] op_sel_hi:[1,0,1]
	v_pk_fma_f32 v[224:225], v[64:65], s[14:15], v[224:225] op_sel_hi:[1,0,1]
	s_waitcnt lgkmcnt(6)
	v_pk_fma_f32 v[212:213], v[110:111], s[0:1], v[212:213] op_sel_hi:[1,0,1]
	v_pk_fma_f32 v[214:215], v[108:109], s[0:1], v[214:215] op_sel_hi:[1,0,1]
	v_readlane_b32 s0, v199, 14
	v_readlane_b32 s14, v199, 23
	s_waitcnt lgkmcnt(3)
	v_pk_fma_f32 v[212:213], v[122:123], s[0:1], v[212:213] op_sel_hi:[1,0,1]
	v_pk_fma_f32 v[214:215], v[120:121], s[0:1], v[214:215] op_sel_hi:[1,0,1]
	v_readlane_b32 s0, v199, 15
	v_pk_fma_f32 v[222:223], v[70:71], s[14:15], v[222:223] op_sel_hi:[1,0,1]
	v_pk_fma_f32 v[224:225], v[68:69], s[14:15], v[224:225] op_sel_hi:[1,0,1]
	s_waitcnt lgkmcnt(2)
; __device__ __forceinline__ void p2_gate(const Params& p, const LAS float* aup, int t0, int lane) {
;     ...
;         for (int r = 0; r < 16; ++r) { const float a0 = __int_as_float(__builtin_amdgcn_readlane(alo, r)), a1 = __int_as_float(__builtin_amdgcn_readlane(alo, 16 + r));
;             acc0 += a0 * *(const LAS f32x4*)(aup + r * 256 + 4 * lane); acc1 += a1 * *(const LAS f32x4*)(aup + (16 + r) * 256 + 4 * lane); }
;         float n0[4], n1[4];
; #pragma unroll
;         for (int j = 0; j < 4; ++j) { const float y0 = -acc0[j], y1 = -acc1[j];
;             n0[j] = (fmaxf(y0, 0.f) + __logf(1.0f + __expf(-fabsf(y0)))) * 0.0625f; n1[j] = (fmaxf(y1, 0.f) + __logf(1.0f + __expf(-fabsf(y1)))) * 0.0625f; }
	v_pk_fma_f32 v[214:215], v[124:125], s[0:1], v[214:215] op_sel_hi:[1,0,1]
	v_readlane_b32 s14, v199, 24
	v_mul_f32_e64 v201, |v214|, s69
	v_exp_f32_e32 v201, v201
	v_pk_fma_f32 v[222:223], v[82:83], s[14:15], v[222:223] op_sel_hi:[1,0,1]
	v_pk_fma_f32 v[224:225], v[80:81], s[14:15], v[224:225] op_sel_hi:[1,0,1]
	v_readlane_b32 s14, v199, 25
	v_add_f32_e32 v201, 1.0, v201
	v_cmp_gt_f32_e32 vcc, s70, v201
	v_pk_fma_f32 v[222:223], v[86:87], s[14:15], v[222:223] op_sel_hi:[1,0,1]
	v_pk_fma_f32 v[224:225], v[84:85], s[14:15], v[224:225] op_sel_hi:[1,0,1]
	v_cndmask_b32_e64 v203, 0, 32, vcc
	v_ldexp_f32 v201, v201, v203
	v_log_f32_e32 v201, v201
	v_readlane_b32 s14, v199, 26
	v_pk_fma_f32 v[212:213], v[126:127], s[0:1], v[212:213] op_sel_hi:[1,0,1]
	v_mul_f32_e32 v203, 0x3f317217, v201
	v_pk_fma_f32 v[222:223], v[98:99], s[14:15], v[222:223] op_sel_hi:[1,0,1]
	v_pk_fma_f32 v[224:225], v[96:97], s[14:15], v[224:225] op_sel_hi:[1,0,1]
	v_readlane_b32 s14, v199, 27
	v_fma_f32 v203, v201, s71, -v203
	v_fmac_f32_e32 v203, 0x3377d1cf, v201
	v_pk_fma_f32 v[222:223], v[102:103], s[14:15], v[222:223] op_sel_hi:[1,0,1]
	v_pk_fma_f32 v[224:225], v[100:101], s[14:15], v[224:225] op_sel_hi:[1,0,1]
	v_readlane_b32 s14, v199, 28
	v_fmac_f32_e32 v203, 0x3f317217, v201
	v_cmp_lt_f32_e64 s[0:1], |v201|, s72
	v_pk_fma_f32 v[222:223], v[114:115], s[14:15], v[222:223] op_sel_hi:[1,0,1]
	v_pk_fma_f32 v[224:225], v[112:113], s[14:15], v[224:225] op_sel_hi:[1,0,1]
	v_readlane_b32 s14, v199, 29
	v_cndmask_b32_e64 v201, v201, v203, s[0:1]
	v_cndmask_b32_e32 v203, 0, v221, vcc
	v_pk_fma_f32 v[222:223], v[118:119], s[14:15], v[222:223] op_sel_hi:[1,0,1]
	v_pk_fma_f32 v[224:225], v[116:117], s[14:15], v[224:225] op_sel_hi:[1,0,1]
	v_readlane_b32 s14, v199, 30
	v_sub_f32_e32 v201, v201, v203
	s_waitcnt lgkmcnt(1)
	v_pk_fma_f32 v[222:223], v[130:131], s[14:15], v[222:223] op_sel_hi:[1,0,1]
	v_pk_fma_f32 v[224:225], v[128:129], s[14:15], v[224:225] op_sel_hi:[1,0,1]
	v_readlane_b32 s14, v199, 31
	v_max_f32_e64 v199, -v214, 0
	v_add_f32_e32 v199, v199, v201
	s_waitcnt lgkmcnt(0)
	v_pk_fma_f32 v[224:225], v[132:133], s[14:15], v[224:225] op_sel_hi:[1,0,1]
	v_mul_f32_e32 v214, 0x3d800000, v199
	v_mul_f32_e64 v201, |v224|, s69
	v_exp_f32_e32 v201, v201
	v_max_f32_e64 v199, -v224, 0
	v_pk_fma_f32 v[222:223], v[134:135], s[14:15], v[222:223] op_sel_hi:[1,0,1]
	v_add_f32_e32 v201, 1.0, v201
	v_cmp_gt_f32_e32 vcc, s70, v201
	s_nop 1
	v_cndmask_b32_e64 v203, 0, 32, vcc
	v_ldexp_f32 v201, v201, v203
	v_log_f32_e32 v201, v201
	s_nop 0
	v_mul_f32_e32 v203, 0x3f317217, v201
	v_fma_f32 v203, v201, s71, -v203
	v_fmac_f32_e32 v203, 0x3377d1cf, v201
	v_fmac_f32_e32 v203, 0x3f317217, v201
	v_cmp_lt_f32_e64 s[0:1], |v201|, s72
	s_nop 1
	v_cndmask_b32_e64 v201, v201, v203, s[0:1]
	v_cndmask_b32_e32 v203, 0, v221, vcc
	v_sub_f32_e32 v201, v201, v203
	v_mul_f32_e64 v203, |v215|, s69
	v_exp_f32_e32 v203, v203
	v_add_f32_e32 v199, v199, v201
	v_max_f32_e64 v201, -v215, 0
	v_mul_f32_e32 v199, 0x3d800000, v199
	v_add_f32_e32 v203, 1.0, v203
	v_cmp_gt_f32_e32 vcc, s70, v203
	s_nop 1
	v_cndmask_b32_e64 v215, 0, 32, vcc
	v_ldexp_f32 v203, v203, v215
	v_log_f32_e32 v203, v203
	s_nop 0
	v_mul_f32_e32 v215, 0x3f317217, v203
	v_fma_f32 v215, v203, s71, -v215
	v_fmac_f32_e32 v215, 0x3377d1cf, v203
	v_fmac_f32_e32 v215, 0x3f317217, v203
	v_cmp_lt_f32_e64 s[0:1], |v203|, s72
	s_nop 1
	v_cndmask_b32_e64 v203, v203, v215, s[0:1]
	v_cndmask_b32_e32 v215, 0, v221, vcc
	v_sub_f32_e32 v203, v203, v215
	v_add_f32_e32 v201, v201, v203
	v_mul_f32_e64 v203, |v225|, s69
	v_exp_f32_e32 v203, v203
	v_mul_f32_e32 v215, 0x3d800000, v201
	v_max_f32_e64 v201, -v225, 0
	v_add_f32_e32 v203, 1.0, v203
	v_cmp_gt_f32_e32 vcc, s70, v203
	s_nop 1
	v_cndmask_b32_e64 v224, 0, 32, vcc
	v_ldexp_f32 v203, v203, v224
	v_log_f32_e32 v203, v203
	s_nop 0
	v_mul_f32_e32 v224, 0x3f317217, v203
	v_fma_f32 v224, v203, s71, -v224
	v_fmac_f32_e32 v224, 0x3377d1cf, v203
	v_fmac_f32_e32 v224, 0x3f317217, v203
	v_cmp_lt_f32_e64 s[0:1], |v203|, s72
	s_nop 1
	v_cndmask_b32_e64 v203, v203, v224, s[0:1]
	v_cndmask_b32_e32 v224, 0, v221, vcc
	v_sub_f32_e32 v203, v203, v224
	v_add_f32_e32 v201, v201, v203
	v_max_f32_e64 v203, -v212, 0
	v_mul_f32_e64 v212, |v212|, s69
	v_exp_f32_e32 v212, v212
	v_mul_f32_e32 v201, 0x3d800000, v201
	v_add_f32_e32 v212, 1.0, v212
	v_cmp_gt_f32_e32 vcc, s70, v212
	s_nop 1
	v_cndmask_b32_e64 v224, 0, 32, vcc
	v_ldexp_f32 v212, v212, v224
	v_log_f32_e32 v212, v212
	s_nop 0
	v_mul_f32_e32 v224, 0x3f317217, v212
	v_fma_f32 v224, v212, s71, -v224
	v_fmac_f32_e32 v224, 0x3377d1cf, v212
	v_fmac_f32_e32 v224, 0x3f317217, v212
	v_cmp_lt_f32_e64 s[0:1], |v212|, s72
	s_nop 1
	v_cndmask_b32_e64 v212, v212, v224, s[0:1]
	v_cndmask_b32_e32 v224, 0, v221, vcc
	v_sub_f32_e32 v212, v212, v224
	v_add_f32_e32 v203, v203, v212
	v_mul_f32_e64 v212, |v222|, s69
	v_exp_f32_e32 v212, v212
	v_mul_f32_e32 v224, 0x3d800000, v203
	v_max_f32_e64 v203, -v222, 0
	v_add_f32_e32 v212, 1.0, v212
	v_cmp_gt_f32_e32 vcc, s70, v212
	s_nop 1
	v_cndmask_b32_e64 v222, 0, 32, vcc
	v_ldexp_f32 v212, v212, v222
	v_log_f32_e32 v212, v212
	s_nop 0
	v_mul_f32_e32 v222, 0x3f317217, v212
	v_fma_f32 v222, v212, s71, -v222
	v_fmac_f32_e32 v222, 0x3377d1cf, v212
	v_fmac_f32_e32 v222, 0x3f317217, v212
	v_cmp_lt_f32_e64 s[0:1], |v212|, s72
	s_nop 1
	v_cndmask_b32_e64 v212, v212, v222, s[0:1]
	v_cndmask_b32_e32 v222, 0, v221, vcc
	v_sub_f32_e32 v212, v212, v222
	v_add_f32_e32 v203, v203, v212
	v_max_f32_e64 v212, -v213, 0
	v_mul_f32_e64 v213, |v213|, s69
	v_exp_f32_e32 v213, v213
	v_mul_f32_e32 v203, 0x3d800000, v203
	v_add_f32_e32 v213, 1.0, v213
	v_cmp_gt_f32_e32 vcc, s70, v213
; __device__ __forceinline__ unsigned pk2(float lo, float hi) { unsigned r; asm("v_cvt_pk_bf16_f32 %0, %1, %2" : "=v"(r) : "v"(lo), "v"(hi)); return r; }
; __device__ __forceinline__ void p2_gate(const Params& p, const LAS float* aup, int t0, int lane) {
;     ...
;     for (int i = 0; i < 16; ++i) {
;         const int t = t0 + i; const bf16_t* zg = (const bf16_t*)(ws + WS_Z) + (size_t)t * ZLD + NRW;
;         *(u32x4*)(GG + (size_t)t * 512 + lane * 8) = __builtin_nontemporal_load((const u32x4*)(zg + 1024 + lane * 8));
;         const unsigned short araw = zg[1536 + (lane & 31)]; const int alo = (int)((unsigned)araw << 16);
;         f32x4 acc0 = ab0, acc1 = ab1;
; #pragma unroll
;         for (int r = 0; r < 16; ++r) { const float a0 = __int_as_float(__builtin_amdgcn_readlane(alo, r)), a1 = __int_as_float(__builtin_amdgcn_readlane(alo, 16 + r));
;             acc0 += a0 * *(const LAS f32x4*)(aup + r * 256 + 4 * lane); acc1 += a1 * *(const LAS f32x4*)(aup + (16 + r) * 256 + 4 * lane); }
;         float n0[4], n1[4];
; #pragma unroll
;         for (int j = 0; j < 4; ++j) { const float y0 = -acc0[j], y1 = -acc1[j];
;             n0[j] = (fmaxf(y0, 0.f) + __logf(1.0f + __expf(-fabsf(y0)))) * 0.0625f; n1[j] = (fmaxf(y1, 0.f) + __logf(1.0f + __expf(-fabsf(y1)))) * 0.0625f; }
;         u32x2 w; w.x = pk2(n0[0], n0[1]); w.y = pk2(n0[2], n0[3]); *(u32x2*)(GNL + (size_t)t * 512 + 4 * lane) = w;
;         w.x = pk2(n1[0], n1[1]); w.y = pk2(n1[2], n1[3]); *(u32x2*)(GNL + (size_t)t * 512 + 256 + 4 * lane) = w;
	s_nop 1
	v_cndmask_b32_e64 v222, 0, 32, vcc
	v_ldexp_f32 v213, v213, v222
	v_log_f32_e32 v213, v213
	s_nop 0
	v_mul_f32_e32 v222, 0x3f317217, v213
	v_fma_f32 v222, v213, s71, -v222
	v_fmac_f32_e32 v222, 0x3377d1cf, v213
	v_fmac_f32_e32 v222, 0x3f317217, v213
	v_cmp_lt_f32_e64 s[0:1], |v213|, s72
	s_nop 1
	v_cndmask_b32_e64 v213, v213, v222, s[0:1]
	v_cndmask_b32_e32 v222, 0, v221, vcc
	v_sub_f32_e32 v213, v213, v222
	v_mul_f32_e64 v222, |v223|, s69
	v_exp_f32_e32 v222, v222
	v_add_f32_e32 v212, v212, v213
	v_mul_f32_e32 v213, 0x3d800000, v212
	v_max_f32_e64 v212, -v223, 0
	v_add_f32_e32 v222, 1.0, v222
	v_cmp_gt_f32_e32 vcc, s70, v222
	v_cvt_pk_bf16_f32 v213, v224, v213
	s_nop 1
	v_cndmask_b32_e64 v223, 0, 32, vcc
	v_ldexp_f32 v222, v222, v223
	v_log_f32_e32 v222, v222
	s_nop 0
	v_mul_f32_e32 v223, 0x3f317217, v222
	v_fma_f32 v223, v222, s71, -v223
	v_fmac_f32_e32 v223, 0x3377d1cf, v222
	v_fmac_f32_e32 v223, 0x3f317217, v222
	v_cmp_lt_f32_e64 s[0:1], |v222|, s72
	s_nop 1
	v_cndmask_b32_e64 v222, v222, v223, s[0:1]
	v_cndmask_b32_e32 v223, 0, v221, vcc
	v_sub_f32_e32 v222, v222, v223
	v_add_f32_e32 v212, v212, v222
	v_mul_f32_e32 v222, 0x3d800000, v212
	v_cvt_pk_bf16_f32 v212, v214, v215
	v_lshl_add_u64 v[214:215], s[58:59], 0, v[204:205]
	s_mov_b32 s0, 0x3000000
	v_add_co_u32_e32 v214, vcc, s0, v214
	s_add_i32 s0, s62, s25
	s_ashr_i32 s1, s0, 31
	s_mul_i32 s15, s0, 0x1c00
	v_addc_co_u32_e32 v215, vcc, 0, v215, vcc
	s_mul_hi_i32 s14, s0, 0x1c00
	s_add_u32 s26, s58, s15
	global_store_dwordx2 v[214:215], v[212:213], off nt
	v_cvt_pk_bf16_f32 v212, v199, v201
	v_cvt_pk_bf16_f32 v213, v203, v222
	s_addc_u32 s27, s59, s14
	global_store_dwordx2 v[214:215], v[212:213], off offset:512 nt
	v_lshl_add_u64 v[212:213], s[26:27], 0, v[138:139]
	v_add_co_u32_e32 v212, vcc, s73, v212
	s_lshl_b64 s[14:15], s[0:1], 10
	s_nop 0
	v_addc_co_u32_e32 v213, vcc, 0, v213, vcc
	global_load_dwordx4 v[222:225], v[212:213], off offset:1664 nt
	v_lshl_add_u64 v[212:213], v[168:169], 0, s[14:15]
	v_mov_b32_e32 v203, v139
	s_add_i32 s25, s25, 2
	v_lshl_add_u64 v[204:205], v[204:205], 0, s[48:49]
	s_cmp_lg_u32 s25, 16
	s_waitcnt vmcnt(0)
	global_store_dwordx4 v[212:213], v[222:225], off nt
	v_lshl_add_u64 v[212:213], s[26:27], 0, v[202:203]
	v_add_co_u32_e32 v212, vcc, s73, v212
	s_nop 1
	v_addc_co_u32_e32 v213, vcc, 0, v213, vcc
	global_load_ushort v199, v[212:213], off offset:2688
	s_waitcnt vmcnt(0)
	v_lshlrev_b32_e32 v199, 16, v199
	s_nop 0
	v_readlane_b32 s0, v199, 0
	v_readlane_b32 s26, v199, 16
	s_nop 0
	v_pk_fma_f32 v[212:213], v[8:9], s[0:1], v[0:1] op_sel_hi:[1,0,1]
	v_pk_fma_f32 v[214:215], v[10:11], s[0:1], v[2:3] op_sel_hi:[1,0,1]
	v_readlane_b32 s0, v199, 1
	v_pk_fma_f32 v[222:223], v[16:17], s[26:27], v[4:5] op_sel_hi:[1,0,1]
	v_pk_fma_f32 v[224:225], v[18:19], s[26:27], v[6:7] op_sel_hi:[1,0,1]
	v_pk_fma_f32 v[214:215], v[14:15], s[0:1], v[214:215] op_sel_hi:[1,0,1]
	v_pk_fma_f32 v[212:213], v[12:13], s[0:1], v[212:213] op_sel_hi:[1,0,1]
	v_readlane_b32 s0, v199, 2
	v_readlane_b32 s26, v199, 17
	s_nop 0
	v_pk_fma_f32 v[212:213], v[24:25], s[0:1], v[212:213] op_sel_hi:[1,0,1]
	v_pk_fma_f32 v[214:215], v[26:27], s[0:1], v[214:215] op_sel_hi:[1,0,1]
	v_readlane_b32 s0, v199, 3
	v_pk_fma_f32 v[224:225], v[22:23], s[26:27], v[224:225] op_sel_hi:[1,0,1]
	v_pk_fma_f32 v[222:223], v[20:21], s[26:27], v[222:223] op_sel_hi:[1,0,1]
	v_pk_fma_f32 v[214:215], v[30:31], s[0:1], v[214:215] op_sel_hi:[1,0,1]
	v_pk_fma_f32 v[212:213], v[28:29], s[0:1], v[212:213] op_sel_hi:[1,0,1]
	v_readlane_b32 s0, v199, 4
	v_readlane_b32 s26, v199, 18
	s_nop 0
	v_pk_fma_f32 v[212:213], v[40:41], s[0:1], v[212:213] op_sel_hi:[1,0,1]
	v_pk_fma_f32 v[214:215], v[42:43], s[0:1], v[214:215] op_sel_hi:[1,0,1]
	v_readlane_b32 s0, v199, 5
	v_pk_fma_f32 v[222:223], v[32:33], s[26:27], v[222:223] op_sel_hi:[1,0,1]
	v_pk_fma_f32 v[224:225], v[34:35], s[26:27], v[224:225] op_sel_hi:[1,0,1]
	v_pk_fma_f32 v[214:215], v[46:47], s[0:1], v[214:215] op_sel_hi:[1,0,1]
	v_pk_fma_f32 v[212:213], v[44:45], s[0:1], v[212:213] op_sel_hi:[1,0,1]
	v_readlane_b32 s0, v199, 6
	v_readlane_b32 s26, v199, 19
	s_nop 0
	v_pk_fma_f32 v[212:213], v[56:57], s[0:1], v[212:213] op_sel_hi:[1,0,1]
	v_pk_fma_f32 v[214:215], v[58:59], s[0:1], v[214:215] op_sel_hi:[1,0,1]
	v_readlane_b32 s0, v199, 7
	v_pk_fma_f32 v[224:225], v[38:39], s[26:27], v[224:225] op_sel_hi:[1,0,1]
	v_pk_fma_f32 v[222:223], v[36:37], s[26:27], v[222:223] op_sel_hi:[1,0,1]
	v_pk_fma_f32 v[214:215], v[62:63], s[0:1], v[214:215] op_sel_hi:[1,0,1]
	v_pk_fma_f32 v[212:213], v[60:61], s[0:1], v[212:213] op_sel_hi:[1,0,1]
	v_readlane_b32 s0, v199, 8
	v_readlane_b32 s26, v199, 20
	s_nop 0
	v_pk_fma_f32 v[212:213], v[72:73], s[0:1], v[212:213] op_sel_hi:[1,0,1]
	v_pk_fma_f32 v[214:215], v[74:75], s[0:1], v[214:215] op_sel_hi:[1,0,1]
	v_readlane_b32 s0, v199, 9
	v_pk_fma_f32 v[222:223], v[48:49], s[26:27], v[222:223] op_sel_hi:[1,0,1]
	v_pk_fma_f32 v[224:225], v[50:51], s[26:27], v[224:225] op_sel_hi:[1,0,1]
	v_pk_fma_f32 v[214:215], v[78:79], s[0:1], v[214:215] op_sel_hi:[1,0,1]
	v_pk_fma_f32 v[212:213], v[76:77], s[0:1], v[212:213] op_sel_hi:[1,0,1]
	v_readlane_b32 s0, v199, 10
	v_readlane_b32 s26, v199, 21
	s_nop 0
	v_pk_fma_f32 v[212:213], v[88:89], s[0:1], v[212:213] op_sel_hi:[1,0,1]
	v_pk_fma_f32 v[214:215], v[90:91], s[0:1], v[214:215] op_sel_hi:[1,0,1]
	v_readlane_b32 s0, v199, 11
	v_pk_fma_f32 v[224:225], v[54:55], s[26:27], v[224:225] op_sel_hi:[1,0,1]
	v_pk_fma_f32 v[222:223], v[52:53], s[26:27], v[222:223] op_sel_hi:[1,0,1]
	v_pk_fma_f32 v[214:215], v[94:95], s[0:1], v[214:215] op_sel_hi:[1,0,1]
	v_pk_fma_f32 v[212:213], v[92:93], s[0:1], v[212:213] op_sel_hi:[1,0,1]
; __device__ __forceinline__ void p2_gate(const Params& p, const LAS float* aup, int t0, int lane) {
;     ...
;         f32x4 acc0 = ab0, acc1 = ab1;
; #pragma unroll
;         for (int r = 0; r < 16; ++r) { const float a0 = __int_as_float(__builtin_amdgcn_readlane(alo, r)), a1 = __int_as_float(__builtin_amdgcn_readlane(alo, 16 + r));
;             acc0 += a0 * *(const LAS f32x4*)(aup + r * 256 + 4 * lane); acc1 += a1 * *(const LAS f32x4*)(aup + (16 + r) * 256 + 4 * lane); }
;         float n0[4], n1[4];
; #pragma unroll
;         for (int j = 0; j < 4; ++j) { const float y0 = -acc0[j], y1 = -acc1[j];
;             n0[j] = (fmaxf(y0, 0.f) + __logf(1.0f + __expf(-fabsf(y0)))) * 0.0625f; n1[j] = (fmaxf(y1, 0.f) + __logf(1.0f + __expf(-fabsf(y1)))) * 0.0625f; }
	v_readlane_b32 s0, v199, 12
	v_readlane_b32 s26, v199, 22
	s_nop 0
	v_pk_fma_f32 v[212:213], v[104:105], s[0:1], v[212:213] op_sel_hi:[1,0,1]
	v_pk_fma_f32 v[214:215], v[106:107], s[0:1], v[214:215] op_sel_hi:[1,0,1]
	v_readlane_b32 s0, v199, 13
	v_pk_fma_f32 v[222:223], v[64:65], s[26:27], v[222:223] op_sel_hi:[1,0,1]
	v_pk_fma_f32 v[224:225], v[66:67], s[26:27], v[224:225] op_sel_hi:[1,0,1]
	v_pk_fma_f32 v[214:215], v[110:111], s[0:1], v[214:215] op_sel_hi:[1,0,1]
	v_pk_fma_f32 v[212:213], v[108:109], s[0:1], v[212:213] op_sel_hi:[1,0,1]
	v_readlane_b32 s0, v199, 14
	v_readlane_b32 s26, v199, 23
	s_nop 0
	v_pk_fma_f32 v[212:213], v[120:121], s[0:1], v[212:213] op_sel_hi:[1,0,1]
	v_pk_fma_f32 v[214:215], v[122:123], s[0:1], v[214:215] op_sel_hi:[1,0,1]
	v_readlane_b32 s0, v199, 15
	v_pk_fma_f32 v[224:225], v[70:71], s[26:27], v[224:225] op_sel_hi:[1,0,1]
	v_pk_fma_f32 v[222:223], v[68:69], s[26:27], v[222:223] op_sel_hi:[1,0,1]
	v_pk_fma_f32 v[212:213], v[124:125], s[0:1], v[212:213] op_sel_hi:[1,0,1]
	v_readlane_b32 s26, v199, 24
	v_mul_f32_e64 v201, |v212|, s69
	v_exp_f32_e32 v201, v201
	v_pk_fma_f32 v[222:223], v[80:81], s[26:27], v[222:223] op_sel_hi:[1,0,1]
	v_pk_fma_f32 v[224:225], v[82:83], s[26:27], v[224:225] op_sel_hi:[1,0,1]
	v_readlane_b32 s26, v199, 25
	v_add_f32_e32 v201, 1.0, v201
	v_cmp_gt_f32_e32 vcc, s70, v201
	v_pk_fma_f32 v[224:225], v[86:87], s[26:27], v[224:225] op_sel_hi:[1,0,1]
	v_pk_fma_f32 v[222:223], v[84:85], s[26:27], v[222:223] op_sel_hi:[1,0,1]
	v_cndmask_b32_e64 v203, 0, 32, vcc
	v_ldexp_f32 v201, v201, v203
	v_log_f32_e32 v201, v201
	v_readlane_b32 s26, v199, 26
	v_pk_fma_f32 v[214:215], v[126:127], s[0:1], v[214:215] op_sel_hi:[1,0,1]
	v_mul_f32_e32 v203, 0x3f317217, v201
	v_pk_fma_f32 v[222:223], v[96:97], s[26:27], v[222:223] op_sel_hi:[1,0,1]
	v_pk_fma_f32 v[224:225], v[98:99], s[26:27], v[224:225] op_sel_hi:[1,0,1]
	v_readlane_b32 s26, v199, 27
	v_fma_f32 v203, v201, s71, -v203
	v_fmac_f32_e32 v203, 0x3377d1cf, v201
	v_pk_fma_f32 v[224:225], v[102:103], s[26:27], v[224:225] op_sel_hi:[1,0,1]
	v_pk_fma_f32 v[222:223], v[100:101], s[26:27], v[222:223] op_sel_hi:[1,0,1]
	v_readlane_b32 s26, v199, 28
	v_fmac_f32_e32 v203, 0x3f317217, v201
	v_cmp_lt_f32_e64 s[0:1], |v201|, s72
	v_pk_fma_f32 v[222:223], v[112:113], s[26:27], v[222:223] op_sel_hi:[1,0,1]
	v_pk_fma_f32 v[224:225], v[114:115], s[26:27], v[224:225] op_sel_hi:[1,0,1]
	v_readlane_b32 s26, v199, 29
	v_cndmask_b32_e64 v201, v201, v203, s[0:1]
	v_cndmask_b32_e32 v203, 0, v221, vcc
	v_pk_fma_f32 v[224:225], v[118:119], s[26:27], v[224:225] op_sel_hi:[1,0,1]
	v_pk_fma_f32 v[222:223], v[116:117], s[26:27], v[222:223] op_sel_hi:[1,0,1]
	v_readlane_b32 s26, v199, 30
	v_sub_f32_e32 v201, v201, v203
	s_nop 0
	v_pk_fma_f32 v[222:223], v[128:129], s[26:27], v[222:223] op_sel_hi:[1,0,1]
	v_pk_fma_f32 v[224:225], v[130:131], s[26:27], v[224:225] op_sel_hi:[1,0,1]
	v_readlane_b32 s26, v199, 31
	v_max_f32_e64 v199, -v212, 0
	v_add_f32_e32 v199, v199, v201
	v_pk_fma_f32 v[222:223], v[132:133], s[26:27], v[222:223] op_sel_hi:[1,0,1]
	v_pk_fma_f32 v[224:225], v[134:135], s[26:27], v[224:225] op_sel_hi:[1,0,1]
	v_mul_f32_e64 v203, |v222|, s69
	v_exp_f32_e32 v203, v203
	v_max_f32_e64 v201, -v222, 0
	v_mul_f32_e32 v199, 0x3d800000, v199
	v_add_f32_e32 v203, 1.0, v203
	v_cmp_gt_f32_e32 vcc, s70, v203
	s_nop 1
	v_cndmask_b32_e64 v212, 0, 32, vcc
	v_ldexp_f32 v203, v203, v212
	v_log_f32_e32 v203, v203
	s_nop 0
	v_mul_f32_e32 v212, 0x3f317217, v203
	v_fma_f32 v212, v203, s71, -v212
	v_fmac_f32_e32 v212, 0x3377d1cf, v203
	v_fmac_f32_e32 v212, 0x3f317217, v203
	v_cmp_lt_f32_e64 s[0:1], |v203|, s72
	s_nop 1
	v_cndmask_b32_e64 v203, v203, v212, s[0:1]
	v_cndmask_b32_e32 v212, 0, v221, vcc
	v_sub_f32_e32 v203, v203, v212
	v_mul_f32_e64 v212, |v213|, s69
	v_exp_f32_e32 v212, v212
	v_add_f32_e32 v201, v201, v203
	v_max_f32_e64 v203, -v213, 0
	v_mul_f32_e32 v201, 0x3d800000, v201
	v_add_f32_e32 v212, 1.0, v212
	v_cmp_gt_f32_e32 vcc, s70, v212
	s_nop 1
	v_cndmask_b32_e64 v213, 0, 32, vcc
	v_ldexp_f32 v212, v212, v213
	v_log_f32_e32 v212, v212
	s_nop 0
	v_mul_f32_e32 v213, 0x3f317217, v212
; __device__ __forceinline__ unsigned pk2(float lo, float hi) { unsigned r; asm("v_cvt_pk_bf16_f32 %0, %1, %2" : "=v"(r) : "v"(lo), "v"(hi)); return r; }
; __device__ __forceinline__ void p2_gate(const Params& p, const LAS float* aup, int t0, int lane) {
;     ...
;         float n0[4], n1[4];
; #pragma unroll
;         for (int j = 0; j < 4; ++j) { const float y0 = -acc0[j], y1 = -acc1[j];
;             n0[j] = (fmaxf(y0, 0.f) + __logf(1.0f + __expf(-fabsf(y0)))) * 0.0625f; n1[j] = (fmaxf(y1, 0.f) + __logf(1.0f + __expf(-fabsf(y1)))) * 0.0625f; }
;         u32x2 w; w.x = pk2(n0[0], n0[1]); w.y = pk2(n0[2], n0[3]); *(u32x2*)(GNL + (size_t)t * 512 + 4 * lane) = w;
;         w.x = pk2(n1[0], n1[1]); w.y = pk2(n1[2], n1[3]); *(u32x2*)(GNL + (size_t)t * 512 + 256 + 4 * lane) = w;
; __device__ __forceinline__ void phase2(const Params& p, LAS unsigned char* lds, int wid, int lane) {
;     ...
;     for (int grp = gw; grp < M_TOK / 16; grp += NGW) {
;         const int t0 = grp * 16;
;         p2_rwkv_chunk<0>(p, t0, lane); p2_rwkv_chunk<1>(p, t0, lane); p2_rwkv_chunk<2>(p, t0, lane); p2_rwkv_chunk<3>(p, t0, lane);
;         p2_gla_chunk<0>(p, t0, lane); p2_gla_chunk<1>(p, t0, lane);
;         p2_gate(p, aup, t0, lane);
	v_fma_f32 v213, v212, s71, -v213
	v_fmac_f32_e32 v213, 0x3377d1cf, v212
	v_fmac_f32_e32 v213, 0x3f317217, v212
	v_cmp_lt_f32_e64 s[0:1], |v212|, s72
	s_nop 1
	v_cndmask_b32_e64 v212, v212, v213, s[0:1]
	v_cndmask_b32_e32 v213, 0, v221, vcc
	v_sub_f32_e32 v212, v212, v213
	v_mul_f32_e64 v213, |v223|, s69
	v_exp_f32_e32 v213, v213
	v_add_f32_e32 v203, v203, v212
	v_max_f32_e64 v212, -v223, 0
	v_mul_f32_e32 v203, 0x3d800000, v203
	v_add_f32_e32 v213, 1.0, v213
	v_cmp_gt_f32_e32 vcc, s70, v213
	s_nop 1
	v_cndmask_b32_e64 v222, 0, 32, vcc
	v_ldexp_f32 v213, v213, v222
	v_log_f32_e32 v213, v213
	s_nop 0
	v_mul_f32_e32 v222, 0x3f317217, v213
	v_fma_f32 v222, v213, s71, -v222
	v_fmac_f32_e32 v222, 0x3377d1cf, v213
	v_fmac_f32_e32 v222, 0x3f317217, v213
	v_cmp_lt_f32_e64 s[0:1], |v213|, s72
	s_nop 1
	v_cndmask_b32_e64 v213, v213, v222, s[0:1]
	v_cndmask_b32_e32 v222, 0, v221, vcc
	v_sub_f32_e32 v213, v213, v222
	v_add_f32_e32 v212, v212, v213
	v_mul_f32_e64 v213, |v214|, s69
	v_exp_f32_e32 v213, v213
	v_mul_f32_e32 v222, 0x3d800000, v212
	v_max_f32_e64 v212, -v214, 0
	v_add_f32_e32 v213, 1.0, v213
	v_cmp_gt_f32_e32 vcc, s70, v213
	s_nop 1
	v_cndmask_b32_e64 v214, 0, 32, vcc
	v_ldexp_f32 v213, v213, v214
	v_log_f32_e32 v213, v213
	s_nop 0
	v_mul_f32_e32 v214, 0x3f317217, v213
	v_fma_f32 v214, v213, s71, -v214
	v_fmac_f32_e32 v214, 0x3377d1cf, v213
	v_fmac_f32_e32 v214, 0x3f317217, v213
	v_cmp_lt_f32_e64 s[0:1], |v213|, s72
	s_nop 1
	v_cndmask_b32_e64 v213, v213, v214, s[0:1]
	v_cndmask_b32_e32 v214, 0, v221, vcc
	v_sub_f32_e32 v213, v213, v214
	v_mul_f32_e64 v214, |v224|, s69
	v_exp_f32_e32 v214, v214
	v_add_f32_e32 v212, v212, v213
	v_mul_f32_e32 v213, 0x3d800000, v212
	v_max_f32_e64 v212, -v224, 0
	v_add_f32_e32 v214, 1.0, v214
	v_cmp_gt_f32_e32 vcc, s70, v214
	s_nop 1
	v_cndmask_b32_e64 v223, 0, 32, vcc
	v_ldexp_f32 v214, v214, v223
	v_log_f32_e32 v214, v214
	s_nop 0
	v_mul_f32_e32 v223, 0x3f317217, v214
	v_fma_f32 v223, v214, s71, -v223
	v_fmac_f32_e32 v223, 0x3377d1cf, v214
	v_fmac_f32_e32 v223, 0x3f317217, v214
	v_cmp_lt_f32_e64 s[0:1], |v214|, s72
	s_nop 1
	v_cndmask_b32_e64 v214, v214, v223, s[0:1]
	v_cndmask_b32_e32 v223, 0, v221, vcc
	v_sub_f32_e32 v214, v214, v223
	v_add_f32_e32 v212, v212, v214
	v_mul_f32_e64 v214, |v215|, s69
	v_exp_f32_e32 v214, v214
	v_mul_f32_e32 v223, 0x3d800000, v212
	v_max_f32_e64 v212, -v215, 0
	v_add_f32_e32 v214, 1.0, v214
	v_cmp_gt_f32_e32 vcc, s70, v214
	s_nop 1
	v_cndmask_b32_e64 v215, 0, 32, vcc
	v_ldexp_f32 v214, v214, v215
	v_log_f32_e32 v214, v214
	s_nop 0
	v_mul_f32_e32 v215, 0x3f317217, v214
	v_fma_f32 v215, v214, s71, -v215
	v_fmac_f32_e32 v215, 0x3377d1cf, v214
	v_fmac_f32_e32 v215, 0x3f317217, v214
	v_cmp_lt_f32_e64 s[0:1], |v214|, s72
	s_nop 1
	v_cndmask_b32_e64 v214, v214, v215, s[0:1]
	v_cndmask_b32_e32 v215, 0, v221, vcc
	v_sub_f32_e32 v214, v214, v215
	v_mul_f32_e64 v215, |v225|, s69
	v_exp_f32_e32 v215, v215
	v_add_f32_e32 v212, v212, v214
	v_mul_f32_e32 v214, 0x3d800000, v212
	v_max_f32_e64 v212, -v225, 0
	v_add_f32_e32 v215, 1.0, v215
	v_cmp_gt_f32_e32 vcc, s70, v215
	v_cvt_pk_bf16_f32 v213, v213, v214
	s_nop 1
	v_cndmask_b32_e64 v224, 0, 32, vcc
	v_ldexp_f32 v215, v215, v224
	v_log_f32_e32 v215, v215
	s_nop 0
	v_mul_f32_e32 v224, 0x3f317217, v215
	v_fma_f32 v224, v215, s71, -v224
	v_fmac_f32_e32 v224, 0x3377d1cf, v215
	v_fmac_f32_e32 v224, 0x3f317217, v215
	v_cmp_lt_f32_e64 s[0:1], |v215|, s72
	s_nop 1
	v_cndmask_b32_e64 v215, v215, v224, s[0:1]
	v_cndmask_b32_e32 v224, 0, v221, vcc
	v_sub_f32_e32 v215, v215, v224
	v_add_f32_e32 v212, v212, v215
	v_mul_f32_e32 v224, 0x3d800000, v212
	v_cvt_pk_bf16_f32 v212, v199, v203
	v_lshl_add_u64 v[214:215], v[176:177], 0, s[14:15]
	global_store_dwordx2 v[214:215], v[212:213], off nt
	v_cvt_pk_bf16_f32 v212, v201, v222
	v_cvt_pk_bf16_f32 v213, v223, v224
	global_store_dwordx2 v[214:215], v[212:213], off offset:512 nt
	s_cbranch_scc1 .LBB0_377
	s_add_i32 s3, s3, s92
	s_add_i32 s62, s62, s63
	s_add_i32 s36, s36, s63
	s_sub_i32 s64, s64, s63
	s_add_i32 s66, s66, s63
	s_add_i32 s67, s67, s63
	s_cmpk_lt_i32 s3, 0x800
	v_add_u32_e32 v137, s65, v137
	s_cbranch_scc1 .LBB0_236

; template <bool RWKV> __device__ __forceinline__ void scan_load_issue(ScanLd& L, const ScanSrc& S, int chunk, int lt) {
;     const int lw = lt >> 6, lane = lt & 63, sl = lane >> 2, col = 16 * lw + 4 * (lane & 3), s = chunk * SC_CH + sl; const size_t tok = (size_t)(S.tokbase + (S.rev ? T_SEQ - 1 - s : s));
;     L.rd = *(const u32x2*)(S.v[0] + tok * S.ld[0] + col); L.rk = *(const u32x2*)(S.v[1] + tok * S.ld[1] + col); L.rr = *(const u32x2*)(S.v[4] + tok * S.ld[4] + col); L.rv = *(const u32x2*)(S.v[5] + tok * S.ld[5] + col);
;     L.rkk = L.rk; L.rnb = L.rk;
;     if (RWKV) { L.rkk = *(const u32x2*)(S.v[2] + tok * S.ld[2] + col); L.rnb = *(const u32x2*)(S.v[3] + tok * S.ld[3] + col); }
; template <bool RWKV> __device__ __forceinline__ void scan_item(LAS unsigned char* lds, const ScanSrc& S, int wid, int lane) {
;     f32x16 T[2];
; #pragma unroll
;     for (int a = 0; a < 2; ++a)
; #pragma unroll
;         for (int i = 0; i < 16; ++i) T[a][i] = 0.f;
;     const bool is_ld = (wid == 4) | (wid == 5) | (wid == 3) | (wid == 7); const bool is_prep = wid == 2;
;     const int lt = (wid == 4 ? 0 : wid == 5 ? 64 : wid == 3 ? 128 : 192) + lane;
;     ScanLd L;
;     constexpr int NCH = T_SEQ / SC_CH;
;     ...
;     const bool is_inv = wid == 6;
;     if (is_ld) { scan_load_issue<RWKV>(L, S, 0, lt); scan_load_finish<RWKV>(lds, L, lt); scan_load_issue<RWKV>(L, S, 1, lt); scan_load_finish<RWKV>(lds + SC_BUF, L, lt);
;                  scan_load_issue<RWKV>(L, S, 2, lt); scan_load_finish<RWKV>(lds + 2 * SC_BUF, L, lt); scan_load_issue<RWKV>(L, S, 3, lt); }
.LBB0_553:
	s_lshl_b32 s0, s69, 25
	s_add_u32 s0, s56, s0
	s_addc_u32 s1, s57, 0
	s_lshl_b32 s67, s70, 1
	s_add_u32 s0, s0, s67
	s_addc_u32 s1, s1, 0
	s_add_u32 s67, s0, s71
	s_addc_u32 s70, s1, 0
	s_lshr_b32 s0, s68, 2
	v_or_b32_e32 v0, s0, v122
	s_lshl_b64 s[0:1], s[86:87], 1
	v_lshlrev_b32_e32 v74, 1, v16
	s_add_u32 s0, s67, s0
	s_waitcnt vmcnt(5)
	v_lshl_add_u64 v[76:77], s[40:41], 0, v[74:75]
	s_waitcnt vmcnt(4)
	v_lshl_add_u64 v[78:79], s[42:43], 0, v[74:75]
	s_waitcnt vmcnt(3)
	v_lshl_add_u64 v[80:81], s[94:95], 0, v[74:75]
	s_waitcnt vmcnt(2)
	v_lshl_add_u64 v[82:83], s[60:61], 0, v[74:75]
	s_addc_u32 s1, s70, s1
	v_lshlrev_b32_e32 v74, 1, v72
	v_lshlrev_b32_e32 v102, 1, v0
	v_mul_u32_u24_e32 v103, 0x50, v0
	v_mul_u32_u24_e32 v104, 48, v0
	v_mad_u32_u24 v105, v0, s88, s88
	v_mad_u32_u24 v106, v0, s88, v180
	v_mad_u32_u24 v107, v0, s88, v181
	v_lshlrev_b32_e32 v108, 2, v0
	v_lshl_add_u64 v[0:1], s[0:1], 0, v[74:75]
	s_mov_b64 s[0:1], 0x4000000
	s_cmp_eq_u32 s69, 0
	s_waitcnt lgkmcnt(0)
	s_barrier
	s_waitcnt vmcnt(1)
	v_lshl_add_u64 v[84:85], v[0:1], 0, s[0:1]
	s_cselect_b64 s[0:1], -1, 0
	v_add_u32_e32 v0, s68, v73
	s_waitcnt lgkmcnt(0)
	s_barrier
	s_and_b64 s[40:41], s[0:1], exec
	v_bfe_u32 v0, v0, 2, 4
	s_cselect_b32 s40, s89, 0xfffffe00
	v_or_b32_e32 v109, 64, v0
	v_sub_u32_e32 v110, 0, v0
	v_mov_b32_e32 v0, 0
	s_mov_b32 s67, 0
	s_waitcnt vmcnt(0)
	v_mul_hi_i32_i24_e32 v87, s40, v138
	v_mul_i32_i24_e32 v86, s40, v138
	v_mul_hi_i32_i24_e32 v89, s40, v139
	v_mul_i32_i24_e32 v88, s40, v139
	v_mul_hi_i32_i24_e32 v91, s40, v140
	v_mul_i32_i24_e32 v90, s40, v140
	v_mul_hi_i32_i24_e32 v93, s40, v141
	v_mul_i32_i24_e32 v92, s40, v141
	v_mul_hi_i32_i24_e32 v95, s40, v142
	v_mul_i32_i24_e32 v94, s40, v142
	v_mul_hi_i32_i24_e32 v97, s40, v143
	v_mul_i32_i24_e32 v96, s40, v143
	v_mul_hi_i32_i24_e32 v99, s40, v144
	v_mul_i32_i24_e32 v98, s40, v144
	v_mul_hi_i32_i24_e32 v101, s40, v145
	v_mul_i32_i24_e32 v100, s40, v145
	s_movk_i32 s68, 0xfbf
	s_mov_b32 s69, 0
	s_mov_b32 s72, 0
	s_mov_b32 s70, 0
	v_mov_b32_e32 v1, v0
	v_mov_b32_e32 v2, v0
	v_mov_b32_e32 v3, v0
	v_mov_b32_e32 v4, v0
	v_mov_b32_e32 v5, v0
	v_mov_b32_e32 v6, v0
	v_mov_b32_e32 v7, v0
	v_mov_b32_e32 v8, v0
	v_mov_b32_e32 v9, v0
	v_mov_b32_e32 v10, v0
	v_mov_b32_e32 v11, v0
	v_mov_b32_e32 v12, v0
	v_mov_b32_e32 v13, v0
	v_mov_b32_e32 v14, v0
	v_mov_b32_e32 v15, v0
	v_mov_b32_e32 v16, v0
	v_mov_b32_e32 v17, v0
	v_mov_b32_e32 v18, v0
	v_mov_b32_e32 v19, v0
	v_mov_b32_e32 v20, v0
	v_mov_b32_e32 v21, v0
	v_mov_b32_e32 v22, v0
	v_mov_b32_e32 v23, v0
	v_mov_b32_e32 v24, v0
	v_mov_b32_e32 v25, v0
	v_mov_b32_e32 v26, v0
	v_mov_b32_e32 v27, v0
	v_mov_b32_e32 v28, v0
	v_mov_b32_e32 v29, v0
	v_mov_b32_e32 v30, v0
	v_mov_b32_e32 v31, v0
	v_and_b32_e32 v251, 3, v73
	v_and_b32_e32 v252, 48, v73
	v_add_u32_e32 v251, v251, v252
	v_add_u32_e32 v251, -4, v251
	v_and_b32_e32 v253, 16, v73
	v_cmp_ne_u32_e32 vcc, 0, v253
	v_and_b32_e32 v252, 3, v73
	v_add_u32_e32 v252, 28, v252
	v_cndmask_b32_e32 v251, v73, v251, vcc
	v_cndmask_b32_e64 v253, 0, 1.0, vcc
	v_cmp_lt_u32_e32 vcc, 31, v73
	v_lshlrev_b32_e32 v251, 2, v251
	v_lshlrev_b32_e32 v252, 2, v252
	v_cndmask_b32_e64 v245, 0, 1.0, vcc
	v_add_u32_e32 v248, v123, v102
	v_add_u32_e32 v249, v103, v127
	v_add_u32_e32 v250, v104, v127
	v_add_u32_e32 v33, 0xfbf, v110
	v_cndmask_b32_e64 v32, v33, v109, s[0:1]
	v_add_u32_e32 v32, s66, v32
	v_mov_b32_e32 v33, 0
	v_lshlrev_b64 v[34:35], 10, v[32:33]
	v_lshlrev_b64 v[36:37], 11, v[32:33]
	v_lshl_add_u64 v[234:235], v[76:77], 0, v[34:35]
	v_lshl_add_u64 v[236:237], v[78:79], 0, v[36:37]
	v_lshl_add_u64 v[238:239], v[80:81], 0, v[36:37]
	v_lshl_add_u64 v[240:241], v[82:83], 0, v[36:37]
	s_and_b64 s[40:41], s[0:1], exec
	s_mov_b32 s98, 0x4000
	s_cselect_b32 s98, s98, 0xffffc000
	s_cselect_b32 s99, 0, -1
	s_mov_b32 s100, 0x8000
	s_cselect_b32 s100, s100, 0xffff8000
	s_cselect_b32 s101, 0, -1
	s_cmp_lt_i32 s3, 3
	s_cbranch_scc1 .Lgl_init_done
	s_cmp_eq_u32 s3, 6
	s_cbranch_scc1 .Lgl_init_done
	global_load_dwordx2 v[222:223], v[234:235], off
	global_load_dwordx2 v[224:225], v[236:237], off
	global_load_dwordx2 v[226:227], v[238:239], off
	global_load_dwordx2 v[228:229], v[240:241], off
.Lgl_init_done:
	v_lshl_add_u64 v[234:235], v[234:235], 0, s[98:99]
	v_lshl_add_u64 v[236:237], v[236:237], 0, s[100:101]
	v_lshl_add_u64 v[238:239], v[238:239], 0, s[100:101]
	v_lshl_add_u64 v[240:241], v[240:241], 0, s[100:101]
	s_branch .LBB0_556

; __device__ __forceinline__ unsigned cvt2(float a, float b) { f32x2 v = {a, b}; bf16x2_t r = __builtin_convertvector(v, bf16x2_t); return __builtin_bit_cast(unsigned, r); }
; #define MFMA32(a, b, c) __builtin_amdgcn_mfma_f32_32x32x16_bf16((a), (b), (c), 0, 0, 0)
; template <bool RWKV> __device__ __forceinline__ void scan_prep_m1(const LAS unsigned char* buf, LAS unsigned char* img, int lane) {
;     const int r = lane & 31, h = lane >> 5;
;     f32x16 gh;
; #pragma unroll
;     for (int i = 0; i < 16; ++i) gh[i] = 0.f;
; #pragma unroll
;     for (int kb = 0; kb < 4; ++kb) { const bf16x8 a = *(const LAS bf16x8*)(buf + SB_XB + r * 144 + (16 * kb + 8 * h) * 2), b = *(const LAS bf16x8*)(buf + SB_XA + r * 144 + (16 * kb + 8 * h) * 2); gh = MFMA32(a, b, gh); }
;     const int lim = r < 16 ? r : r - 15;
; #pragma unroll
;     for (int g = 0; g < 2; ++g) { const int t0 = 8 * g + 4 * h; float x[4], y[4];
; #pragma unroll
;         for (int q = 0; q < 4; ++q) { x[q] = (t0 + q < lim) ? gh[4 * g + q] : 0.f; y[q] = (t0 + q < lim) ? gh[8 + 4 * g + q] : 0.f; }
;         if (RWKV && r < 16) {
; #pragma unroll
;             for (int q = 0; q < 4; ++q) *(LAS float*)(img + SW_GR + ((t0 + q) * 16 + r) * 4) = x[q]; }
;         u32x2 wv; wv.x = r >= 16 ? cvt2(x[0], x[1]) : 0u; wv.y = r >= 16 ? cvt2(x[2], x[3]) : 0u; *(LAS u32x2*)(img + SW_GYT + r * 48 + t0 * 2) = wv;
;         wv.x = cvt2(y[0], y[1]); wv.y = cvt2(y[2], y[3]); *(LAS u32x2*)(img + SW_HT + r * 48 + t0 * 2) = wv; }
; }
; template <bool RWKV> __device__ __forceinline__ void scan_item(LAS unsigned char* lds, const ScanSrc& S, int wid, int lane) {
;     ...
;     for (int c = 0; c < NCH; ++c) {
;         const int i1 = i0 == 2 ? 0 : i0 + 1, i2 = i1 == 2 ? 0 : i1 + 1;
;         if (is_ld) {
;             if (c + 3 < NCH) scan_load_finish<RWKV>(lds + ((b0 + 3) & 3) * SC_BUF, L, lt);
;             if (c + 4 < NCH) scan_load_issue<RWKV>(L, S, c + 4, lt); }
;         else if (is_prep) { if (c + 2 < NCH) scan_prep_m1<RWKV>(lds + ((b0 + 2) & 3) * SC_BUF, lds + SC_IMG + i2 * SW_SIZE, lane); }
;         else if (is_inv) { if (c + 1 < NCH) scan_prep_inv<RWKV>(lds + SC_IMG + i1 * SW_SIZE, lane); }
;         else if (wid < 2) scan_chunk<RWKV>(lds + b0 * SC_BUF, lds + SC_IMG + i0 * SW_SIZE, T, S, c, wid, lane);
.LBB0_556:
	s_add_i32 s40, s72, 1
	s_cmp_lg_u32 s72, 2
	s_cselect_b32 s71, s40, 0
	s_cmp_lt_i32 s3, 2
	s_cbranch_scc1 .Lgl_compute
	s_cmp_eq_u32 s3, 2
	s_cbranch_scc1 .Lgl_prep
	s_cmp_eq_u32 s3, 6
	s_cbranch_scc1 .LBB0_555
	s_branch .LBB0_571
.Lgl_prep:
	s_cmpk_gt_u32 s69, 0xfd
	s_cbranch_scc1 .LBB0_555
	s_xor_b32 s40, s70, 2
	s_mulk_i32 s40, 0x4500
	v_add_u32_e32 v60, s40, v147
	ds_read_b128 v[32:35], v60 offset:4608
	ds_read_b128 v[36:39], v60
	ds_read_b128 v[48:51], v60 offset:4640
	ds_read_b128 v[52:55], v60 offset:32
	s_mul_i32 s40, s71, 0x1600
	s_addk_i32 s40, 0x1600
	s_cmp_lg_u32 s71, 2
	s_waitcnt lgkmcnt(2)
	v_mfma_f32_32x32x16_bf16 v[32:47], v[32:35], v[36:39], 0
	s_cselect_b32 s40, s40, 0
	s_waitcnt lgkmcnt(0)
	v_mfma_f32_32x32x16_bf16 v[32:47], v[48:51], v[52:55], v[32:47]
	ds_read_b128 v[48:51], v60 offset:4672
	ds_read_b128 v[52:55], v60 offset:64
	ds_read_b128 v[56:59], v60 offset:4704
	s_waitcnt lgkmcnt(1)
	v_mfma_f32_32x32x16_bf16 v[32:47], v[48:51], v[52:55], v[32:47]
	ds_read_b128 v[48:51], v60 offset:96
	v_add_u32_e32 v52, s40, v177
	v_add_u32_e32 v53, v52, v136
	s_waitcnt lgkmcnt(0)
	v_mfma_f32_32x32x16_bf16 v[32:47], v[56:59], v[48:51], v[32:47]
	s_nop 11
	v_cndmask_b32_e64 v32, 0, v32, s[20:21]
	v_cndmask_b32_e64 v33, 0, v33, s[22:23]
	v_cndmask_b32_e64 v34, 0, v34, s[24:25]
	v_cndmask_b32_e64 v35, 0, v35, s[26:27]
	v_cndmask_b32_e64 v40, 0, v40, s[20:21]
	v_cndmask_b32_e64 v41, 0, v41, s[22:23]
	v_cndmask_b32_e64 v42, 0, v42, s[24:25]
	v_cndmask_b32_e64 v43, 0, v43, s[26:27]
	v_cndmask_b32_e64 v36, 0, v36, s[28:29]
	v_cndmask_b32_e64 v37, 0, v37, s[30:31]
	v_cndmask_b32_e64 v38, 0, v38, s[34:35]
	v_cndmask_b32_e64 v39, 0, v39, s[36:37]
	v_cvt_pk_bf16_f32 v48, v32, v33
	v_cvt_pk_bf16_f32 v35, v34, v35
	v_cndmask_b32_e64 v44, 0, v44, s[28:29]
	v_cndmask_b32_e64 v45, 0, v45, s[30:31]
	v_cndmask_b32_e64 v46, 0, v46, s[34:35]
	v_cndmask_b32_e64 v47, 0, v47, s[36:37]
	v_cvt_pk_bf16_f32 v32, v40, v41
	v_cvt_pk_bf16_f32 v33, v42, v43
	v_cvt_pk_bf16_f32 v36, v36, v37
	v_cvt_pk_bf16_f32 v37, v38, v39
	v_cndmask_b32_e64 v34, 0, v48, s[18:19]
	v_cndmask_b32_e64 v35, 0, v35, s[18:19]
	v_cndmask_b32_e64 v36, 0, v36, s[18:19]
	v_cndmask_b32_e64 v37, 0, v37, s[18:19]
	ds_write2st64_b64 v53, v[32:33], v[34:35] offset0:2 offset1:5
	v_add_u32_e32 v34, v52, v146
	v_cvt_pk_bf16_f32 v32, v44, v45
	v_cvt_pk_bf16_f32 v33, v46, v47
	ds_write2st64_b64 v34, v[32:33], v[36:37] offset0:2 offset1:5
	s_branch .LBB0_555
.LBB0_571:
	s_cmpk_gt_u32 s69, 0xfc
	s_cbranch_scc1 .LBB0_555
	s_add_i32 s40, s70, -1
	s_and_b32 s40, s40, 3
	s_mulk_i32 s40, 0x4500
	v_add_u32_e32 v190, s40, v250
	s_bitcmp1_b32 s69, 0
	s_cbranch_scc1 .Lgl_ld_odd
	s_cmpk_gt_u32 s69, 0xfa
	s_cbranch_scc1 .Lgl_ld_e_tail
	s_waitcnt vmcnt(4)
	v_lshlrev_b32_e32 v32, 16, v64
	v_and_b32_e32 v33, 0xffff0000, v64
	v_lshlrev_b32_e32 v34, 16, v65
	v_and_b32_e32 v35, 0xffff0000, v65
	v_mul_f32_e32 v52, 0x3fb8aa3b, v32
	v_mul_f32_e32 v53, 0x3fb8aa3b, v33
	v_mul_f32_e32 v54, 0x3fb8aa3b, v34
	v_mul_f32_e32 v55, 0x3fb8aa3b, v35
	v_add_f32_dpp v52, v52, v52 row_shr:4 row_mask:0xf bank_mask:0xf
	v_add_f32_dpp v53, v53, v53 row_shr:4 row_mask:0xf bank_mask:0xf
	v_add_f32_dpp v54, v54, v54 row_shr:4 row_mask:0xf bank_mask:0xf
	v_add_f32_dpp v55, v55, v55 row_shr:4 row_mask:0xf bank_mask:0xf
	v_add_f32_dpp v52, v52, v52 row_shr:8 row_mask:0xf bank_mask:0xf
	v_add_f32_dpp v53, v53, v53 row_shr:8 row_mask:0xf bank_mask:0xf
	v_add_f32_dpp v54, v54, v54 row_shr:8 row_mask:0xf bank_mask:0xf
	v_add_f32_dpp v55, v55, v55 row_shr:8 row_mask:0xf bank_mask:0xf
	ds_bpermute_b32 v60, v251, v52
	ds_bpermute_b32 v61, v251, v53
	ds_bpermute_b32 v62, v251, v54
	ds_bpermute_b32 v63, v251, v55
	ds_write_b16 v190, v70 offset:14336
	ds_write_b16_d16_hi v190, v70 offset:14384
	ds_write_b16 v190, v71 offset:14432
	ds_write_b16_d16_hi v190, v71 offset:14480
	v_lshlrev_b32_e32 v36, 16, v66
	v_and_b32_e32 v37, 0xffff0000, v66
	v_lshlrev_b32_e32 v38, 16, v67
	v_and_b32_e32 v39, 0xffff0000, v67
	v_lshlrev_b32_e32 v40, 16, v68
	v_and_b32_e32 v41, 0xffff0000, v68
	v_lshlrev_b32_e32 v42, 16, v69
	v_and_b32_e32 v43, 0xffff0000, v69
	s_waitcnt lgkmcnt(4)
	v_fmac_f32_e32 v52, v60, v253
	v_fmac_f32_e32 v53, v61, v253
	v_fmac_f32_e32 v54, v62, v253
	v_fmac_f32_e32 v55, v63, v253
	ds_bpermute_b32 v60, v252, v52
	ds_bpermute_b32 v61, v252, v53
	ds_bpermute_b32 v62, v252, v54
	ds_bpermute_b32 v63, v252, v55
	global_load_dwordx2 v[64:65], v[234:235], off
	global_load_dwordx2 v[66:67], v[236:237], off
	global_load_dwordx2 v[68:69], v[238:239], off
	global_load_dwordx2 v[70:71], v[240:241], off
	v_lshl_add_u64 v[234:235], v[234:235], 0, s[98:99]
	v_lshl_add_u64 v[236:237], v[236:237], 0, s[100:101]
	v_lshl_add_u64 v[238:239], v[238:239], 0, s[100:101]
	v_lshl_add_u64 v[240:241], v[240:241], 0, s[100:101]
	s_waitcnt lgkmcnt(0)
	v_fmac_f32_e32 v52, v60, v245
	v_fmac_f32_e32 v53, v61, v245
	v_fmac_f32_e32 v54, v62, v245
	v_fmac_f32_e32 v55, v63, v245
	s_branch .Lgl_ldfin
; template <bool RWKV> __device__ __forceinline__ void scan_load_issue(ScanLd& L, const ScanSrc& S, int chunk, int lt) {
;     const int lw = lt >> 6, lane = lt & 63, sl = lane >> 2, col = 16 * lw + 4 * (lane & 3), s = chunk * SC_CH + sl; const size_t tok = (size_t)(S.tokbase + (S.rev ? T_SEQ - 1 - s : s));
;     L.rd = *(const u32x2*)(S.v[0] + tok * S.ld[0] + col); L.rk = *(const u32x2*)(S.v[1] + tok * S.ld[1] + col); L.rr = *(const u32x2*)(S.v[4] + tok * S.ld[4] + col); L.rv = *(const u32x2*)(S.v[5] + tok * S.ld[5] + col);
;     L.rkk = L.rk; L.rnb = L.rk;
;     if (RWKV) { L.rkk = *(const u32x2*)(S.v[2] + tok * S.ld[2] + col); L.rnb = *(const u32x2*)(S.v[3] + tok * S.ld[3] + col); }
; }
; template <bool RWKV> __device__ __forceinline__ void scan_load_finish(LAS unsigned char* buf, const ScanLd& L, int lt) {
;     const int lw = lt >> 6, lane = lt & 63, sl = lane >> 2, col = 16 * lw + 4 * (lane & 3);
;     float d[4], c[4], k[4], r[4], v[4], kk[4], nb[4];
;     unpack4(L.rd, d); unpack4(L.rk, k); unpack4(L.rr, r); unpack4(L.rv, v); unpack4(L.rkk, kk); unpack4(L.rnb, nb);
; #pragma unroll
;     for (int i = 0; i < 4; ++i) c[i] = d[i];
; #pragma unroll
;     for (int dl = 4; dl < 64; dl <<= 1)
; #pragma unroll
;         for (int i = 0; i < 4; ++i) { const float t = __shfl_up(c[i], dl); c[i] += (lane >= dl) ? t : 0.f; }
;     float o1[4], o2[4], o3[4], o4[4]; f32x4 we;
; #pragma unroll
;     for (int i = 0; i < 4; ++i) { const float W = __expf(-c[i]), iW = __expf(c[i]), Wp = __expf(d[i] - c[i]); o1[i] = RWKV ? kk[i] * Wp : 0.f; o2[i] = RWKV ? nb[i] * iW : 0.f; o3[i] = k[i] * iW; o4[i] = r[i] * W; we[i] = W; }
;     u32x2 w;
;     w.x = cvt2(o1[0], o1[1]); w.y = cvt2(o1[2], o1[3]); *(LAS u32x2*)(buf + SB_XA + sl * 144 + col * 2) = w;
;     w.x = cvt2(o4[0], o4[1]); w.y = cvt2(o4[2], o4[3]); *(LAS u32x2*)(buf + SB_XA + (16 + sl) * 144 + col * 2) = w;
;     w.x = cvt2(o2[0], o2[1]); w.y = cvt2(o2[2], o2[3]); *(LAS u32x2*)(buf + SB_XB + sl * 144 + col * 2) = w;
;     w.x = cvt2(o3[0], o3[1]); w.y = cvt2(o3[2], o3[3]); *(LAS u32x2*)(buf + SB_XB + (16 + sl) * 144 + col * 2) = w;
; #pragma unroll
;     for (int i = 0; i < 4; ++i) {
;         *(LAS unsigned short*)(buf + SB_XBT + (col + i) * 80 + sl * 2) = (unsigned short)(cvt2(o2[i], 0.f) & 0xffffu);
.Lgl_ld_e_tail:
	s_waitcnt vmcnt(0)
	v_lshlrev_b32_e32 v32, 16, v64
	v_and_b32_e32 v33, 0xffff0000, v64
	v_lshlrev_b32_e32 v34, 16, v65
	v_and_b32_e32 v35, 0xffff0000, v65
	v_mul_f32_e32 v52, 0x3fb8aa3b, v32
	v_mul_f32_e32 v53, 0x3fb8aa3b, v33
	v_mul_f32_e32 v54, 0x3fb8aa3b, v34
	v_mul_f32_e32 v55, 0x3fb8aa3b, v35
	v_add_f32_dpp v52, v52, v52 row_shr:4 row_mask:0xf bank_mask:0xf
	v_add_f32_dpp v53, v53, v53 row_shr:4 row_mask:0xf bank_mask:0xf
	v_add_f32_dpp v54, v54, v54 row_shr:4 row_mask:0xf bank_mask:0xf
	v_add_f32_dpp v55, v55, v55 row_shr:4 row_mask:0xf bank_mask:0xf
	v_add_f32_dpp v52, v52, v52 row_shr:8 row_mask:0xf bank_mask:0xf
	v_add_f32_dpp v53, v53, v53 row_shr:8 row_mask:0xf bank_mask:0xf
	v_add_f32_dpp v54, v54, v54 row_shr:8 row_mask:0xf bank_mask:0xf
	v_add_f32_dpp v55, v55, v55 row_shr:8 row_mask:0xf bank_mask:0xf
	ds_bpermute_b32 v60, v251, v52
	ds_bpermute_b32 v61, v251, v53
	ds_bpermute_b32 v62, v251, v54
	ds_bpermute_b32 v63, v251, v55
	ds_write_b16 v190, v70 offset:14336
	ds_write_b16_d16_hi v190, v70 offset:14384
	ds_write_b16 v190, v71 offset:14432
	ds_write_b16_d16_hi v190, v71 offset:14480
	v_lshlrev_b32_e32 v36, 16, v66
	v_and_b32_e32 v37, 0xffff0000, v66
	v_lshlrev_b32_e32 v38, 16, v67
	v_and_b32_e32 v39, 0xffff0000, v67
	v_lshlrev_b32_e32 v40, 16, v68
	v_and_b32_e32 v41, 0xffff0000, v68
	v_lshlrev_b32_e32 v42, 16, v69
	v_and_b32_e32 v43, 0xffff0000, v69
	s_waitcnt lgkmcnt(4)
	v_fmac_f32_e32 v52, v60, v253
	v_fmac_f32_e32 v53, v61, v253
	v_fmac_f32_e32 v54, v62, v253
	v_fmac_f32_e32 v55, v63, v253
	ds_bpermute_b32 v60, v252, v52
	ds_bpermute_b32 v61, v252, v53
	ds_bpermute_b32 v62, v252, v54
	ds_bpermute_b32 v63, v252, v55
	s_waitcnt lgkmcnt(0)
	v_fmac_f32_e32 v52, v60, v245
	v_fmac_f32_e32 v53, v61, v245
	v_fmac_f32_e32 v54, v62, v245
	v_fmac_f32_e32 v55, v63, v245
	s_branch .Lgl_ldfin
.Lgl_ld_odd:
	s_cmpk_gt_u32 s69, 0xfa
	s_cbranch_scc1 .Lgl_ld_o_tail
	s_waitcnt vmcnt(4)
	v_lshlrev_b32_e32 v32, 16, v222
	v_and_b32_e32 v33, 0xffff0000, v222
	v_lshlrev_b32_e32 v34, 16, v223
	v_and_b32_e32 v35, 0xffff0000, v223
	v_mul_f32_e32 v52, 0x3fb8aa3b, v32
	v_mul_f32_e32 v53, 0x3fb8aa3b, v33
	v_mul_f32_e32 v54, 0x3fb8aa3b, v34
	v_mul_f32_e32 v55, 0x3fb8aa3b, v35
	v_add_f32_dpp v52, v52, v52 row_shr:4 row_mask:0xf bank_mask:0xf
	v_add_f32_dpp v53, v53, v53 row_shr:4 row_mask:0xf bank_mask:0xf
	v_add_f32_dpp v54, v54, v54 row_shr:4 row_mask:0xf bank_mask:0xf
	v_add_f32_dpp v55, v55, v55 row_shr:4 row_mask:0xf bank_mask:0xf
	v_add_f32_dpp v52, v52, v52 row_shr:8 row_mask:0xf bank_mask:0xf
	v_add_f32_dpp v53, v53, v53 row_shr:8 row_mask:0xf bank_mask:0xf
	v_add_f32_dpp v54, v54, v54 row_shr:8 row_mask:0xf bank_mask:0xf
	v_add_f32_dpp v55, v55, v55 row_shr:8 row_mask:0xf bank_mask:0xf
	ds_bpermute_b32 v60, v251, v52
	ds_bpermute_b32 v61, v251, v53
	ds_bpermute_b32 v62, v251, v54
	ds_bpermute_b32 v63, v251, v55
	ds_write_b16 v190, v228 offset:14336
	ds_write_b16_d16_hi v190, v228 offset:14384
	ds_write_b16 v190, v229 offset:14432
	ds_write_b16_d16_hi v190, v229 offset:14480
	v_lshlrev_b32_e32 v36, 16, v224
	v_and_b32_e32 v37, 0xffff0000, v224
	v_lshlrev_b32_e32 v38, 16, v225
	v_and_b32_e32 v39, 0xffff0000, v225
	v_lshlrev_b32_e32 v40, 16, v226
	v_and_b32_e32 v41, 0xffff0000, v226
	v_lshlrev_b32_e32 v42, 16, v227
	v_and_b32_e32 v43, 0xffff0000, v227
	s_waitcnt lgkmcnt(4)
	v_fmac_f32_e32 v52, v60, v253
	v_fmac_f32_e32 v53, v61, v253
	v_fmac_f32_e32 v54, v62, v253
	v_fmac_f32_e32 v55, v63, v253
	ds_bpermute_b32 v60, v252, v52
	ds_bpermute_b32 v61, v252, v53
	ds_bpermute_b32 v62, v252, v54
	ds_bpermute_b32 v63, v252, v55
	global_load_dwordx2 v[222:223], v[234:235], off
	global_load_dwordx2 v[224:225], v[236:237], off
	global_load_dwordx2 v[226:227], v[238:239], off
	global_load_dwordx2 v[228:229], v[240:241], off
	v_lshl_add_u64 v[234:235], v[234:235], 0, s[98:99]
	v_lshl_add_u64 v[236:237], v[236:237], 0, s[100:101]
	v_lshl_add_u64 v[238:239], v[238:239], 0, s[100:101]
	v_lshl_add_u64 v[240:241], v[240:241], 0, s[100:101]
	s_waitcnt lgkmcnt(0)
	v_fmac_f32_e32 v52, v60, v245
	v_fmac_f32_e32 v53, v61, v245
	v_fmac_f32_e32 v54, v62, v245
	v_fmac_f32_e32 v55, v63, v245
	s_branch .Lgl_ldfin
; __device__ __forceinline__ void unpack4(const u32x2 w, float (&f)[4]) { f[0] = bflo(w.x); f[1] = bfhi(w.x); f[2] = bflo(w.y); f[3] = bfhi(w.y); }
; __device__ __forceinline__ unsigned cvt2(float a, float b) { f32x2 v = {a, b}; bf16x2_t r = __builtin_convertvector(v, bf16x2_t); return __builtin_bit_cast(unsigned, r); }
; template <bool RWKV> __device__ __forceinline__ void scan_load_finish(LAS unsigned char* buf, const ScanLd& L, int lt) {
;     const int lw = lt >> 6, lane = lt & 63, sl = lane >> 2, col = 16 * lw + 4 * (lane & 3);
;     float d[4], c[4], k[4], r[4], v[4], kk[4], nb[4];
;     unpack4(L.rd, d); unpack4(L.rk, k); unpack4(L.rr, r); unpack4(L.rv, v); unpack4(L.rkk, kk); unpack4(L.rnb, nb);
; #pragma unroll
;     for (int i = 0; i < 4; ++i) c[i] = d[i];
; #pragma unroll
;     for (int dl = 4; dl < 64; dl <<= 1)
; #pragma unroll
;         for (int i = 0; i < 4; ++i) { const float t = __shfl_up(c[i], dl); c[i] += (lane >= dl) ? t : 0.f; }
;     float o1[4], o2[4], o3[4], o4[4]; f32x4 we;
; #pragma unroll
;     for (int i = 0; i < 4; ++i) { const float W = __expf(-c[i]), iW = __expf(c[i]), Wp = __expf(d[i] - c[i]); o1[i] = RWKV ? kk[i] * Wp : 0.f; o2[i] = RWKV ? nb[i] * iW : 0.f; o3[i] = k[i] * iW; o4[i] = r[i] * W; we[i] = W; }
;     u32x2 w;
;     w.x = cvt2(o1[0], o1[1]); w.y = cvt2(o1[2], o1[3]); *(LAS u32x2*)(buf + SB_XA + sl * 144 + col * 2) = w;
;     w.x = cvt2(o4[0], o4[1]); w.y = cvt2(o4[2], o4[3]); *(LAS u32x2*)(buf + SB_XA + (16 + sl) * 144 + col * 2) = w;
;     w.x = cvt2(o2[0], o2[1]); w.y = cvt2(o2[2], o2[3]); *(LAS u32x2*)(buf + SB_XB + sl * 144 + col * 2) = w;
;     w.x = cvt2(o3[0], o3[1]); w.y = cvt2(o3[2], o3[3]); *(LAS u32x2*)(buf + SB_XB + (16 + sl) * 144 + col * 2) = w;
; #pragma unroll
;     for (int i = 0; i < 4; ++i) {
;         *(LAS unsigned short*)(buf + SB_XBT + (col + i) * 80 + sl * 2) = (unsigned short)(cvt2(o2[i], 0.f) & 0xffffu);
;         *(LAS unsigned short*)(buf + SB_XBT + (col + i) * 80 + (16 + sl) * 2) = (unsigned short)(cvt2(o3[i], 0.f) & 0xffffu);
;         *(LAS unsigned short*)(buf + SB_VT + (col + i) * 48 + sl * 2) = (unsigned short)(cvt2(v[i], 0.f) & 0xffffu); }
;     if (sl == SC_CH - 1) *(LAS f32x4*)(buf + SB_WE + col * 4) = we;
; }
.Lgl_ld_o_tail:
	s_waitcnt vmcnt(0)
	v_lshlrev_b32_e32 v32, 16, v222
	v_and_b32_e32 v33, 0xffff0000, v222
	v_lshlrev_b32_e32 v34, 16, v223
	v_and_b32_e32 v35, 0xffff0000, v223
	v_mul_f32_e32 v52, 0x3fb8aa3b, v32
	v_mul_f32_e32 v53, 0x3fb8aa3b, v33
	v_mul_f32_e32 v54, 0x3fb8aa3b, v34
	v_mul_f32_e32 v55, 0x3fb8aa3b, v35
	v_add_f32_dpp v52, v52, v52 row_shr:4 row_mask:0xf bank_mask:0xf
	v_add_f32_dpp v53, v53, v53 row_shr:4 row_mask:0xf bank_mask:0xf
	v_add_f32_dpp v54, v54, v54 row_shr:4 row_mask:0xf bank_mask:0xf
	v_add_f32_dpp v55, v55, v55 row_shr:4 row_mask:0xf bank_mask:0xf
	v_add_f32_dpp v52, v52, v52 row_shr:8 row_mask:0xf bank_mask:0xf
	v_add_f32_dpp v53, v53, v53 row_shr:8 row_mask:0xf bank_mask:0xf
	v_add_f32_dpp v54, v54, v54 row_shr:8 row_mask:0xf bank_mask:0xf
	v_add_f32_dpp v55, v55, v55 row_shr:8 row_mask:0xf bank_mask:0xf
	ds_bpermute_b32 v60, v251, v52
	ds_bpermute_b32 v61, v251, v53
	ds_bpermute_b32 v62, v251, v54
	ds_bpermute_b32 v63, v251, v55
	ds_write_b16 v190, v228 offset:14336
	ds_write_b16_d16_hi v190, v228 offset:14384
	ds_write_b16 v190, v229 offset:14432
	ds_write_b16_d16_hi v190, v229 offset:14480
	v_lshlrev_b32_e32 v36, 16, v224
	v_and_b32_e32 v37, 0xffff0000, v224
	v_lshlrev_b32_e32 v38, 16, v225
	v_and_b32_e32 v39, 0xffff0000, v225
	v_lshlrev_b32_e32 v40, 16, v226
	v_and_b32_e32 v41, 0xffff0000, v226
	v_lshlrev_b32_e32 v42, 16, v227
	v_and_b32_e32 v43, 0xffff0000, v227
	s_waitcnt lgkmcnt(4)
	v_fmac_f32_e32 v52, v60, v253
	v_fmac_f32_e32 v53, v61, v253
	v_fmac_f32_e32 v54, v62, v253
	v_fmac_f32_e32 v55, v63, v253
	ds_bpermute_b32 v60, v252, v52
	ds_bpermute_b32 v61, v252, v53
	ds_bpermute_b32 v62, v252, v54
	ds_bpermute_b32 v63, v252, v55
	s_waitcnt lgkmcnt(0)
	v_fmac_f32_e32 v52, v60, v245
	v_fmac_f32_e32 v53, v61, v245
	v_fmac_f32_e32 v54, v62, v245
	v_fmac_f32_e32 v55, v63, v245
.Lgl_ldfin:
	v_exp_f32_e64 v194, -v52
	v_exp_f32_e64 v195, -v53
	v_exp_f32_e64 v196, -v54
	v_exp_f32_e64 v197, -v55
	v_exp_f32_e32 v198, v52
	v_exp_f32_e32 v199, v53
	v_exp_f32_e32 v200, v54
	v_exp_f32_e32 v201, v55
	v_add_u32_e32 v191, s40, v248
	v_mov_b32_e32 v192, 0
	v_mov_b32_e32 v193, 0
	v_pk_mul_f32 v[208:209], v[194:195], v[40:41]
	v_pk_mul_f32 v[210:211], v[196:197], v[42:43]
	v_pk_mul_f32 v[204:205], v[198:199], v[36:37]
	v_pk_mul_f32 v[206:207], v[200:201], v[38:39]
	v_cvt_pk_bf16_f32 v218, v208, v209
	v_cvt_pk_bf16_f32 v219, v210, v211
	v_cvt_pk_bf16_f32 v216, v204, v205
	v_cvt_pk_bf16_f32 v217, v206, v207
	v_add_u32_e32 v220, 0x900, v191
	v_add_u32_e32 v221, s40, v249
	ds_write2st64_b64 v191, v[192:193], v[192:193] offset1:9
	ds_write2st64_b64 v220, v[218:219], v[216:217] offset1:9
	ds_write_b16 v221, v192 offset:9216
	ds_write_b16 v221, v192 offset:9296
	ds_write_b16 v221, v192 offset:9376
	ds_write_b16 v221, v192 offset:9456
	ds_write_b16 v221, v216 offset:9248
	ds_write_b16_d16_hi v221, v216 offset:9328
	ds_write_b16 v221, v217 offset:9408
	ds_write_b16_d16_hi v221, v217 offset:9488
	s_and_saveexec_b64 s[42:43], s[14:15]
	v_add_u32_e32 v60, s40, v108
	ds_write_b128 v60, v[194:197] offset:17408
	s_or_b64 exec, exec, s[42:43]
	s_branch .LBB0_555

; #define SC_BAR() do { asm volatile("s_waitcnt lgkmcnt(0)" ::: "memory"); __builtin_amdgcn_s_barrier(); asm volatile("" ::: "memory"); } while (0)
; template <bool RWKV> __device__ __forceinline__ void scan_load_issue(ScanLd& L, const ScanSrc& S, int chunk, int lt) {
;     const int lw = lt >> 6, lane = lt & 63, sl = lane >> 2, col = 16 * lw + 4 * (lane & 3), s = chunk * SC_CH + sl; const size_t tok = (size_t)(S.tokbase + (S.rev ? T_SEQ - 1 - s : s));
;     L.rd = *(const u32x2*)(S.v[0] + tok * S.ld[0] + col); L.rk = *(const u32x2*)(S.v[1] + tok * S.ld[1] + col); L.rr = *(const u32x2*)(S.v[4] + tok * S.ld[4] + col); L.rv = *(const u32x2*)(S.v[5] + tok * S.ld[5] + col);
;     L.rkk = L.rk; L.rnb = L.rk;
;     if (RWKV) { L.rkk = *(const u32x2*)(S.v[2] + tok * S.ld[2] + col); L.rnb = *(const u32x2*)(S.v[3] + tok * S.ld[3] + col); }
; template <bool RWKV> __device__ __forceinline__ void scan_item(LAS unsigned char* lds, const ScanSrc& S, int wid, int lane) {
;     f32x16 T[2];
; #pragma unroll
;     for (int a = 0; a < 2; ++a)
; #pragma unroll
;         for (int i = 0; i < 16; ++i) T[a][i] = 0.f;
;     const bool is_ld = (wid == 4) | (wid == 5) | (wid == 3) | (wid == 7); const bool is_prep = wid == 2;
;     const int lt = (wid == 4 ? 0 : wid == 5 ? 64 : wid == 3 ? 128 : 192) + lane;
;     ScanLd L;
;     constexpr int NCH = T_SEQ / SC_CH;
;     ...
;     const bool is_inv = wid == 6;
;     if (is_ld) { scan_load_issue<RWKV>(L, S, 0, lt); scan_load_finish<RWKV>(lds, L, lt); scan_load_issue<RWKV>(L, S, 1, lt); scan_load_finish<RWKV>(lds + SC_BUF, L, lt);
;                  scan_load_issue<RWKV>(L, S, 2, lt); scan_load_finish<RWKV>(lds + 2 * SC_BUF, L, lt); scan_load_issue<RWKV>(L, S, 3, lt); }
;     __syncthreads();
;     if (is_prep) { scan_prep_m1<RWKV>(lds, lds + SC_IMG, lane); scan_prep_m1<RWKV>(lds + SC_BUF, lds + SC_IMG + SW_SIZE, lane); }
;     SC_BAR();
;     if (is_inv) scan_prep_inv<RWKV>(lds + SC_IMG, lane);
;     SC_BAR();
;     int b0 = 0, i0 = 0;
;     for (int c = 0; c < NCH; ++c) {
;         const int i1 = i0 == 2 ? 0 : i0 + 1, i2 = i1 == 2 ? 0 : i1 + 1;
;         if (is_ld) {
;             if (c + 3 < NCH) scan_load_finish<RWKV>(lds + ((b0 + 3) & 3) * SC_BUF, L, lt);
;             if (c + 4 < NCH) scan_load_issue<RWKV>(L, S, c + 4, lt); }
.LBB0_611:
	s_or_b64 exec, exec, s[72:73]
	s_lshl_b32 s72, s89, 25
	s_add_u32 s72, s56, s72
	s_addc_u32 s73, s57, 0
	s_add_u32 s72, s72, s93
	v_lshlrev_b32_e32 v74, 1, v20
	s_addc_u32 s73, s73, 0
	s_lshr_b32 s89, s81, 2
	v_lshl_add_u64 v[88:89], s[0:1], 0, v[74:75]
	s_lshl_b64 s[0:1], s[86:87], 1
	v_or_b32_e32 v0, s89, v122
	s_add_u32 s0, s72, s0
	v_lshlrev_b32_e32 v182, 1, v0
	v_mul_u32_u24_e32 v183, 0x50, v0
	v_mul_u32_u24_e32 v184, 48, v0
	v_mad_u32_u24 v185, v0, s88, s88
	v_mad_u32_u24 v186, v0, s88, v180
	v_mad_u32_u24 v187, v0, s88, v181
	v_lshlrev_b32_e32 v188, 2, v0
	v_lshl_add_u64 v[90:91], s[60:61], 0, v[74:75]
	v_lshl_add_u64 v[92:93], s[68:69], 0, v[74:75]
	v_lshl_add_u64 v[94:95], s[70:71], 0, v[74:75]
	v_lshl_add_u64 v[96:97], s[42:43], 0, v[74:75]
	v_lshl_add_u64 v[98:99], s[66:67], 0, v[74:75]
	s_addc_u32 s1, s73, s1
	v_lshlrev_b32_e32 v74, 1, v72
	s_ashr_i32 s66, s83, 31
	v_add_u32_e32 v0, s81, v73
	s_waitcnt lgkmcnt(0)
	s_barrier
	v_lshl_add_u64 v[100:101], s[0:1], 0, v[74:75]
	s_and_b64 s[0:1], s[40:41], exec
	s_movk_i32 s89, 0x200
	v_bfe_u32 v0, v0, 2, 4
	s_cselect_b32 s0, s89, 0xfffffe00
	v_or_b32_e32 v74, 64, v0
	v_sub_u32_e32 v189, 0, v0
	v_mov_b32_e32 v0, 0
	v_mul_hi_i32_i24_e32 v103, s0, v138
	v_mul_i32_i24_e32 v102, s0, v138
	v_mul_hi_i32_i24_e32 v105, s0, v139
	v_mul_i32_i24_e32 v104, s0, v139
	v_mul_hi_i32_i24_e32 v107, s0, v140
	v_mul_i32_i24_e32 v106, s0, v140
	v_mul_hi_i32_i24_e32 v109, s0, v141
	v_mul_i32_i24_e32 v108, s0, v141
	v_mul_hi_i32_i24_e32 v111, s0, v142
	v_mul_i32_i24_e32 v110, s0, v142
	v_mul_hi_i32_i24_e32 v113, s0, v143
	v_mul_i32_i24_e32 v112, s0, v143
	v_mul_hi_i32_i24_e32 v115, s0, v144
	v_mul_i32_i24_e32 v114, s0, v144
	v_mul_hi_i32_i24_e32 v117, s0, v145
	v_mul_i32_i24_e32 v116, s0, v145
	s_mov_b32 s67, 0
	s_movk_i32 s68, 0xfbf
	s_mov_b32 s69, 0
	s_mov_b32 s72, 0
	s_mov_b32 s70, 0
	v_mov_b32_e32 v1, v0
	v_mov_b32_e32 v2, v0
	v_mov_b32_e32 v3, v0
	v_mov_b32_e32 v4, v0
	v_mov_b32_e32 v5, v0
	v_mov_b32_e32 v6, v0
	v_mov_b32_e32 v7, v0
	v_mov_b32_e32 v8, v0
	v_mov_b32_e32 v9, v0
	v_mov_b32_e32 v10, v0
	v_mov_b32_e32 v11, v0
	v_mov_b32_e32 v12, v0
	v_mov_b32_e32 v13, v0
	v_mov_b32_e32 v14, v0
	v_mov_b32_e32 v15, v0
	v_mov_b32_e32 v16, v0
	v_mov_b32_e32 v17, v0
	v_mov_b32_e32 v18, v0
	v_mov_b32_e32 v19, v0
	v_mov_b32_e32 v20, v0
	v_mov_b32_e32 v21, v0
	v_mov_b32_e32 v22, v0
	v_mov_b32_e32 v23, v0
	v_mov_b32_e32 v24, v0
	v_mov_b32_e32 v25, v0
	v_mov_b32_e32 v26, v0
	v_mov_b32_e32 v27, v0
	v_mov_b32_e32 v28, v0
	v_mov_b32_e32 v29, v0
	v_mov_b32_e32 v30, v0
	v_mov_b32_e32 v31, v0
	v_and_b32_e32 v251, 3, v73
	v_and_b32_e32 v252, 48, v73
	v_add_u32_e32 v251, v251, v252
	v_add_u32_e32 v251, -4, v251
	v_and_b32_e32 v253, 16, v73
	v_cmp_ne_u32_e32 vcc, 0, v253
	v_and_b32_e32 v252, 3, v73
	v_add_u32_e32 v252, 28, v252
	v_cndmask_b32_e32 v251, v73, v251, vcc
	v_cndmask_b32_e64 v253, 0, 1.0, vcc
	v_cmp_lt_u32_e32 vcc, 31, v73
	v_lshlrev_b32_e32 v251, 2, v251
	v_lshlrev_b32_e32 v252, 2, v252
	v_cndmask_b32_e64 v245, 0, 1.0, vcc
	v_add_u32_e32 v248, v123, v182
	v_add_u32_e32 v249, v183, v127
	v_add_u32_e32 v250, v184, v127
	v_add_u32_e32 v33, 0xfbf, v189
	v_cndmask_b32_e64 v32, v33, v74, s[40:41]
	v_add_u32_e32 v32, s83, v32
	v_ashrrev_i32_e32 v33, 31, v32
	v_lshlrev_b64 v[34:35], 10, v[32:33]
	v_lshl_add_u64 v[234:235], v[88:89], 0, v[34:35]
	v_mad_i64_i32 v[236:237], s[0:1], v32, s79, v[90:91]
	v_mad_i64_i32 v[238:239], s[0:1], v32, s79, v[92:93]
	v_mad_i64_i32 v[240:241], s[0:1], v32, s79, v[94:95]
	v_lshl_add_u64 v[242:243], v[96:97], 0, v[34:35]
	v_lshl_add_u64 v[246:247], v[98:99], 0, v[34:35]
	s_and_b64 s[0:1], s[40:41], exec
	s_mov_b32 s98, 0x4000
	s_cselect_b32 s98, s98, 0xffffc000
	s_cselect_b32 s99, 0, -1
	s_mov_b32 s100, 0xc000
	s_cselect_b32 s100, s100, 0xffff4000
	s_cselect_b32 s101, 0, -1
	s_cmp_lt_i32 s3, 3
	s_cbranch_scc1 .Lrw_init_done
	s_cmp_eq_u32 s3, 6
	s_cbranch_scc1 .Lrw_init_done
	global_load_dwordx2 v[222:223], v[234:235], off
	global_load_dwordx2 v[224:225], v[236:237], off
	global_load_dwordx2 v[226:227], v[238:239], off
	global_load_dwordx2 v[228:229], v[240:241], off
	global_load_dwordx2 v[230:231], v[242:243], off
	global_load_dwordx2 v[232:233], v[246:247], off
.Lrw_init_done:
	v_lshl_add_u64 v[234:235], v[234:235], 0, s[98:99]
	v_lshl_add_u64 v[236:237], v[236:237], 0, s[100:101]
	v_lshl_add_u64 v[238:239], v[238:239], 0, s[100:101]
	v_lshl_add_u64 v[240:241], v[240:241], 0, s[100:101]
	v_lshl_add_u64 v[242:243], v[242:243], 0, s[98:99]
	v_lshl_add_u64 v[246:247], v[246:247], 0, s[98:99]
	s_branch .LBB0_614

; #define MFMA32(a, b, c) __builtin_amdgcn_mfma_f32_32x32x16_bf16((a), (b), (c), 0, 0, 0)
; template <bool RWKV> __device__ __forceinline__ void scan_prep_m1(const LAS unsigned char* buf, LAS unsigned char* img, int lane) {
;     const int r = lane & 31, h = lane >> 5;
;     f32x16 gh;
; #pragma unroll
;     for (int i = 0; i < 16; ++i) gh[i] = 0.f;
; #pragma unroll
;     for (int kb = 0; kb < 4; ++kb) { const bf16x8 a = *(const LAS bf16x8*)(buf + SB_XB + r * 144 + (16 * kb + 8 * h) * 2), b = *(const LAS bf16x8*)(buf + SB_XA + r * 144 + (16 * kb + 8 * h) * 2); gh = MFMA32(a, b, gh); }
;     const int lim = r < 16 ? r : r - 15;
; #pragma unroll
;     for (int g = 0; g < 2; ++g) { const int t0 = 8 * g + 4 * h; float x[4], y[4];
; #pragma unroll
;         for (int q = 0; q < 4; ++q) { x[q] = (t0 + q < lim) ? gh[4 * g + q] : 0.f; y[q] = (t0 + q < lim) ? gh[8 + 4 * g + q] : 0.f; }
; template <bool RWKV> __device__ __forceinline__ void scan_item(LAS unsigned char* lds, const ScanSrc& S, int wid, int lane) {
;     ...
;     for (int c = 0; c < NCH; ++c) {
;         const int i1 = i0 == 2 ? 0 : i0 + 1, i2 = i1 == 2 ? 0 : i1 + 1;
;         if (is_ld) {
;             if (c + 3 < NCH) scan_load_finish<RWKV>(lds + ((b0 + 3) & 3) * SC_BUF, L, lt);
;             if (c + 4 < NCH) scan_load_issue<RWKV>(L, S, c + 4, lt); }
;         else if (is_prep) { if (c + 2 < NCH) scan_prep_m1<RWKV>(lds + ((b0 + 2) & 3) * SC_BUF, lds + SC_IMG + i2 * SW_SIZE, lane); }
;         else if (is_inv) { if (c + 1 < NCH) scan_prep_inv<RWKV>(lds + SC_IMG + i1 * SW_SIZE, lane); }
;         else if (wid < 2) scan_chunk<RWKV>(lds + b0 * SC_BUF, lds + SC_IMG + i0 * SW_SIZE, T, S, c, wid, lane);
.LBB0_614:
	s_add_i32 s0, s72, 1
	s_cmp_lg_u32 s72, 2
	s_cselect_b32 s71, s0, 0
	s_cmp_lt_i32 s3, 2
	s_cbranch_scc1 .Lrw_compute
	s_cmp_eq_u32 s3, 2
	s_cbranch_scc1 .Lrw_prep
	s_cmp_eq_u32 s3, 6
	s_cbranch_scc1 .Lrw_inv
	s_branch .LBB0_640
.Lrw_prep:
	s_cmpk_gt_u32 s69, 0xfd
	s_cbranch_scc1 .LBB0_613
	s_xor_b32 s0, s70, 2
	s_mulk_i32 s0, 0x4500
	v_add_u32_e32 v56, s0, v147
	ds_read_b128 v[32:35], v56 offset:4608
	ds_read_b128 v[36:39], v56
	ds_read_b128 v[48:51], v56 offset:4640
	ds_read_b128 v[52:55], v56 offset:32
	s_mul_i32 s0, s71, 0x1600
	s_addk_i32 s0, 0x1600
	s_cmp_lg_u32 s71, 2
	s_waitcnt lgkmcnt(2)
	v_mfma_f32_32x32x16_bf16 v[32:47], v[32:35], v[36:39], 0
	s_cselect_b32 s0, s0, 0
	s_add_i32 s42, s0, 0
	s_add_i32 s42, s42, 0x11400
	s_waitcnt lgkmcnt(0)
	v_mfma_f32_32x32x16_bf16 v[32:47], v[48:51], v[52:55], v[32:47]
	ds_read_b128 v[48:51], v56 offset:4672
	ds_read_b128 v[52:55], v56 offset:64
	s_waitcnt lgkmcnt(0)
	v_mfma_f32_32x32x16_bf16 v[32:47], v[48:51], v[52:55], v[32:47]
	ds_read_b128 v[48:51], v56 offset:4704
	ds_read_b128 v[52:55], v56 offset:96
	s_waitcnt lgkmcnt(0)
	v_mfma_f32_32x32x16_bf16 v[32:47], v[48:51], v[52:55], v[32:47]
	v_add_u32_e32 v48, s42, v155
	s_nop 10
	v_cndmask_b32_e64 v49, 0, v32, s[20:21]
	v_cndmask_b32_e64 v50, 0, v33, s[22:23]
	v_cndmask_b32_e64 v34, 0, v34, s[24:25]
	v_cndmask_b32_e64 v35, 0, v35, s[26:27]
	v_add_u32_e32 v33, v48, v157
	s_and_saveexec_b64 s[0:1], s[16:17]
	s_cbranch_execz .LBB0_636
	ds_write2_b32 v33, v49, v50 offset1:16
	ds_write2_b32 v33, v34, v35 offset0:32 offset1:48

; __device__ __forceinline__ unsigned cvt2(float a, float b) { f32x2 v = {a, b}; bf16x2_t r = __builtin_convertvector(v, bf16x2_t); return __builtin_bit_cast(unsigned, r); }
; template <bool RWKV> __device__ __forceinline__ void scan_prep_m1(const LAS unsigned char* buf, LAS unsigned char* img, int lane) {
;     ...
;         if (RWKV && r < 16) {
; #pragma unroll
;             for (int q = 0; q < 4; ++q) *(LAS float*)(img + SW_GR + ((t0 + q) * 16 + r) * 4) = x[q]; }
;         u32x2 wv; wv.x = r >= 16 ? cvt2(x[0], x[1]) : 0u; wv.y = r >= 16 ? cvt2(x[2], x[3]) : 0u; *(LAS u32x2*)(img + SW_GYT + r * 48 + t0 * 2) = wv;
;         wv.x = cvt2(y[0], y[1]); wv.y = cvt2(y[2], y[3]); *(LAS u32x2*)(img + SW_HT + r * 48 + t0 * 2) = wv; }
; }
; template <bool RWKV> __device__ __forceinline__ void scan_prep_inv(LAS unsigned char* img, int lane) {
;     const int r = lane & 31;
;     if (RWKV) {
;         const int sc = lane & 15; float X[16];
; #pragma unroll
;         for (int t = 15; t >= 0; --t) { float acc = (t == sc) ? 1.f : 0.f;
; #pragma unroll
;             for (int m4 = (t + 1) / 4; m4 < 4; ++m4) { const f32x4 gv = *(const LAS f32x4*)(img + SW_GR + (t * 16 + 4 * m4) * 4);
; #pragma unroll
;                 for (int q = 0; q < 4; ++q) if (4 * m4 + q > t) acc = fmaf(gv[q], X[4 * m4 + q], acc); }
;             X[t] = acc; }
;         if (lane < 32) { u32x4 p0, p1; const bool z = r >= 16;
;             p0.x = z ? 0u : cvt2(X[0], X[1]); p0.y = z ? 0u : cvt2(X[2], X[3]); p0.z = z ? 0u : cvt2(X[4], X[5]); p0.w = z ? 0u : cvt2(X[6], X[7]);
;             p1.x = z ? 0u : cvt2(X[8], X[9]); p1.y = z ? 0u : cvt2(X[10], X[11]); p1.z = z ? 0u : cvt2(X[12], X[13]); p1.w = z ? 0u : cvt2(X[14], X[15]);
;             *(LAS u32x4*)(img + SW_TIT + r * 48) = p0; *(LAS u32x4*)(img + SW_TIT + r * 48 + 16) = p1; }
;     }
; }
; template <bool RWKV> __device__ __forceinline__ void scan_item(LAS unsigned char* lds, const ScanSrc& S, int wid, int lane) {
;     ...
;         else if (is_inv) { if (c + 1 < NCH) scan_prep_inv<RWKV>(lds + SC_IMG + i1 * SW_SIZE, lane); }
.LBB0_638:
	s_or_b64 exec, exec, s[0:1]
	v_cndmask_b32_e64 v33, 0, v44, s[28:29]
	v_cndmask_b32_e64 v38, 0, v45, s[30:31]
	v_cndmask_b32_e64 v39, 0, v46, s[34:35]
	v_cndmask_b32_e64 v40, 0, v47, s[36:37]
	v_cvt_pk_bf16_f32 v34, v34, v36
	v_cvt_pk_bf16_f32 v35, v35, v37
	v_cndmask_b32_e64 v34, 0, v34, s[18:19]
	v_cndmask_b32_e64 v35, 0, v35, s[18:19]
	v_add_u32_e32 v36, v32, v146
	v_cvt_pk_bf16_f32 v32, v33, v38
	v_cvt_pk_bf16_f32 v33, v39, v40
	ds_write2st64_b64 v36, v[32:33], v[34:35] offset0:2 offset1:5
	s_branch .LBB0_613
.Lrw_inv:
	s_cmpk_eq_i32 s68, 0xffcf
	s_cbranch_scc1 .LBB0_613
	s_mul_i32 s42, s71, 0x1600
	s_add_i32 s42, s42, 0x11400
	v_and_b32_e32 v234, 3, v73
	v_lshrrev_b32_e32 v235, 2, v73
	v_lshl_add_u32 v228, v234, 6, s42
	ds_read_b128 v[68:71], v228 offset:816
	ds_read_b128 v[64:67], v228 offset:560
	ds_read_b128 v[56:59], v228 offset:304
	ds_read_b128 v[44:47], v228 offset:48
	ds_read_b128 v[60:63], v228 offset:544
	ds_read_b128 v[52:55], v228 offset:288
	ds_read_b128 v[40:43], v228 offset:32
	ds_read_b128 v[48:51], v228 offset:272
	ds_read_b128 v[36:39], v228 offset:16
	ds_read_b128 v[32:35], v228
	v_sub_u32_e32 v236, v235, v234
	v_cmp_eq_u32_e64 s[0:1], 0, v236
	v_cmp_eq_u32_e64 s[100:101], 4, v236
	v_cmp_eq_u32_e32 vcc, 8, v236
	v_mul_u32_u24_e32 v229, 48, v235
	v_cndmask_b32_e64 v222, 0, 1.0, s[0:1]
	v_cndmask_b32_e64 v223, 0, 1.0, s[100:101]
	v_cndmask_b32_e64 v224, 0, 1.0, vcc
	v_cmp_eq_u32_e32 vcc, 12, v236
	v_lshl_add_u32 v237, v234, 1, s42
	v_lshl_add_u32 v238, v234, 3, s42
	v_add_u32_e32 v230, v229, v238
	v_add_u32_e32 v229, v229, v237
	v_cndmask_b32_e64 v225, 0, 1.0, vcc
	v_mov_b32_e32 v232, 0
	v_mov_b32_e32 v233, 0
	s_waitcnt lgkmcnt(6)
	v_mov_b32_dpp v226, v225 quad_perm:[3,3,3,3] row_mask:0xf bank_mask:0xf
	v_fmac_f32_e32 v225, v71, v226
	v_fmac_f32_e32 v224, v67, v226
	v_fmac_f32_e32 v223, v59, v226
	v_fmac_f32_e32 v222, v47, v226
	v_mov_b32_dpp v226, v225 quad_perm:[2,2,2,2] row_mask:0xf bank_mask:0xf
	v_fmac_f32_e32 v225, v70, v226
	v_fmac_f32_e32 v224, v66, v226
	v_fmac_f32_e32 v223, v58, v226
	v_fmac_f32_e32 v222, v46, v226
	v_mov_b32_dpp v226, v225 quad_perm:[1,1,1,1] row_mask:0xf bank_mask:0xf
	v_fmac_f32_e32 v225, v69, v226
	v_fmac_f32_e32 v224, v65, v226
	v_fmac_f32_e32 v223, v57, v226
	v_fmac_f32_e32 v222, v45, v226
	v_mov_b32_dpp v226, v225 quad_perm:[0,0,0,0] row_mask:0xf bank_mask:0xf
	v_fmac_f32_e32 v224, v64, v226
	v_fmac_f32_e32 v223, v56, v226
	v_fmac_f32_e32 v222, v44, v226
	s_waitcnt lgkmcnt(3)
	v_mov_b32_dpp v226, v224 quad_perm:[3,3,3,3] row_mask:0xf bank_mask:0xf
	v_fmac_f32_e32 v224, v63, v226
	v_fmac_f32_e32 v223, v55, v226
	v_fmac_f32_e32 v222, v43, v226
	v_mov_b32_dpp v226, v224 quad_perm:[2,2,2,2] row_mask:0xf bank_mask:0xf
	v_fmac_f32_e32 v224, v62, v226
	v_fmac_f32_e32 v223, v54, v226
	v_fmac_f32_e32 v222, v42, v226
	v_mov_b32_dpp v226, v224 quad_perm:[1,1,1,1] row_mask:0xf bank_mask:0xf
	v_fmac_f32_e32 v224, v61, v226
	v_fmac_f32_e32 v223, v53, v226
	v_fmac_f32_e32 v222, v41, v226
	v_mov_b32_dpp v226, v224 quad_perm:[0,0,0,0] row_mask:0xf bank_mask:0xf
	v_fmac_f32_e32 v223, v52, v226
	v_fmac_f32_e32 v222, v40, v226
	s_nop 0
	s_waitcnt lgkmcnt(1)
	v_mov_b32_dpp v226, v223 quad_perm:[3,3,3,3] row_mask:0xf bank_mask:0xf
	v_fmac_f32_e32 v223, v51, v226
	v_fmac_f32_e32 v222, v39, v226
	s_nop 0
	v_mov_b32_dpp v226, v223 quad_perm:[2,2,2,2] row_mask:0xf bank_mask:0xf
	v_fmac_f32_e32 v223, v50, v226
	v_fmac_f32_e32 v222, v38, v226
	s_nop 0
	v_mov_b32_dpp v226, v223 quad_perm:[1,1,1,1] row_mask:0xf bank_mask:0xf
	v_fmac_f32_e32 v223, v49, v226
	v_fmac_f32_e32 v222, v37, v226
	s_nop 0
	v_mov_b32_dpp v226, v223 quad_perm:[0,0,0,0] row_mask:0xf bank_mask:0xf
	v_fmac_f32_e32 v222, v36, v226
	s_nop 1
	s_waitcnt lgkmcnt(0)
	v_mov_b32_dpp v226, v222 quad_perm:[3,3,3,3] row_mask:0xf bank_mask:0xf
	v_fmac_f32_e32 v222, v35, v226
	s_nop 1
	v_mov_b32_dpp v226, v222 quad_perm:[2,2,2,2] row_mask:0xf bank_mask:0xf
	v_fmac_f32_e32 v222, v34, v226
	s_nop 1
	v_mov_b32_dpp v226, v222 quad_perm:[1,1,1,1] row_mask:0xf bank_mask:0xf
	v_fmac_f32_e32 v222, v33, v226
	v_cvt_pk_bf16_f32 v236, v222, v222
	v_cvt_pk_bf16_f32 v237, v223, v223
	v_cvt_pk_bf16_f32 v238, v224, v224
	v_cvt_pk_bf16_f32 v239, v225, v225
	ds_write_b16 v229, v236 offset:4096
	ds_write_b16 v229, v237 offset:4104
	ds_write_b16 v229, v238 offset:4112
	ds_write_b16 v229, v239 offset:4120
	ds_write_b64 v230, v[232:233] offset:4864
	s_branch .LBB0_613
; __device__ __forceinline__ void unpack4(const u32x2 w, float (&f)[4]) { f[0] = bflo(w.x); f[1] = bfhi(w.x); f[2] = bflo(w.y); f[3] = bfhi(w.y); }
; template <bool RWKV> __device__ __forceinline__ void scan_load_issue(ScanLd& L, const ScanSrc& S, int chunk, int lt) {
;     const int lw = lt >> 6, lane = lt & 63, sl = lane >> 2, col = 16 * lw + 4 * (lane & 3), s = chunk * SC_CH + sl; const size_t tok = (size_t)(S.tokbase + (S.rev ? T_SEQ - 1 - s : s));
;     L.rd = *(const u32x2*)(S.v[0] + tok * S.ld[0] + col); L.rk = *(const u32x2*)(S.v[1] + tok * S.ld[1] + col); L.rr = *(const u32x2*)(S.v[4] + tok * S.ld[4] + col); L.rv = *(const u32x2*)(S.v[5] + tok * S.ld[5] + col);
;     L.rkk = L.rk; L.rnb = L.rk;
;     if (RWKV) { L.rkk = *(const u32x2*)(S.v[2] + tok * S.ld[2] + col); L.rnb = *(const u32x2*)(S.v[3] + tok * S.ld[3] + col); }
; }
; template <bool RWKV> __device__ __forceinline__ void scan_load_finish(LAS unsigned char* buf, const ScanLd& L, int lt) {
;     const int lw = lt >> 6, lane = lt & 63, sl = lane >> 2, col = 16 * lw + 4 * (lane & 3);
;     float d[4], c[4], k[4], r[4], v[4], kk[4], nb[4];
;     unpack4(L.rd, d); unpack4(L.rk, k); unpack4(L.rr, r); unpack4(L.rv, v); unpack4(L.rkk, kk); unpack4(L.rnb, nb);
; #pragma unroll
;     for (int i = 0; i < 4; ++i) c[i] = d[i];
; #pragma unroll
;     for (int dl = 4; dl < 64; dl <<= 1)
; #pragma unroll
;         for (int i = 0; i < 4; ++i) { const float t = __shfl_up(c[i], dl); c[i] += (lane >= dl) ? t : 0.f; }
;     float o1[4], o2[4], o3[4], o4[4]; f32x4 we;
; #pragma unroll
;     for (int i = 0; i < 4; ++i) { const float W = __expf(-c[i]), iW = __expf(c[i]), Wp = __expf(d[i] - c[i]); o1[i] = RWKV ? kk[i] * Wp : 0.f; o2[i] = RWKV ? nb[i] * iW : 0.f; o3[i] = k[i] * iW; o4[i] = r[i] * W; we[i] = W; }
; template <bool RWKV> __device__ __forceinline__ void scan_item(LAS unsigned char* lds, const ScanSrc& S, int wid, int lane) {
;     ...
;             if (c + 3 < NCH) scan_load_finish<RWKV>(lds + ((b0 + 3) & 3) * SC_BUF, L, lt);
;             if (c + 4 < NCH) scan_load_issue<RWKV>(L, S, c + 4, lt); }
.LBB0_640:
	s_cmpk_gt_u32 s69, 0xfc
	s_cbranch_scc1 .LBB0_613
	s_add_i32 s0, s70, -1
	s_and_b32 s0, s0, 3
	s_mulk_i32 s0, 0x4500
	v_add_u32_e32 v190, s0, v250
	s_bitcmp1_b32 s69, 0
	s_cbranch_scc1 .Lrw_ld_odd
	s_cmpk_gt_u32 s69, 0xfa
	s_cbranch_scc1 .Lrw_ld_e_tail
	s_waitcnt vmcnt(6)
	v_lshlrev_b32_e32 v32, 16, v76
	v_and_b32_e32 v33, 0xffff0000, v76
	v_lshlrev_b32_e32 v34, 16, v77
	v_and_b32_e32 v35, 0xffff0000, v77
	v_mul_f32_e32 v52, 0x3fb8aa3b, v32
	v_mul_f32_e32 v53, 0x3fb8aa3b, v33
	v_mul_f32_e32 v54, 0x3fb8aa3b, v34
	v_mul_f32_e32 v55, 0x3fb8aa3b, v35
	v_add_f32_dpp v52, v52, v52 row_shr:4 row_mask:0xf bank_mask:0xf
	v_add_f32_dpp v53, v53, v53 row_shr:4 row_mask:0xf bank_mask:0xf
	v_add_f32_dpp v54, v54, v54 row_shr:4 row_mask:0xf bank_mask:0xf
	v_add_f32_dpp v55, v55, v55 row_shr:4 row_mask:0xf bank_mask:0xf
	v_add_f32_dpp v52, v52, v52 row_shr:8 row_mask:0xf bank_mask:0xf
	v_add_f32_dpp v53, v53, v53 row_shr:8 row_mask:0xf bank_mask:0xf
	v_add_f32_dpp v54, v54, v54 row_shr:8 row_mask:0xf bank_mask:0xf
	v_add_f32_dpp v55, v55, v55 row_shr:8 row_mask:0xf bank_mask:0xf
	ds_bpermute_b32 v60, v251, v52
	ds_bpermute_b32 v61, v251, v53
	ds_bpermute_b32 v62, v251, v54
	ds_bpermute_b32 v63, v251, v55
	ds_write_b16 v190, v82 offset:14336
	ds_write_b16_d16_hi v190, v82 offset:14384
	ds_write_b16 v190, v83 offset:14432
	ds_write_b16_d16_hi v190, v83 offset:14480
	v_lshlrev_b32_e32 v36, 16, v78
	v_and_b32_e32 v37, 0xffff0000, v78
	v_lshlrev_b32_e32 v38, 16, v79
	v_and_b32_e32 v39, 0xffff0000, v79
	v_lshlrev_b32_e32 v40, 16, v80
	v_and_b32_e32 v41, 0xffff0000, v80
	v_lshlrev_b32_e32 v42, 16, v81
	v_and_b32_e32 v43, 0xffff0000, v81
	v_lshlrev_b32_e32 v44, 16, v84
	v_and_b32_e32 v45, 0xffff0000, v84
	v_lshlrev_b32_e32 v46, 16, v85
	v_and_b32_e32 v47, 0xffff0000, v85
	v_lshlrev_b32_e32 v48, 16, v86
	v_and_b32_e32 v49, 0xffff0000, v86
	v_lshlrev_b32_e32 v50, 16, v87
	v_and_b32_e32 v51, 0xffff0000, v87
	s_waitcnt lgkmcnt(4)
	v_fmac_f32_e32 v52, v60, v253
	v_fmac_f32_e32 v53, v61, v253
	v_fmac_f32_e32 v54, v62, v253
	v_fmac_f32_e32 v55, v63, v253
	ds_bpermute_b32 v60, v252, v52
	ds_bpermute_b32 v61, v252, v53
	ds_bpermute_b32 v62, v252, v54
	ds_bpermute_b32 v63, v252, v55
	global_load_dwordx2 v[76:77], v[234:235], off
	global_load_dwordx2 v[78:79], v[236:237], off
	global_load_dwordx2 v[80:81], v[238:239], off
	global_load_dwordx2 v[82:83], v[240:241], off
	global_load_dwordx2 v[84:85], v[242:243], off
	global_load_dwordx2 v[86:87], v[246:247], off
	v_lshl_add_u64 v[234:235], v[234:235], 0, s[98:99]
	v_lshl_add_u64 v[236:237], v[236:237], 0, s[100:101]
	v_lshl_add_u64 v[238:239], v[238:239], 0, s[100:101]
	v_lshl_add_u64 v[240:241], v[240:241], 0, s[100:101]
	v_lshl_add_u64 v[242:243], v[242:243], 0, s[98:99]
	v_lshl_add_u64 v[246:247], v[246:247], 0, s[98:99]
	s_waitcnt lgkmcnt(0)
	v_fmac_f32_e32 v52, v60, v245
	v_fmac_f32_e32 v53, v61, v245
	v_fmac_f32_e32 v54, v62, v245
	v_fmac_f32_e32 v55, v63, v245
	s_branch .Lrw_ldfin
.Lrw_ld_e_tail:
	s_waitcnt vmcnt(0)
	v_lshlrev_b32_e32 v32, 16, v76
	v_and_b32_e32 v33, 0xffff0000, v76
	v_lshlrev_b32_e32 v34, 16, v77
	v_and_b32_e32 v35, 0xffff0000, v77
	v_mul_f32_e32 v52, 0x3fb8aa3b, v32
	v_mul_f32_e32 v53, 0x3fb8aa3b, v33
	v_mul_f32_e32 v54, 0x3fb8aa3b, v34
	v_mul_f32_e32 v55, 0x3fb8aa3b, v35
	v_add_f32_dpp v52, v52, v52 row_shr:4 row_mask:0xf bank_mask:0xf
	v_add_f32_dpp v53, v53, v53 row_shr:4 row_mask:0xf bank_mask:0xf
	v_add_f32_dpp v54, v54, v54 row_shr:4 row_mask:0xf bank_mask:0xf
	v_add_f32_dpp v55, v55, v55 row_shr:4 row_mask:0xf bank_mask:0xf
	v_add_f32_dpp v52, v52, v52 row_shr:8 row_mask:0xf bank_mask:0xf
	v_add_f32_dpp v53, v53, v53 row_shr:8 row_mask:0xf bank_mask:0xf
	v_add_f32_dpp v54, v54, v54 row_shr:8 row_mask:0xf bank_mask:0xf
	v_add_f32_dpp v55, v55, v55 row_shr:8 row_mask:0xf bank_mask:0xf
	ds_bpermute_b32 v60, v251, v52
	ds_bpermute_b32 v61, v251, v53
	ds_bpermute_b32 v62, v251, v54
	ds_bpermute_b32 v63, v251, v55
	ds_write_b16 v190, v82 offset:14336
	ds_write_b16_d16_hi v190, v82 offset:14384
	ds_write_b16 v190, v83 offset:14432
	ds_write_b16_d16_hi v190, v83 offset:14480
	v_lshlrev_b32_e32 v36, 16, v78
	v_and_b32_e32 v37, 0xffff0000, v78
	v_lshlrev_b32_e32 v38, 16, v79
	v_and_b32_e32 v39, 0xffff0000, v79
	v_lshlrev_b32_e32 v40, 16, v80
	v_and_b32_e32 v41, 0xffff0000, v80
	v_lshlrev_b32_e32 v42, 16, v81
	v_and_b32_e32 v43, 0xffff0000, v81
	v_lshlrev_b32_e32 v44, 16, v84
	v_and_b32_e32 v45, 0xffff0000, v84
	v_lshlrev_b32_e32 v46, 16, v85
	v_and_b32_e32 v47, 0xffff0000, v85
	v_lshlrev_b32_e32 v48, 16, v86
	v_and_b32_e32 v49, 0xffff0000, v86
	v_lshlrev_b32_e32 v50, 16, v87
	v_and_b32_e32 v51, 0xffff0000, v87
	s_waitcnt lgkmcnt(4)
	v_fmac_f32_e32 v52, v60, v253
	v_fmac_f32_e32 v53, v61, v253
	v_fmac_f32_e32 v54, v62, v253
	v_fmac_f32_e32 v55, v63, v253
	ds_bpermute_b32 v60, v252, v52
	ds_bpermute_b32 v61, v252, v53
	ds_bpermute_b32 v62, v252, v54
	ds_bpermute_b32 v63, v252, v55
	s_waitcnt lgkmcnt(0)
	v_fmac_f32_e32 v52, v60, v245
	v_fmac_f32_e32 v53, v61, v245
	v_fmac_f32_e32 v54, v62, v245
	v_fmac_f32_e32 v55, v63, v245
	s_branch .Lrw_ldfin
; __device__ __forceinline__ void unpack4(const u32x2 w, float (&f)[4]) { f[0] = bflo(w.x); f[1] = bfhi(w.x); f[2] = bflo(w.y); f[3] = bfhi(w.y); }
; __device__ __forceinline__ unsigned cvt2(float a, float b) { f32x2 v = {a, b}; bf16x2_t r = __builtin_convertvector(v, bf16x2_t); return __builtin_bit_cast(unsigned, r); }
; template <bool RWKV> __device__ __forceinline__ void scan_load_finish(LAS unsigned char* buf, const ScanLd& L, int lt) {
;     const int lw = lt >> 6, lane = lt & 63, sl = lane >> 2, col = 16 * lw + 4 * (lane & 3);
;     float d[4], c[4], k[4], r[4], v[4], kk[4], nb[4];
;     unpack4(L.rd, d); unpack4(L.rk, k); unpack4(L.rr, r); unpack4(L.rv, v); unpack4(L.rkk, kk); unpack4(L.rnb, nb);
; #pragma unroll
;     for (int i = 0; i < 4; ++i) c[i] = d[i];
; #pragma unroll
;     for (int dl = 4; dl < 64; dl <<= 1)
; #pragma unroll
;         for (int i = 0; i < 4; ++i) { const float t = __shfl_up(c[i], dl); c[i] += (lane >= dl) ? t : 0.f; }
;     float o1[4], o2[4], o3[4], o4[4]; f32x4 we;
; #pragma unroll
;     for (int i = 0; i < 4; ++i) { const float W = __expf(-c[i]), iW = __expf(c[i]), Wp = __expf(d[i] - c[i]); o1[i] = RWKV ? kk[i] * Wp : 0.f; o2[i] = RWKV ? nb[i] * iW : 0.f; o3[i] = k[i] * iW; o4[i] = r[i] * W; we[i] = W; }
;     u32x2 w;
;     w.x = cvt2(o1[0], o1[1]); w.y = cvt2(o1[2], o1[3]); *(LAS u32x2*)(buf + SB_XA + sl * 144 + col * 2) = w;
;     w.x = cvt2(o4[0], o4[1]); w.y = cvt2(o4[2], o4[3]); *(LAS u32x2*)(buf + SB_XA + (16 + sl) * 144 + col * 2) = w;
;     w.x = cvt2(o2[0], o2[1]); w.y = cvt2(o2[2], o2[3]); *(LAS u32x2*)(buf + SB_XB + sl * 144 + col * 2) = w;
;     w.x = cvt2(o3[0], o3[1]); w.y = cvt2(o3[2], o3[3]); *(LAS u32x2*)(buf + SB_XB + (16 + sl) * 144 + col * 2) = w;
; #pragma unroll
;     for (int i = 0; i < 4; ++i) {
;         *(LAS unsigned short*)(buf + SB_XBT + (col + i) * 80 + sl * 2) = (unsigned short)(cvt2(o2[i], 0.f) & 0xffffu);
;         *(LAS unsigned short*)(buf + SB_XBT + (col + i) * 80 + (16 + sl) * 2) = (unsigned short)(cvt2(o3[i], 0.f) & 0xffffu);
;         *(LAS unsigned short*)(buf + SB_VT + (col + i) * 48 + sl * 2) = (unsigned short)(cvt2(v[i], 0.f) & 0xffffu); }
;     if (sl == SC_CH - 1) *(LAS f32x4*)(buf + SB_WE + col * 4) = we;
.Lrw_ld_odd:
	s_cmpk_gt_u32 s69, 0xfa
	s_cbranch_scc1 .Lrw_ld_o_tail
	s_waitcnt vmcnt(6)
	v_lshlrev_b32_e32 v32, 16, v222
	v_and_b32_e32 v33, 0xffff0000, v222
	v_lshlrev_b32_e32 v34, 16, v223
	v_and_b32_e32 v35, 0xffff0000, v223
	v_mul_f32_e32 v52, 0x3fb8aa3b, v32
	v_mul_f32_e32 v53, 0x3fb8aa3b, v33
	v_mul_f32_e32 v54, 0x3fb8aa3b, v34
	v_mul_f32_e32 v55, 0x3fb8aa3b, v35
	v_add_f32_dpp v52, v52, v52 row_shr:4 row_mask:0xf bank_mask:0xf
	v_add_f32_dpp v53, v53, v53 row_shr:4 row_mask:0xf bank_mask:0xf
	v_add_f32_dpp v54, v54, v54 row_shr:4 row_mask:0xf bank_mask:0xf
	v_add_f32_dpp v55, v55, v55 row_shr:4 row_mask:0xf bank_mask:0xf
	v_add_f32_dpp v52, v52, v52 row_shr:8 row_mask:0xf bank_mask:0xf
	v_add_f32_dpp v53, v53, v53 row_shr:8 row_mask:0xf bank_mask:0xf
	v_add_f32_dpp v54, v54, v54 row_shr:8 row_mask:0xf bank_mask:0xf
	v_add_f32_dpp v55, v55, v55 row_shr:8 row_mask:0xf bank_mask:0xf
	ds_bpermute_b32 v60, v251, v52
	ds_bpermute_b32 v61, v251, v53
	ds_bpermute_b32 v62, v251, v54
	ds_bpermute_b32 v63, v251, v55
	ds_write_b16 v190, v228 offset:14336
	ds_write_b16_d16_hi v190, v228 offset:14384
	ds_write_b16 v190, v229 offset:14432
	ds_write_b16_d16_hi v190, v229 offset:14480
	v_lshlrev_b32_e32 v36, 16, v224
	v_and_b32_e32 v37, 0xffff0000, v224
	v_lshlrev_b32_e32 v38, 16, v225
	v_and_b32_e32 v39, 0xffff0000, v225
	v_lshlrev_b32_e32 v40, 16, v226
	v_and_b32_e32 v41, 0xffff0000, v226
	v_lshlrev_b32_e32 v42, 16, v227
	v_and_b32_e32 v43, 0xffff0000, v227
	v_lshlrev_b32_e32 v44, 16, v230
	v_and_b32_e32 v45, 0xffff0000, v230
	v_lshlrev_b32_e32 v46, 16, v231
	v_and_b32_e32 v47, 0xffff0000, v231
	v_lshlrev_b32_e32 v48, 16, v232
	v_and_b32_e32 v49, 0xffff0000, v232
	v_lshlrev_b32_e32 v50, 16, v233
	v_and_b32_e32 v51, 0xffff0000, v233
	s_waitcnt lgkmcnt(4)
	v_fmac_f32_e32 v52, v60, v253
	v_fmac_f32_e32 v53, v61, v253
	v_fmac_f32_e32 v54, v62, v253
	v_fmac_f32_e32 v55, v63, v253
	ds_bpermute_b32 v60, v252, v52
	ds_bpermute_b32 v61, v252, v53
	ds_bpermute_b32 v62, v252, v54
	ds_bpermute_b32 v63, v252, v55
	global_load_dwordx2 v[222:223], v[234:235], off
	global_load_dwordx2 v[224:225], v[236:237], off
	global_load_dwordx2 v[226:227], v[238:239], off
	global_load_dwordx2 v[228:229], v[240:241], off
	global_load_dwordx2 v[230:231], v[242:243], off
	global_load_dwordx2 v[232:233], v[246:247], off
	v_lshl_add_u64 v[234:235], v[234:235], 0, s[98:99]
	v_lshl_add_u64 v[236:237], v[236:237], 0, s[100:101]
	v_lshl_add_u64 v[238:239], v[238:239], 0, s[100:101]
	v_lshl_add_u64 v[240:241], v[240:241], 0, s[100:101]
	v_lshl_add_u64 v[242:243], v[242:243], 0, s[98:99]
	v_lshl_add_u64 v[246:247], v[246:247], 0, s[98:99]
	s_waitcnt lgkmcnt(0)
	v_fmac_f32_e32 v52, v60, v245
	v_fmac_f32_e32 v53, v61, v245
	v_fmac_f32_e32 v54, v62, v245
	v_fmac_f32_e32 v55, v63, v245
	s_branch .Lrw_ldfin
.Lrw_ld_o_tail:
	s_waitcnt vmcnt(0)
	v_lshlrev_b32_e32 v32, 16, v222
	v_and_b32_e32 v33, 0xffff0000, v222
	v_lshlrev_b32_e32 v34, 16, v223
	v_and_b32_e32 v35, 0xffff0000, v223
	v_mul_f32_e32 v52, 0x3fb8aa3b, v32
	v_mul_f32_e32 v53, 0x3fb8aa3b, v33
	v_mul_f32_e32 v54, 0x3fb8aa3b, v34
	v_mul_f32_e32 v55, 0x3fb8aa3b, v35
	v_add_f32_dpp v52, v52, v52 row_shr:4 row_mask:0xf bank_mask:0xf
	v_add_f32_dpp v53, v53, v53 row_shr:4 row_mask:0xf bank_mask:0xf
	v_add_f32_dpp v54, v54, v54 row_shr:4 row_mask:0xf bank_mask:0xf
	v_add_f32_dpp v55, v55, v55 row_shr:4 row_mask:0xf bank_mask:0xf
	v_add_f32_dpp v52, v52, v52 row_shr:8 row_mask:0xf bank_mask:0xf
	v_add_f32_dpp v53, v53, v53 row_shr:8 row_mask:0xf bank_mask:0xf
	v_add_f32_dpp v54, v54, v54 row_shr:8 row_mask:0xf bank_mask:0xf
	v_add_f32_dpp v55, v55, v55 row_shr:8 row_mask:0xf bank_mask:0xf
	ds_bpermute_b32 v60, v251, v52
	ds_bpermute_b32 v61, v251, v53
	ds_bpermute_b32 v62, v251, v54
	ds_bpermute_b32 v63, v251, v55
	ds_write_b16 v190, v228 offset:14336
	ds_write_b16_d16_hi v190, v228 offset:14384
	ds_write_b16 v190, v229 offset:14432
	ds_write_b16_d16_hi v190, v229 offset:14480
	v_lshlrev_b32_e32 v36, 16, v224
	v_and_b32_e32 v37, 0xffff0000, v224
	v_lshlrev_b32_e32 v38, 16, v225
	v_and_b32_e32 v39, 0xffff0000, v225
	v_lshlrev_b32_e32 v40, 16, v226
	v_and_b32_e32 v41, 0xffff0000, v226
	v_lshlrev_b32_e32 v42, 16, v227
	v_and_b32_e32 v43, 0xffff0000, v227
	v_lshlrev_b32_e32 v44, 16, v230
	v_and_b32_e32 v45, 0xffff0000, v230
	v_lshlrev_b32_e32 v46, 16, v231
	v_and_b32_e32 v47, 0xffff0000, v231
	v_lshlrev_b32_e32 v48, 16, v232
	v_and_b32_e32 v49, 0xffff0000, v232
	v_lshlrev_b32_e32 v50, 16, v233
	v_and_b32_e32 v51, 0xffff0000, v233
	s_waitcnt lgkmcnt(4)
	v_fmac_f32_e32 v52, v60, v253
	v_fmac_f32_e32 v53, v61, v253
	v_fmac_f32_e32 v54, v62, v253
	v_fmac_f32_e32 v55, v63, v253
	ds_bpermute_b32 v60, v252, v52
	ds_bpermute_b32 v61, v252, v53
	ds_bpermute_b32 v62, v252, v54
	ds_bpermute_b32 v63, v252, v55
	s_waitcnt lgkmcnt(0)
	v_fmac_f32_e32 v52, v60, v245
	v_fmac_f32_e32 v53, v61, v245
	v_fmac_f32_e32 v54, v62, v245
	v_fmac_f32_e32 v55, v63, v245
.Lrw_ldfin:
	v_fmamk_f32 v56, v32, 0xbfb8aa3b, v52
	v_fmamk_f32 v57, v33, 0xbfb8aa3b, v53
	v_fmamk_f32 v58, v34, 0xbfb8aa3b, v54
	v_fmamk_f32 v59, v35, 0xbfb8aa3b, v55
	v_exp_f32_e64 v64, -v52
	v_exp_f32_e64 v65, -v53
	v_exp_f32_e64 v66, -v54
	v_exp_f32_e64 v67, -v55
	v_exp_f32_e32 v68, v52
	v_exp_f32_e32 v69, v53
	v_exp_f32_e32 v70, v54
	v_exp_f32_e32 v71, v55
	v_exp_f32_e64 v192, -v56
	v_exp_f32_e64 v193, -v57
	v_exp_f32_e64 v194, -v58
	v_exp_f32_e64 v195, -v59
	v_add_u32_e32 v191, s0, v248
	v_pk_mul_f32 v[208:209], v[64:65], v[40:41]
	v_pk_mul_f32 v[210:211], v[66:67], v[42:43]
	v_pk_mul_f32 v[200:201], v[68:69], v[48:49]
	v_pk_mul_f32 v[202:203], v[70:71], v[50:51]
	v_pk_mul_f32 v[204:205], v[68:69], v[36:37]
	v_pk_mul_f32 v[206:207], v[70:71], v[38:39]
	v_pk_mul_f32 v[196:197], v[192:193], v[44:45]
	v_pk_mul_f32 v[198:199], v[194:195], v[46:47]
	v_cvt_pk_bf16_f32 v218, v208, v209
	v_cvt_pk_bf16_f32 v219, v210, v211
	v_cvt_pk_bf16_f32 v214, v200, v201
	v_cvt_pk_bf16_f32 v215, v202, v203
	v_cvt_pk_bf16_f32 v216, v204, v205
	v_cvt_pk_bf16_f32 v217, v206, v207
	v_cvt_pk_bf16_f32 v212, v196, v197
	v_cvt_pk_bf16_f32 v213, v198, v199
	v_add_u32_e32 v220, 0x900, v191
	v_add_u32_e32 v221, s0, v249
	ds_write2st64_b64 v220, v[218:219], v[216:217] offset1:9
	ds_write2st64_b64 v191, v[212:213], v[214:215] offset1:9
	ds_write_b16 v221, v214 offset:9216
	ds_write_b16_d16_hi v221, v214 offset:9296
	ds_write_b16 v221, v215 offset:9376
	ds_write_b16_d16_hi v221, v215 offset:9456
	ds_write_b16 v221, v216 offset:9248
	ds_write_b16_d16_hi v221, v216 offset:9328
	ds_write_b16 v221, v217 offset:9408
	ds_write_b16_d16_hi v221, v217 offset:9488
	s_and_saveexec_b64 s[42:43], s[14:15]
	v_add_u32_e32 v60, s0, v188
	ds_write_b128 v60, v[64:67] offset:17408
	s_or_b64 exec, exec, s[42:43]
	s_branch .LBB0_613
